# LDS-DMA tile staging also for the full tiles of phase 4b and 5b (GLU stays register-staged)
# baseline (speedup 1.0000x reference)
.LBB0_765:
	s_and_b64 vcc, exec, s[24:25]
	s_cbranch_vccz .LBB0_724
	s_ashr_i32 s14, s51, 31
	s_lshr_b32 s14, s14, 29
	s_add_i32 s14, s51, s14
	s_lshl_b32 s15, s14, 4
	s_and_b32 s14, s14, 0x1fffff8
	s_sub_i32 s14, s51, s14
	s_and_b32 s24, s15, 0xffffff80
	s_lshl_b32 s25, s14, 7
	v_add_u32_e32 v0, s24, v105
	v_add_u32_e32 v16, s25, v105
	v_ashrrev_i32_e32 v1, 31, v0
	v_ashrrev_i32_e32 v17, 31, v16
	v_lshlrev_b64 v[0:1], 11, v[0:1]
	v_lshlrev_b64 v[16:17], 11, v[16:17]
	v_lshl_add_u64 v[70:71], v[66:67], 0, v[0:1]
	v_lshl_add_u64 v[72:73], v[68:69], 0, v[16:17]
	v_readfirstlane_b32 s98, v66
	v_readfirstlane_b32 s99, v67
	v_readfirstlane_b32 s100, v68
	v_readfirstlane_b32 s101, v69
	s_lshl_b32 s15, s24, 11
	s_add_u32 s98, s98, s15
	s_addc_u32 s99, s99, 0
	s_lshl_b32 s15, s25, 11
	s_add_u32 s100, s100, s15
	s_addc_u32 s101, s101, 0
	v_lshrrev_b32_e32 v246, 3, v100
	v_and_b32_e32 v247, 7, v100
	v_bfe_u32 v244, v100, 4, 3
	v_xor_b32_e32 v244, v244, v247
	v_lshlrev_b32_e32 v244, 4, v244
	v_lshl_or_b32 v110, v246, 7, v244
	v_lshlrev_b32_e32 v245, 4, v247
	v_lshl_or_b32 v93, v246, 11, v244
	v_add_u32_e32 v94, 0x10000, v93
	v_add_u32_e32 v95, 0x20000, v93
	v_add_u32_e32 v109, 0x30000, v93
	v_and_b32_e32 v244, 15, v100
	v_bfe_u32 v245, v100, 4, 2
	v_bfe_u32 v246, v100, 1, 3
	v_xor_b32_e32 v247, v245, v246
	v_lshlrev_b32_e32 v247, 4, v247
	v_lshl_or_b32 v247, v244, 7, v247
	v_bfe_u32 v246, v100, 7, 1
	v_lshl_add_u32 v239, v246, 13, v247
	v_xor_b32_e32 v240, 64, v239
	v_bfe_u32 v246, v100, 6, 1
	v_lshl_add_u32 v241, v246, 13, v247
	v_add_u32_e32 v241, 0x4000, v241
	v_xor_b32_e32 v242, 64, v241
	v_bfe_u32 v247, v100, 7, 1
	v_lshlrev_b32_e32 v247, 6, v247
	v_lshl_add_u32 v247, v245, 2, v247
	v_mul_u32_u24_e32 v247, 0x84, v247
	v_lshl_add_u32 v247, v246, 6, v247
	v_add_u32_e32 v247, v247, v244
	v_lshlrev_b32_e32 v243, 2, v247
	v_lshrrev_b32_e32 v244, 6, v100
	v_lshlrev_b32_e32 v244, 10, v244
	s_nop 1
	v_readfirstlane_b32 s15, v244
	s_nop 3
	s_add_u32 m0, s15, 0x0
	s_nop 0
	global_load_lds_dwordx4 v93, s[98:99]
	s_add_u32 m0, s15, 0x1000
	s_nop 0
	global_load_lds_dwordx4 v94, s[98:99]
	s_add_u32 m0, s15, 0x2000
	s_nop 0
	global_load_lds_dwordx4 v95, s[98:99]
	s_add_u32 m0, s15, 0x3000
	s_nop 0
	global_load_lds_dwordx4 v109, s[98:99]
	s_add_u32 m0, s15, 0x4000
	s_nop 0
	global_load_lds_dwordx4 v93, s[100:101]
	s_add_u32 m0, s15, 0x5000
	s_nop 0
	global_load_lds_dwordx4 v94, s[100:101]
	s_add_u32 m0, s15, 0x6000
	s_nop 0
	global_load_lds_dwordx4 v95, s[100:101]
	s_add_u32 m0, s15, 0x7000
	s_nop 0
	global_load_lds_dwordx4 v109, s[100:101]
	v_readlane_b32 s52, v238, 32
	v_readlane_b32 s54, v238, 34
	v_readlane_b32 s55, v238, 35
	s_mov_b32 s14, 0
	v_readlane_b32 s53, v238, 33
	v_readlane_b32 s56, v238, 36
	v_readlane_b32 s57, v238, 37
	v_readlane_b32 s58, v238, 38
	v_readlane_b32 s59, v238, 39
	v_readlane_b32 s60, v238, 40
	v_readlane_b32 s61, v238, 41
	v_readlane_b32 s62, v238, 42
	v_readlane_b32 s63, v238, 43
	v_readlane_b32 s64, v238, 44
	v_readlane_b32 s65, v238, 45
	v_readlane_b32 s66, v238, 46
	v_readlane_b32 s67, v238, 47
	s_waitcnt vmcnt(0)
	s_barrier
	s_add_u32 s98, s98, 0x80
	s_addc_u32 s99, s99, 0
	s_add_u32 s100, s100, 0x80
	s_addc_u32 s101, s101, 0
	ds_read_b128 v[112:115], v239
	ds_read_b128 v[134:137], v241
	ds_read_b128 v[138:141], v241 offset:2048
	ds_read_b128 v[142:145], v241 offset:4096
	ds_read_b128 v[154:157], v241 offset:6144
	ds_read_b128 v[118:121], v239 offset:2048
	ds_read_b128 v[126:129], v239 offset:4096
	ds_read_b128 v[130:133], v239 offset:6144
	s_waitcnt lgkmcnt(6)
	v_mfma_f32_16x16x32_bf16 v[0:3], v[112:115], v[134:137], 0
	ds_read_b128 v[158:161], v240
	s_waitcnt lgkmcnt(6)
	v_mfma_f32_16x16x32_bf16 v[4:7], v[112:115], v[138:141], 0
	ds_read_b128 v[166:169], v242
	s_waitcnt lgkmcnt(6)
	v_mfma_f32_16x16x32_bf16 v[8:11], v[112:115], v[142:145], 0
	ds_read_b128 v[170:173], v242 offset:2048
	s_waitcnt lgkmcnt(6)
	v_mfma_f32_16x16x32_bf16 v[12:15], v[112:115], v[154:157], 0
	ds_read_b128 v[174:177], v242 offset:4096
	s_waitcnt lgkmcnt(6)
	v_mfma_f32_16x16x32_bf16 v[16:19], v[118:121], v[134:137], 0
	ds_read_b128 v[252:255], v242 offset:6144
	v_mfma_f32_16x16x32_bf16 v[20:23], v[118:121], v[138:141], 0
	ds_read_b128 v[162:165], v240 offset:2048
	v_mfma_f32_16x16x32_bf16 v[24:27], v[118:121], v[142:145], 0
	ds_read_b128 v[244:247], v240 offset:4096
	v_mfma_f32_16x16x32_bf16 v[28:31], v[118:121], v[154:157], 0
	ds_read_b128 v[248:251], v240 offset:6144
	s_add_u32 m0, s15, 0x8000
	s_waitcnt lgkmcnt(9)
	v_mfma_f32_16x16x32_bf16 v[32:35], v[126:129], v[134:137], 0
	global_load_lds_dwordx4 v93, s[98:99]
	s_add_u32 m0, s15, 0x9000
	v_mfma_f32_16x16x32_bf16 v[36:39], v[126:129], v[138:141], 0
	global_load_lds_dwordx4 v94, s[98:99]
	s_add_u32 m0, s15, 0xa000
	v_mfma_f32_16x16x32_bf16 v[40:43], v[126:129], v[142:145], 0
	global_load_lds_dwordx4 v95, s[98:99]
	s_add_u32 m0, s15, 0xb000
	v_mfma_f32_16x16x32_bf16 v[44:47], v[126:129], v[154:157], 0
	global_load_lds_dwordx4 v109, s[98:99]
	s_add_u32 m0, s15, 0xc000
	s_waitcnt lgkmcnt(8)
	v_mfma_f32_16x16x32_bf16 v[48:51], v[130:133], v[134:137], 0
	global_load_lds_dwordx4 v93, s[100:101]
	s_add_u32 m0, s15, 0xd000
	v_mfma_f32_16x16x32_bf16 v[52:55], v[130:133], v[138:141], 0
	global_load_lds_dwordx4 v94, s[100:101]
	s_add_u32 m0, s15, 0xe000
	v_mfma_f32_16x16x32_bf16 v[56:59], v[130:133], v[142:145], 0
	global_load_lds_dwordx4 v95, s[100:101]
	s_add_u32 m0, s15, 0xf000
	v_mfma_f32_16x16x32_bf16 v[60:63], v[130:133], v[154:157], 0
	global_load_lds_dwordx4 v109, s[100:101]
	s_waitcnt lgkmcnt(6)
	v_mfma_f32_16x16x32_bf16 v[0:3], v[158:161], v[166:169], v[0:3]
	s_waitcnt lgkmcnt(5)
	v_mfma_f32_16x16x32_bf16 v[4:7], v[158:161], v[170:173], v[4:7]
	s_waitcnt lgkmcnt(4)
	v_mfma_f32_16x16x32_bf16 v[8:11], v[158:161], v[174:177], v[8:11]
	s_waitcnt lgkmcnt(3)
	v_mfma_f32_16x16x32_bf16 v[12:15], v[158:161], v[252:255], v[12:15]
	s_waitcnt lgkmcnt(2)
	v_mfma_f32_16x16x32_bf16 v[16:19], v[162:165], v[166:169], v[16:19]
	v_mfma_f32_16x16x32_bf16 v[20:23], v[162:165], v[170:173], v[20:23]
	v_mfma_f32_16x16x32_bf16 v[24:27], v[162:165], v[174:177], v[24:27]
	v_mfma_f32_16x16x32_bf16 v[28:31], v[162:165], v[252:255], v[28:31]
	s_waitcnt lgkmcnt(1)
	v_mfma_f32_16x16x32_bf16 v[32:35], v[244:247], v[166:169], v[32:35]
	v_mfma_f32_16x16x32_bf16 v[36:39], v[244:247], v[170:173], v[36:39]
	v_mfma_f32_16x16x32_bf16 v[40:43], v[244:247], v[174:177], v[40:43]
	v_mfma_f32_16x16x32_bf16 v[44:47], v[244:247], v[252:255], v[44:47]
	s_waitcnt lgkmcnt(0)
	v_mfma_f32_16x16x32_bf16 v[48:51], v[248:251], v[166:169], v[48:51]
	v_mfma_f32_16x16x32_bf16 v[52:55], v[248:251], v[170:173], v[52:55]
	v_mfma_f32_16x16x32_bf16 v[56:59], v[248:251], v[174:177], v[56:59]
	v_mfma_f32_16x16x32_bf16 v[60:63], v[248:251], v[252:255], v[60:63]
	s_waitcnt vmcnt(0) lgkmcnt(0)
	s_barrier
	s_add_u32 s98, s98, 0x80
	s_addc_u32 s99, s99, 0
	s_add_u32 s100, s100, 0x80
	s_addc_u32 s101, s101, 0
	ds_read_b128 v[112:115], v239 offset:32768
	ds_read_b128 v[134:137], v241 offset:32768
	ds_read_b128 v[138:141], v241 offset:34816
	ds_read_b128 v[142:145], v241 offset:36864
	ds_read_b128 v[154:157], v241 offset:38912
	ds_read_b128 v[118:121], v239 offset:34816
	ds_read_b128 v[126:129], v239 offset:36864
	ds_read_b128 v[130:133], v239 offset:38912
	s_waitcnt lgkmcnt(6)
	v_mfma_f32_16x16x32_bf16 v[0:3], v[112:115], v[134:137], v[0:3]
	ds_read_b128 v[158:161], v240 offset:32768
	s_waitcnt lgkmcnt(6)
	v_mfma_f32_16x16x32_bf16 v[4:7], v[112:115], v[138:141], v[4:7]
	ds_read_b128 v[166:169], v242 offset:32768
	s_waitcnt lgkmcnt(6)
	v_mfma_f32_16x16x32_bf16 v[8:11], v[112:115], v[142:145], v[8:11]
	ds_read_b128 v[170:173], v242 offset:34816
	s_waitcnt lgkmcnt(6)
	v_mfma_f32_16x16x32_bf16 v[12:15], v[112:115], v[154:157], v[12:15]
	ds_read_b128 v[174:177], v242 offset:36864
	s_waitcnt lgkmcnt(6)
	v_mfma_f32_16x16x32_bf16 v[16:19], v[118:121], v[134:137], v[16:19]
	ds_read_b128 v[252:255], v242 offset:38912
	v_mfma_f32_16x16x32_bf16 v[20:23], v[118:121], v[138:141], v[20:23]
	ds_read_b128 v[162:165], v240 offset:34816
	v_mfma_f32_16x16x32_bf16 v[24:27], v[118:121], v[142:145], v[24:27]
	ds_read_b128 v[244:247], v240 offset:36864
	v_mfma_f32_16x16x32_bf16 v[28:31], v[118:121], v[154:157], v[28:31]
	ds_read_b128 v[248:251], v240 offset:38912
	s_add_u32 m0, s15, 0x0
	s_waitcnt lgkmcnt(9)
	v_mfma_f32_16x16x32_bf16 v[32:35], v[126:129], v[134:137], v[32:35]
	global_load_lds_dwordx4 v93, s[98:99]
	s_add_u32 m0, s15, 0x1000
	v_mfma_f32_16x16x32_bf16 v[36:39], v[126:129], v[138:141], v[36:39]
	global_load_lds_dwordx4 v94, s[98:99]
	s_add_u32 m0, s15, 0x2000
	v_mfma_f32_16x16x32_bf16 v[40:43], v[126:129], v[142:145], v[40:43]
	global_load_lds_dwordx4 v95, s[98:99]
	s_add_u32 m0, s15, 0x3000
	v_mfma_f32_16x16x32_bf16 v[44:47], v[126:129], v[154:157], v[44:47]
	global_load_lds_dwordx4 v109, s[98:99]
	s_add_u32 m0, s15, 0x4000
	s_waitcnt lgkmcnt(8)
	v_mfma_f32_16x16x32_bf16 v[48:51], v[130:133], v[134:137], v[48:51]
	global_load_lds_dwordx4 v93, s[100:101]
	s_add_u32 m0, s15, 0x5000
	v_mfma_f32_16x16x32_bf16 v[52:55], v[130:133], v[138:141], v[52:55]
	global_load_lds_dwordx4 v94, s[100:101]
	s_add_u32 m0, s15, 0x6000
	v_mfma_f32_16x16x32_bf16 v[56:59], v[130:133], v[142:145], v[56:59]
	global_load_lds_dwordx4 v95, s[100:101]
	s_add_u32 m0, s15, 0x7000
	v_mfma_f32_16x16x32_bf16 v[60:63], v[130:133], v[154:157], v[60:63]
	global_load_lds_dwordx4 v109, s[100:101]
	s_waitcnt lgkmcnt(6)
	v_mfma_f32_16x16x32_bf16 v[0:3], v[158:161], v[166:169], v[0:3]
	s_waitcnt lgkmcnt(5)
	v_mfma_f32_16x16x32_bf16 v[4:7], v[158:161], v[170:173], v[4:7]
	s_waitcnt lgkmcnt(4)
	v_mfma_f32_16x16x32_bf16 v[8:11], v[158:161], v[174:177], v[8:11]
	s_waitcnt lgkmcnt(3)
	v_mfma_f32_16x16x32_bf16 v[12:15], v[158:161], v[252:255], v[12:15]
	s_waitcnt lgkmcnt(2)
	v_mfma_f32_16x16x32_bf16 v[16:19], v[162:165], v[166:169], v[16:19]
	v_mfma_f32_16x16x32_bf16 v[20:23], v[162:165], v[170:173], v[20:23]
	v_mfma_f32_16x16x32_bf16 v[24:27], v[162:165], v[174:177], v[24:27]
	v_mfma_f32_16x16x32_bf16 v[28:31], v[162:165], v[252:255], v[28:31]
	s_waitcnt lgkmcnt(1)
	v_mfma_f32_16x16x32_bf16 v[32:35], v[244:247], v[166:169], v[32:35]
	v_mfma_f32_16x16x32_bf16 v[36:39], v[244:247], v[170:173], v[36:39]
	v_mfma_f32_16x16x32_bf16 v[40:43], v[244:247], v[174:177], v[40:43]
	v_mfma_f32_16x16x32_bf16 v[44:47], v[244:247], v[252:255], v[44:47]
	s_waitcnt lgkmcnt(0)
	v_mfma_f32_16x16x32_bf16 v[48:51], v[248:251], v[166:169], v[48:51]
	v_mfma_f32_16x16x32_bf16 v[52:55], v[248:251], v[170:173], v[52:55]
	v_mfma_f32_16x16x32_bf16 v[56:59], v[248:251], v[174:177], v[56:59]
	v_mfma_f32_16x16x32_bf16 v[60:63], v[248:251], v[252:255], v[60:63]
	s_waitcnt vmcnt(0) lgkmcnt(0)
	s_barrier
	s_add_u32 s98, s98, 0x80
	s_addc_u32 s99, s99, 0
	s_add_u32 s100, s100, 0x80
	s_addc_u32 s101, s101, 0
	ds_read_b128 v[112:115], v239
	ds_read_b128 v[134:137], v241
	ds_read_b128 v[138:141], v241 offset:2048
	ds_read_b128 v[142:145], v241 offset:4096
	ds_read_b128 v[154:157], v241 offset:6144
	ds_read_b128 v[118:121], v239 offset:2048
	ds_read_b128 v[126:129], v239 offset:4096
	ds_read_b128 v[130:133], v239 offset:6144
	s_waitcnt lgkmcnt(6)
	v_mfma_f32_16x16x32_bf16 v[0:3], v[112:115], v[134:137], v[0:3]
	ds_read_b128 v[158:161], v240
	s_waitcnt lgkmcnt(6)
	v_mfma_f32_16x16x32_bf16 v[4:7], v[112:115], v[138:141], v[4:7]
	ds_read_b128 v[166:169], v242
	s_waitcnt lgkmcnt(6)
	v_mfma_f32_16x16x32_bf16 v[8:11], v[112:115], v[142:145], v[8:11]
	ds_read_b128 v[170:173], v242 offset:2048
	s_waitcnt lgkmcnt(6)
	v_mfma_f32_16x16x32_bf16 v[12:15], v[112:115], v[154:157], v[12:15]
	ds_read_b128 v[174:177], v242 offset:4096
	s_waitcnt lgkmcnt(6)
	v_mfma_f32_16x16x32_bf16 v[16:19], v[118:121], v[134:137], v[16:19]
	ds_read_b128 v[252:255], v242 offset:6144
	v_mfma_f32_16x16x32_bf16 v[20:23], v[118:121], v[138:141], v[20:23]
	ds_read_b128 v[162:165], v240 offset:2048
	v_mfma_f32_16x16x32_bf16 v[24:27], v[118:121], v[142:145], v[24:27]
	ds_read_b128 v[244:247], v240 offset:4096
	v_mfma_f32_16x16x32_bf16 v[28:31], v[118:121], v[154:157], v[28:31]
	ds_read_b128 v[248:251], v240 offset:6144
	s_add_u32 m0, s15, 0x8000
	s_waitcnt lgkmcnt(9)
	v_mfma_f32_16x16x32_bf16 v[32:35], v[126:129], v[134:137], v[32:35]
	global_load_lds_dwordx4 v93, s[98:99]
	s_add_u32 m0, s15, 0x9000
	v_mfma_f32_16x16x32_bf16 v[36:39], v[126:129], v[138:141], v[36:39]
	global_load_lds_dwordx4 v94, s[98:99]
	s_add_u32 m0, s15, 0xa000
	v_mfma_f32_16x16x32_bf16 v[40:43], v[126:129], v[142:145], v[40:43]
	global_load_lds_dwordx4 v95, s[98:99]
	s_add_u32 m0, s15, 0xb000
	v_mfma_f32_16x16x32_bf16 v[44:47], v[126:129], v[154:157], v[44:47]
	global_load_lds_dwordx4 v109, s[98:99]
	s_add_u32 m0, s15, 0xc000
	s_waitcnt lgkmcnt(8)
	v_mfma_f32_16x16x32_bf16 v[48:51], v[130:133], v[134:137], v[48:51]
	global_load_lds_dwordx4 v93, s[100:101]
	s_add_u32 m0, s15, 0xd000
	v_mfma_f32_16x16x32_bf16 v[52:55], v[130:133], v[138:141], v[52:55]
	global_load_lds_dwordx4 v94, s[100:101]
	s_add_u32 m0, s15, 0xe000
	v_mfma_f32_16x16x32_bf16 v[56:59], v[130:133], v[142:145], v[56:59]
	global_load_lds_dwordx4 v95, s[100:101]
	s_add_u32 m0, s15, 0xf000
	v_mfma_f32_16x16x32_bf16 v[60:63], v[130:133], v[154:157], v[60:63]
	global_load_lds_dwordx4 v109, s[100:101]
	s_waitcnt lgkmcnt(6)
	v_mfma_f32_16x16x32_bf16 v[0:3], v[158:161], v[166:169], v[0:3]
	s_waitcnt lgkmcnt(5)
	v_mfma_f32_16x16x32_bf16 v[4:7], v[158:161], v[170:173], v[4:7]
	s_waitcnt lgkmcnt(4)
	v_mfma_f32_16x16x32_bf16 v[8:11], v[158:161], v[174:177], v[8:11]
	s_waitcnt lgkmcnt(3)
	v_mfma_f32_16x16x32_bf16 v[12:15], v[158:161], v[252:255], v[12:15]
	s_waitcnt lgkmcnt(2)
	v_mfma_f32_16x16x32_bf16 v[16:19], v[162:165], v[166:169], v[16:19]
	v_mfma_f32_16x16x32_bf16 v[20:23], v[162:165], v[170:173], v[20:23]
	v_mfma_f32_16x16x32_bf16 v[24:27], v[162:165], v[174:177], v[24:27]
	v_mfma_f32_16x16x32_bf16 v[28:31], v[162:165], v[252:255], v[28:31]
	s_waitcnt lgkmcnt(1)
	v_mfma_f32_16x16x32_bf16 v[32:35], v[244:247], v[166:169], v[32:35]
	v_mfma_f32_16x16x32_bf16 v[36:39], v[244:247], v[170:173], v[36:39]
	v_mfma_f32_16x16x32_bf16 v[40:43], v[244:247], v[174:177], v[40:43]
	v_mfma_f32_16x16x32_bf16 v[44:47], v[244:247], v[252:255], v[44:47]
	s_waitcnt lgkmcnt(0)
	v_mfma_f32_16x16x32_bf16 v[48:51], v[248:251], v[166:169], v[48:51]
	v_mfma_f32_16x16x32_bf16 v[52:55], v[248:251], v[170:173], v[52:55]
	v_mfma_f32_16x16x32_bf16 v[56:59], v[248:251], v[174:177], v[56:59]
	v_mfma_f32_16x16x32_bf16 v[60:63], v[248:251], v[252:255], v[60:63]
	s_waitcnt vmcnt(0) lgkmcnt(0)
	s_barrier
	s_add_u32 s98, s98, 0x80
	s_addc_u32 s99, s99, 0
	s_add_u32 s100, s100, 0x80
	s_addc_u32 s101, s101, 0
	ds_read_b128 v[112:115], v239 offset:32768
	ds_read_b128 v[134:137], v241 offset:32768
	ds_read_b128 v[138:141], v241 offset:34816
	ds_read_b128 v[142:145], v241 offset:36864
	ds_read_b128 v[154:157], v241 offset:38912
	ds_read_b128 v[118:121], v239 offset:34816
	ds_read_b128 v[126:129], v239 offset:36864
	ds_read_b128 v[130:133], v239 offset:38912
	s_waitcnt lgkmcnt(6)
	v_mfma_f32_16x16x32_bf16 v[0:3], v[112:115], v[134:137], v[0:3]
	ds_read_b128 v[158:161], v240 offset:32768
	s_waitcnt lgkmcnt(6)
	v_mfma_f32_16x16x32_bf16 v[4:7], v[112:115], v[138:141], v[4:7]
	ds_read_b128 v[166:169], v242 offset:32768
	s_waitcnt lgkmcnt(6)
	v_mfma_f32_16x16x32_bf16 v[8:11], v[112:115], v[142:145], v[8:11]
	ds_read_b128 v[170:173], v242 offset:34816
	s_waitcnt lgkmcnt(6)
	v_mfma_f32_16x16x32_bf16 v[12:15], v[112:115], v[154:157], v[12:15]
	ds_read_b128 v[174:177], v242 offset:36864
	s_waitcnt lgkmcnt(6)
	v_mfma_f32_16x16x32_bf16 v[16:19], v[118:121], v[134:137], v[16:19]
	ds_read_b128 v[252:255], v242 offset:38912
	v_mfma_f32_16x16x32_bf16 v[20:23], v[118:121], v[138:141], v[20:23]
	ds_read_b128 v[162:165], v240 offset:34816
	v_mfma_f32_16x16x32_bf16 v[24:27], v[118:121], v[142:145], v[24:27]
	ds_read_b128 v[244:247], v240 offset:36864
	v_mfma_f32_16x16x32_bf16 v[28:31], v[118:121], v[154:157], v[28:31]
	ds_read_b128 v[248:251], v240 offset:38912
	s_add_u32 m0, s15, 0x0
	s_waitcnt lgkmcnt(9)
	v_mfma_f32_16x16x32_bf16 v[32:35], v[126:129], v[134:137], v[32:35]
	global_load_lds_dwordx4 v93, s[98:99]
	s_add_u32 m0, s15, 0x1000
	v_mfma_f32_16x16x32_bf16 v[36:39], v[126:129], v[138:141], v[36:39]
	global_load_lds_dwordx4 v94, s[98:99]
	s_add_u32 m0, s15, 0x2000
	v_mfma_f32_16x16x32_bf16 v[40:43], v[126:129], v[142:145], v[40:43]
	global_load_lds_dwordx4 v95, s[98:99]
	s_add_u32 m0, s15, 0x3000
	v_mfma_f32_16x16x32_bf16 v[44:47], v[126:129], v[154:157], v[44:47]
	global_load_lds_dwordx4 v109, s[98:99]
	s_add_u32 m0, s15, 0x4000
	s_waitcnt lgkmcnt(8)
	v_mfma_f32_16x16x32_bf16 v[48:51], v[130:133], v[134:137], v[48:51]
	global_load_lds_dwordx4 v93, s[100:101]
	s_add_u32 m0, s15, 0x5000
	v_mfma_f32_16x16x32_bf16 v[52:55], v[130:133], v[138:141], v[52:55]
	global_load_lds_dwordx4 v94, s[100:101]
	s_add_u32 m0, s15, 0x6000
	v_mfma_f32_16x16x32_bf16 v[56:59], v[130:133], v[142:145], v[56:59]
	global_load_lds_dwordx4 v95, s[100:101]
	s_add_u32 m0, s15, 0x7000
	v_mfma_f32_16x16x32_bf16 v[60:63], v[130:133], v[154:157], v[60:63]
	global_load_lds_dwordx4 v109, s[100:101]
	s_waitcnt lgkmcnt(6)
	v_mfma_f32_16x16x32_bf16 v[0:3], v[158:161], v[166:169], v[0:3]
	s_waitcnt lgkmcnt(5)
	v_mfma_f32_16x16x32_bf16 v[4:7], v[158:161], v[170:173], v[4:7]
	s_waitcnt lgkmcnt(4)
	v_mfma_f32_16x16x32_bf16 v[8:11], v[158:161], v[174:177], v[8:11]
	s_waitcnt lgkmcnt(3)
	v_mfma_f32_16x16x32_bf16 v[12:15], v[158:161], v[252:255], v[12:15]
	s_waitcnt lgkmcnt(2)
	v_mfma_f32_16x16x32_bf16 v[16:19], v[162:165], v[166:169], v[16:19]
	v_mfma_f32_16x16x32_bf16 v[20:23], v[162:165], v[170:173], v[20:23]
	v_mfma_f32_16x16x32_bf16 v[24:27], v[162:165], v[174:177], v[24:27]
	v_mfma_f32_16x16x32_bf16 v[28:31], v[162:165], v[252:255], v[28:31]
	s_waitcnt lgkmcnt(1)
	v_mfma_f32_16x16x32_bf16 v[32:35], v[244:247], v[166:169], v[32:35]
	v_mfma_f32_16x16x32_bf16 v[36:39], v[244:247], v[170:173], v[36:39]
	v_mfma_f32_16x16x32_bf16 v[40:43], v[244:247], v[174:177], v[40:43]
	v_mfma_f32_16x16x32_bf16 v[44:47], v[244:247], v[252:255], v[44:47]
	s_waitcnt lgkmcnt(0)
	v_mfma_f32_16x16x32_bf16 v[48:51], v[248:251], v[166:169], v[48:51]
	v_mfma_f32_16x16x32_bf16 v[52:55], v[248:251], v[170:173], v[52:55]
	v_mfma_f32_16x16x32_bf16 v[56:59], v[248:251], v[174:177], v[56:59]
	v_mfma_f32_16x16x32_bf16 v[60:63], v[248:251], v[252:255], v[60:63]
	s_waitcnt vmcnt(0) lgkmcnt(0)
	s_barrier
	s_add_u32 s98, s98, 0x80
	s_addc_u32 s99, s99, 0
	s_add_u32 s100, s100, 0x80
	s_addc_u32 s101, s101, 0
	ds_read_b128 v[112:115], v239
	ds_read_b128 v[134:137], v241
	ds_read_b128 v[138:141], v241 offset:2048
	ds_read_b128 v[142:145], v241 offset:4096
	ds_read_b128 v[154:157], v241 offset:6144
	ds_read_b128 v[118:121], v239 offset:2048
	ds_read_b128 v[126:129], v239 offset:4096
	ds_read_b128 v[130:133], v239 offset:6144
	s_waitcnt lgkmcnt(6)
	v_mfma_f32_16x16x32_bf16 v[0:3], v[112:115], v[134:137], v[0:3]
	ds_read_b128 v[158:161], v240
	s_waitcnt lgkmcnt(6)
	v_mfma_f32_16x16x32_bf16 v[4:7], v[112:115], v[138:141], v[4:7]
	ds_read_b128 v[166:169], v242
	s_waitcnt lgkmcnt(6)
	v_mfma_f32_16x16x32_bf16 v[8:11], v[112:115], v[142:145], v[8:11]
	ds_read_b128 v[170:173], v242 offset:2048
	s_waitcnt lgkmcnt(6)
	v_mfma_f32_16x16x32_bf16 v[12:15], v[112:115], v[154:157], v[12:15]
	ds_read_b128 v[174:177], v242 offset:4096
	s_waitcnt lgkmcnt(6)
	v_mfma_f32_16x16x32_bf16 v[16:19], v[118:121], v[134:137], v[16:19]
	ds_read_b128 v[252:255], v242 offset:6144
	v_mfma_f32_16x16x32_bf16 v[20:23], v[118:121], v[138:141], v[20:23]
	ds_read_b128 v[162:165], v240 offset:2048
	v_mfma_f32_16x16x32_bf16 v[24:27], v[118:121], v[142:145], v[24:27]
	ds_read_b128 v[244:247], v240 offset:4096
	v_mfma_f32_16x16x32_bf16 v[28:31], v[118:121], v[154:157], v[28:31]
	ds_read_b128 v[248:251], v240 offset:6144
	s_add_u32 m0, s15, 0x8000
	s_waitcnt lgkmcnt(9)
	v_mfma_f32_16x16x32_bf16 v[32:35], v[126:129], v[134:137], v[32:35]
	global_load_lds_dwordx4 v93, s[98:99]
	s_add_u32 m0, s15, 0x9000
	v_mfma_f32_16x16x32_bf16 v[36:39], v[126:129], v[138:141], v[36:39]
	global_load_lds_dwordx4 v94, s[98:99]
	s_add_u32 m0, s15, 0xa000
	v_mfma_f32_16x16x32_bf16 v[40:43], v[126:129], v[142:145], v[40:43]
	global_load_lds_dwordx4 v95, s[98:99]
	s_add_u32 m0, s15, 0xb000
	v_mfma_f32_16x16x32_bf16 v[44:47], v[126:129], v[154:157], v[44:47]
	global_load_lds_dwordx4 v109, s[98:99]
	s_add_u32 m0, s15, 0xc000
	s_waitcnt lgkmcnt(8)
	v_mfma_f32_16x16x32_bf16 v[48:51], v[130:133], v[134:137], v[48:51]
	global_load_lds_dwordx4 v93, s[100:101]
	s_add_u32 m0, s15, 0xd000
	v_mfma_f32_16x16x32_bf16 v[52:55], v[130:133], v[138:141], v[52:55]
	global_load_lds_dwordx4 v94, s[100:101]
	s_add_u32 m0, s15, 0xe000
	v_mfma_f32_16x16x32_bf16 v[56:59], v[130:133], v[142:145], v[56:59]
	global_load_lds_dwordx4 v95, s[100:101]
	s_add_u32 m0, s15, 0xf000
	v_mfma_f32_16x16x32_bf16 v[60:63], v[130:133], v[154:157], v[60:63]
	global_load_lds_dwordx4 v109, s[100:101]
	s_waitcnt lgkmcnt(6)
	v_mfma_f32_16x16x32_bf16 v[0:3], v[158:161], v[166:169], v[0:3]
	s_waitcnt lgkmcnt(5)
	v_mfma_f32_16x16x32_bf16 v[4:7], v[158:161], v[170:173], v[4:7]
	s_waitcnt lgkmcnt(4)
	v_mfma_f32_16x16x32_bf16 v[8:11], v[158:161], v[174:177], v[8:11]
	s_waitcnt lgkmcnt(3)
	v_mfma_f32_16x16x32_bf16 v[12:15], v[158:161], v[252:255], v[12:15]
	s_waitcnt lgkmcnt(2)
	v_mfma_f32_16x16x32_bf16 v[16:19], v[162:165], v[166:169], v[16:19]
	v_mfma_f32_16x16x32_bf16 v[20:23], v[162:165], v[170:173], v[20:23]
	v_mfma_f32_16x16x32_bf16 v[24:27], v[162:165], v[174:177], v[24:27]
	v_mfma_f32_16x16x32_bf16 v[28:31], v[162:165], v[252:255], v[28:31]
	s_waitcnt lgkmcnt(1)
	v_mfma_f32_16x16x32_bf16 v[32:35], v[244:247], v[166:169], v[32:35]
	v_mfma_f32_16x16x32_bf16 v[36:39], v[244:247], v[170:173], v[36:39]
	v_mfma_f32_16x16x32_bf16 v[40:43], v[244:247], v[174:177], v[40:43]
	v_mfma_f32_16x16x32_bf16 v[44:47], v[244:247], v[252:255], v[44:47]
	s_waitcnt lgkmcnt(0)
	v_mfma_f32_16x16x32_bf16 v[48:51], v[248:251], v[166:169], v[48:51]
	v_mfma_f32_16x16x32_bf16 v[52:55], v[248:251], v[170:173], v[52:55]
	v_mfma_f32_16x16x32_bf16 v[56:59], v[248:251], v[174:177], v[56:59]
	v_mfma_f32_16x16x32_bf16 v[60:63], v[248:251], v[252:255], v[60:63]
	s_waitcnt vmcnt(0) lgkmcnt(0)
	s_barrier
	s_add_u32 s98, s98, 0x80
	s_addc_u32 s99, s99, 0
	s_add_u32 s100, s100, 0x80
	s_addc_u32 s101, s101, 0
	ds_read_b128 v[112:115], v239 offset:32768
	ds_read_b128 v[134:137], v241 offset:32768
	ds_read_b128 v[138:141], v241 offset:34816
	ds_read_b128 v[142:145], v241 offset:36864
	ds_read_b128 v[154:157], v241 offset:38912
	ds_read_b128 v[118:121], v239 offset:34816
	ds_read_b128 v[126:129], v239 offset:36864
	ds_read_b128 v[130:133], v239 offset:38912
	s_waitcnt lgkmcnt(6)
	v_mfma_f32_16x16x32_bf16 v[0:3], v[112:115], v[134:137], v[0:3]
	ds_read_b128 v[158:161], v240 offset:32768
	s_waitcnt lgkmcnt(6)
	v_mfma_f32_16x16x32_bf16 v[4:7], v[112:115], v[138:141], v[4:7]
	ds_read_b128 v[166:169], v242 offset:32768
	s_waitcnt lgkmcnt(6)
	v_mfma_f32_16x16x32_bf16 v[8:11], v[112:115], v[142:145], v[8:11]
	ds_read_b128 v[170:173], v242 offset:34816
	s_waitcnt lgkmcnt(6)
	v_mfma_f32_16x16x32_bf16 v[12:15], v[112:115], v[154:157], v[12:15]
	ds_read_b128 v[174:177], v242 offset:36864
	s_waitcnt lgkmcnt(6)
	v_mfma_f32_16x16x32_bf16 v[16:19], v[118:121], v[134:137], v[16:19]
	ds_read_b128 v[252:255], v242 offset:38912
	v_mfma_f32_16x16x32_bf16 v[20:23], v[118:121], v[138:141], v[20:23]
	ds_read_b128 v[162:165], v240 offset:34816
	v_mfma_f32_16x16x32_bf16 v[24:27], v[118:121], v[142:145], v[24:27]
	ds_read_b128 v[244:247], v240 offset:36864
	v_mfma_f32_16x16x32_bf16 v[28:31], v[118:121], v[154:157], v[28:31]
	ds_read_b128 v[248:251], v240 offset:38912
	s_add_u32 m0, s15, 0x0
	s_waitcnt lgkmcnt(9)
	v_mfma_f32_16x16x32_bf16 v[32:35], v[126:129], v[134:137], v[32:35]
	global_load_lds_dwordx4 v93, s[98:99]
	s_add_u32 m0, s15, 0x1000
	v_mfma_f32_16x16x32_bf16 v[36:39], v[126:129], v[138:141], v[36:39]
	global_load_lds_dwordx4 v94, s[98:99]
	s_add_u32 m0, s15, 0x2000
	v_mfma_f32_16x16x32_bf16 v[40:43], v[126:129], v[142:145], v[40:43]
	global_load_lds_dwordx4 v95, s[98:99]
	s_add_u32 m0, s15, 0x3000
	v_mfma_f32_16x16x32_bf16 v[44:47], v[126:129], v[154:157], v[44:47]
	global_load_lds_dwordx4 v109, s[98:99]
	s_add_u32 m0, s15, 0x4000
	s_waitcnt lgkmcnt(8)
	v_mfma_f32_16x16x32_bf16 v[48:51], v[130:133], v[134:137], v[48:51]
	global_load_lds_dwordx4 v93, s[100:101]
	s_add_u32 m0, s15, 0x5000
	v_mfma_f32_16x16x32_bf16 v[52:55], v[130:133], v[138:141], v[52:55]
	global_load_lds_dwordx4 v94, s[100:101]
	s_add_u32 m0, s15, 0x6000
	v_mfma_f32_16x16x32_bf16 v[56:59], v[130:133], v[142:145], v[56:59]
	global_load_lds_dwordx4 v95, s[100:101]
	s_add_u32 m0, s15, 0x7000
	v_mfma_f32_16x16x32_bf16 v[60:63], v[130:133], v[154:157], v[60:63]
	global_load_lds_dwordx4 v109, s[100:101]
	s_waitcnt lgkmcnt(6)
	v_mfma_f32_16x16x32_bf16 v[0:3], v[158:161], v[166:169], v[0:3]
	s_waitcnt lgkmcnt(5)
	v_mfma_f32_16x16x32_bf16 v[4:7], v[158:161], v[170:173], v[4:7]
	s_waitcnt lgkmcnt(4)
	v_mfma_f32_16x16x32_bf16 v[8:11], v[158:161], v[174:177], v[8:11]
	s_waitcnt lgkmcnt(3)
	v_mfma_f32_16x16x32_bf16 v[12:15], v[158:161], v[252:255], v[12:15]
	s_waitcnt lgkmcnt(2)
	v_mfma_f32_16x16x32_bf16 v[16:19], v[162:165], v[166:169], v[16:19]
	v_mfma_f32_16x16x32_bf16 v[20:23], v[162:165], v[170:173], v[20:23]
	v_mfma_f32_16x16x32_bf16 v[24:27], v[162:165], v[174:177], v[24:27]
	v_mfma_f32_16x16x32_bf16 v[28:31], v[162:165], v[252:255], v[28:31]
	s_waitcnt lgkmcnt(1)
	v_mfma_f32_16x16x32_bf16 v[32:35], v[244:247], v[166:169], v[32:35]
	v_mfma_f32_16x16x32_bf16 v[36:39], v[244:247], v[170:173], v[36:39]
	v_mfma_f32_16x16x32_bf16 v[40:43], v[244:247], v[174:177], v[40:43]
	v_mfma_f32_16x16x32_bf16 v[44:47], v[244:247], v[252:255], v[44:47]
	s_waitcnt lgkmcnt(0)
	v_mfma_f32_16x16x32_bf16 v[48:51], v[248:251], v[166:169], v[48:51]
	v_mfma_f32_16x16x32_bf16 v[52:55], v[248:251], v[170:173], v[52:55]
	v_mfma_f32_16x16x32_bf16 v[56:59], v[248:251], v[174:177], v[56:59]
	v_mfma_f32_16x16x32_bf16 v[60:63], v[248:251], v[252:255], v[60:63]
	s_waitcnt vmcnt(0) lgkmcnt(0)
	s_barrier
	s_add_u32 s98, s98, 0x80
	s_addc_u32 s99, s99, 0
	s_add_u32 s100, s100, 0x80
	s_addc_u32 s101, s101, 0
	ds_read_b128 v[112:115], v239
	ds_read_b128 v[134:137], v241
	ds_read_b128 v[138:141], v241 offset:2048
	ds_read_b128 v[142:145], v241 offset:4096
	ds_read_b128 v[154:157], v241 offset:6144
	ds_read_b128 v[118:121], v239 offset:2048
	ds_read_b128 v[126:129], v239 offset:4096
	ds_read_b128 v[130:133], v239 offset:6144
	s_waitcnt lgkmcnt(6)
	v_mfma_f32_16x16x32_bf16 v[0:3], v[112:115], v[134:137], v[0:3]
	ds_read_b128 v[158:161], v240
	s_waitcnt lgkmcnt(6)
	v_mfma_f32_16x16x32_bf16 v[4:7], v[112:115], v[138:141], v[4:7]
	ds_read_b128 v[166:169], v242
	s_waitcnt lgkmcnt(6)
	v_mfma_f32_16x16x32_bf16 v[8:11], v[112:115], v[142:145], v[8:11]
	ds_read_b128 v[170:173], v242 offset:2048
	s_waitcnt lgkmcnt(6)
	v_mfma_f32_16x16x32_bf16 v[12:15], v[112:115], v[154:157], v[12:15]
	ds_read_b128 v[174:177], v242 offset:4096
	s_waitcnt lgkmcnt(6)
	v_mfma_f32_16x16x32_bf16 v[16:19], v[118:121], v[134:137], v[16:19]
	ds_read_b128 v[252:255], v242 offset:6144
	v_mfma_f32_16x16x32_bf16 v[20:23], v[118:121], v[138:141], v[20:23]
	ds_read_b128 v[162:165], v240 offset:2048
	v_mfma_f32_16x16x32_bf16 v[24:27], v[118:121], v[142:145], v[24:27]
	ds_read_b128 v[244:247], v240 offset:4096
	v_mfma_f32_16x16x32_bf16 v[28:31], v[118:121], v[154:157], v[28:31]
	ds_read_b128 v[248:251], v240 offset:6144
	s_add_u32 m0, s15, 0x8000
	s_waitcnt lgkmcnt(9)
	v_mfma_f32_16x16x32_bf16 v[32:35], v[126:129], v[134:137], v[32:35]
	global_load_lds_dwordx4 v93, s[98:99]
	s_add_u32 m0, s15, 0x9000
	v_mfma_f32_16x16x32_bf16 v[36:39], v[126:129], v[138:141], v[36:39]
	global_load_lds_dwordx4 v94, s[98:99]
	s_add_u32 m0, s15, 0xa000
	v_mfma_f32_16x16x32_bf16 v[40:43], v[126:129], v[142:145], v[40:43]
	global_load_lds_dwordx4 v95, s[98:99]
	s_add_u32 m0, s15, 0xb000
	v_mfma_f32_16x16x32_bf16 v[44:47], v[126:129], v[154:157], v[44:47]
	global_load_lds_dwordx4 v109, s[98:99]
	s_add_u32 m0, s15, 0xc000
	s_waitcnt lgkmcnt(8)
	v_mfma_f32_16x16x32_bf16 v[48:51], v[130:133], v[134:137], v[48:51]
	global_load_lds_dwordx4 v93, s[100:101]
	s_add_u32 m0, s15, 0xd000
	v_mfma_f32_16x16x32_bf16 v[52:55], v[130:133], v[138:141], v[52:55]
	global_load_lds_dwordx4 v94, s[100:101]
	s_add_u32 m0, s15, 0xe000
	v_mfma_f32_16x16x32_bf16 v[56:59], v[130:133], v[142:145], v[56:59]
	global_load_lds_dwordx4 v95, s[100:101]
	s_add_u32 m0, s15, 0xf000
	v_mfma_f32_16x16x32_bf16 v[60:63], v[130:133], v[154:157], v[60:63]
	global_load_lds_dwordx4 v109, s[100:101]
	s_waitcnt lgkmcnt(6)
	v_mfma_f32_16x16x32_bf16 v[0:3], v[158:161], v[166:169], v[0:3]
	s_waitcnt lgkmcnt(5)
	v_mfma_f32_16x16x32_bf16 v[4:7], v[158:161], v[170:173], v[4:7]
	s_waitcnt lgkmcnt(4)
	v_mfma_f32_16x16x32_bf16 v[8:11], v[158:161], v[174:177], v[8:11]
	s_waitcnt lgkmcnt(3)
	v_mfma_f32_16x16x32_bf16 v[12:15], v[158:161], v[252:255], v[12:15]
	s_waitcnt lgkmcnt(2)
	v_mfma_f32_16x16x32_bf16 v[16:19], v[162:165], v[166:169], v[16:19]
	v_mfma_f32_16x16x32_bf16 v[20:23], v[162:165], v[170:173], v[20:23]
	v_mfma_f32_16x16x32_bf16 v[24:27], v[162:165], v[174:177], v[24:27]
	v_mfma_f32_16x16x32_bf16 v[28:31], v[162:165], v[252:255], v[28:31]
	s_waitcnt lgkmcnt(1)
	v_mfma_f32_16x16x32_bf16 v[32:35], v[244:247], v[166:169], v[32:35]
	v_mfma_f32_16x16x32_bf16 v[36:39], v[244:247], v[170:173], v[36:39]
	v_mfma_f32_16x16x32_bf16 v[40:43], v[244:247], v[174:177], v[40:43]
	v_mfma_f32_16x16x32_bf16 v[44:47], v[244:247], v[252:255], v[44:47]
	s_waitcnt lgkmcnt(0)
	v_mfma_f32_16x16x32_bf16 v[48:51], v[248:251], v[166:169], v[48:51]
	v_mfma_f32_16x16x32_bf16 v[52:55], v[248:251], v[170:173], v[52:55]
	v_mfma_f32_16x16x32_bf16 v[56:59], v[248:251], v[174:177], v[56:59]
	v_mfma_f32_16x16x32_bf16 v[60:63], v[248:251], v[252:255], v[60:63]
	s_waitcnt vmcnt(0) lgkmcnt(0)
	s_barrier
	s_add_u32 s98, s98, 0x80
	s_addc_u32 s99, s99, 0
	s_add_u32 s100, s100, 0x80
	s_addc_u32 s101, s101, 0
	ds_read_b128 v[112:115], v239 offset:32768
	ds_read_b128 v[134:137], v241 offset:32768
	ds_read_b128 v[138:141], v241 offset:34816
	ds_read_b128 v[142:145], v241 offset:36864
	ds_read_b128 v[154:157], v241 offset:38912
	ds_read_b128 v[118:121], v239 offset:34816
	ds_read_b128 v[126:129], v239 offset:36864
	ds_read_b128 v[130:133], v239 offset:38912
	s_waitcnt lgkmcnt(6)
	v_mfma_f32_16x16x32_bf16 v[0:3], v[112:115], v[134:137], v[0:3]
	ds_read_b128 v[158:161], v240 offset:32768
	s_waitcnt lgkmcnt(6)
	v_mfma_f32_16x16x32_bf16 v[4:7], v[112:115], v[138:141], v[4:7]
	ds_read_b128 v[166:169], v242 offset:32768
	s_waitcnt lgkmcnt(6)
	v_mfma_f32_16x16x32_bf16 v[8:11], v[112:115], v[142:145], v[8:11]
	ds_read_b128 v[170:173], v242 offset:34816
	s_waitcnt lgkmcnt(6)
	v_mfma_f32_16x16x32_bf16 v[12:15], v[112:115], v[154:157], v[12:15]
	ds_read_b128 v[174:177], v242 offset:36864
	s_waitcnt lgkmcnt(6)
	v_mfma_f32_16x16x32_bf16 v[16:19], v[118:121], v[134:137], v[16:19]
	ds_read_b128 v[252:255], v242 offset:38912
	v_mfma_f32_16x16x32_bf16 v[20:23], v[118:121], v[138:141], v[20:23]
	ds_read_b128 v[162:165], v240 offset:34816
	v_mfma_f32_16x16x32_bf16 v[24:27], v[118:121], v[142:145], v[24:27]
	ds_read_b128 v[244:247], v240 offset:36864
	v_mfma_f32_16x16x32_bf16 v[28:31], v[118:121], v[154:157], v[28:31]
	ds_read_b128 v[248:251], v240 offset:38912
	s_add_u32 m0, s15, 0x0
	s_waitcnt lgkmcnt(9)
	v_mfma_f32_16x16x32_bf16 v[32:35], v[126:129], v[134:137], v[32:35]
	global_load_lds_dwordx4 v93, s[98:99]
	s_add_u32 m0, s15, 0x1000
	v_mfma_f32_16x16x32_bf16 v[36:39], v[126:129], v[138:141], v[36:39]
	global_load_lds_dwordx4 v94, s[98:99]
	s_add_u32 m0, s15, 0x2000
	v_mfma_f32_16x16x32_bf16 v[40:43], v[126:129], v[142:145], v[40:43]
	global_load_lds_dwordx4 v95, s[98:99]
	s_add_u32 m0, s15, 0x3000
	v_mfma_f32_16x16x32_bf16 v[44:47], v[126:129], v[154:157], v[44:47]
	global_load_lds_dwordx4 v109, s[98:99]
	s_add_u32 m0, s15, 0x4000
	s_waitcnt lgkmcnt(8)
	v_mfma_f32_16x16x32_bf16 v[48:51], v[130:133], v[134:137], v[48:51]
	global_load_lds_dwordx4 v93, s[100:101]
	s_add_u32 m0, s15, 0x5000
	v_mfma_f32_16x16x32_bf16 v[52:55], v[130:133], v[138:141], v[52:55]
	global_load_lds_dwordx4 v94, s[100:101]
	s_add_u32 m0, s15, 0x6000
	v_mfma_f32_16x16x32_bf16 v[56:59], v[130:133], v[142:145], v[56:59]
	global_load_lds_dwordx4 v95, s[100:101]
	s_add_u32 m0, s15, 0x7000
	v_mfma_f32_16x16x32_bf16 v[60:63], v[130:133], v[154:157], v[60:63]
	global_load_lds_dwordx4 v109, s[100:101]
	s_waitcnt lgkmcnt(6)
	v_mfma_f32_16x16x32_bf16 v[0:3], v[158:161], v[166:169], v[0:3]
	s_waitcnt lgkmcnt(5)
	v_mfma_f32_16x16x32_bf16 v[4:7], v[158:161], v[170:173], v[4:7]
	s_waitcnt lgkmcnt(4)
	v_mfma_f32_16x16x32_bf16 v[8:11], v[158:161], v[174:177], v[8:11]
	s_waitcnt lgkmcnt(3)
	v_mfma_f32_16x16x32_bf16 v[12:15], v[158:161], v[252:255], v[12:15]
	s_waitcnt lgkmcnt(2)
	v_mfma_f32_16x16x32_bf16 v[16:19], v[162:165], v[166:169], v[16:19]
	v_mfma_f32_16x16x32_bf16 v[20:23], v[162:165], v[170:173], v[20:23]
	v_mfma_f32_16x16x32_bf16 v[24:27], v[162:165], v[174:177], v[24:27]
	v_mfma_f32_16x16x32_bf16 v[28:31], v[162:165], v[252:255], v[28:31]
	s_waitcnt lgkmcnt(1)
	v_mfma_f32_16x16x32_bf16 v[32:35], v[244:247], v[166:169], v[32:35]
	v_mfma_f32_16x16x32_bf16 v[36:39], v[244:247], v[170:173], v[36:39]
	v_mfma_f32_16x16x32_bf16 v[40:43], v[244:247], v[174:177], v[40:43]
	v_mfma_f32_16x16x32_bf16 v[44:47], v[244:247], v[252:255], v[44:47]
	s_waitcnt lgkmcnt(0)
	v_mfma_f32_16x16x32_bf16 v[48:51], v[248:251], v[166:169], v[48:51]
	v_mfma_f32_16x16x32_bf16 v[52:55], v[248:251], v[170:173], v[52:55]
	v_mfma_f32_16x16x32_bf16 v[56:59], v[248:251], v[174:177], v[56:59]
	v_mfma_f32_16x16x32_bf16 v[60:63], v[248:251], v[252:255], v[60:63]
	s_waitcnt vmcnt(0) lgkmcnt(0)
	s_barrier
	s_add_u32 s98, s98, 0x80
	s_addc_u32 s99, s99, 0
	s_add_u32 s100, s100, 0x80
	s_addc_u32 s101, s101, 0
	ds_read_b128 v[112:115], v239
	ds_read_b128 v[134:137], v241
	ds_read_b128 v[138:141], v241 offset:2048
	ds_read_b128 v[142:145], v241 offset:4096
	ds_read_b128 v[154:157], v241 offset:6144
	ds_read_b128 v[118:121], v239 offset:2048
	ds_read_b128 v[126:129], v239 offset:4096
	ds_read_b128 v[130:133], v239 offset:6144
	s_waitcnt lgkmcnt(6)
	v_mfma_f32_16x16x32_bf16 v[0:3], v[112:115], v[134:137], v[0:3]
	ds_read_b128 v[158:161], v240
	s_waitcnt lgkmcnt(6)
	v_mfma_f32_16x16x32_bf16 v[4:7], v[112:115], v[138:141], v[4:7]
	ds_read_b128 v[166:169], v242
	s_waitcnt lgkmcnt(6)
	v_mfma_f32_16x16x32_bf16 v[8:11], v[112:115], v[142:145], v[8:11]
	ds_read_b128 v[170:173], v242 offset:2048
	s_waitcnt lgkmcnt(6)
	v_mfma_f32_16x16x32_bf16 v[12:15], v[112:115], v[154:157], v[12:15]
	ds_read_b128 v[174:177], v242 offset:4096
	s_waitcnt lgkmcnt(6)
	v_mfma_f32_16x16x32_bf16 v[16:19], v[118:121], v[134:137], v[16:19]
	ds_read_b128 v[252:255], v242 offset:6144
	v_mfma_f32_16x16x32_bf16 v[20:23], v[118:121], v[138:141], v[20:23]
	ds_read_b128 v[162:165], v240 offset:2048
	v_mfma_f32_16x16x32_bf16 v[24:27], v[118:121], v[142:145], v[24:27]
	ds_read_b128 v[244:247], v240 offset:4096
	v_mfma_f32_16x16x32_bf16 v[28:31], v[118:121], v[154:157], v[28:31]
	ds_read_b128 v[248:251], v240 offset:6144
	s_add_u32 m0, s15, 0x8000
	s_waitcnt lgkmcnt(9)
	v_mfma_f32_16x16x32_bf16 v[32:35], v[126:129], v[134:137], v[32:35]
	global_load_lds_dwordx4 v93, s[98:99]
	s_add_u32 m0, s15, 0x9000
	v_mfma_f32_16x16x32_bf16 v[36:39], v[126:129], v[138:141], v[36:39]
	global_load_lds_dwordx4 v94, s[98:99]
	s_add_u32 m0, s15, 0xa000
	v_mfma_f32_16x16x32_bf16 v[40:43], v[126:129], v[142:145], v[40:43]
	global_load_lds_dwordx4 v95, s[98:99]
	s_add_u32 m0, s15, 0xb000
	v_mfma_f32_16x16x32_bf16 v[44:47], v[126:129], v[154:157], v[44:47]
	global_load_lds_dwordx4 v109, s[98:99]
	s_add_u32 m0, s15, 0xc000
	s_waitcnt lgkmcnt(8)
	v_mfma_f32_16x16x32_bf16 v[48:51], v[130:133], v[134:137], v[48:51]
	global_load_lds_dwordx4 v93, s[100:101]
	s_add_u32 m0, s15, 0xd000
	v_mfma_f32_16x16x32_bf16 v[52:55], v[130:133], v[138:141], v[52:55]
	global_load_lds_dwordx4 v94, s[100:101]
	s_add_u32 m0, s15, 0xe000
	v_mfma_f32_16x16x32_bf16 v[56:59], v[130:133], v[142:145], v[56:59]
	global_load_lds_dwordx4 v95, s[100:101]
	s_add_u32 m0, s15, 0xf000
	v_mfma_f32_16x16x32_bf16 v[60:63], v[130:133], v[154:157], v[60:63]
	global_load_lds_dwordx4 v109, s[100:101]
	s_waitcnt lgkmcnt(6)
	v_mfma_f32_16x16x32_bf16 v[0:3], v[158:161], v[166:169], v[0:3]
	s_waitcnt lgkmcnt(5)
	v_mfma_f32_16x16x32_bf16 v[4:7], v[158:161], v[170:173], v[4:7]
	s_waitcnt lgkmcnt(4)
	v_mfma_f32_16x16x32_bf16 v[8:11], v[158:161], v[174:177], v[8:11]
	s_waitcnt lgkmcnt(3)
	v_mfma_f32_16x16x32_bf16 v[12:15], v[158:161], v[252:255], v[12:15]
	s_waitcnt lgkmcnt(2)
	v_mfma_f32_16x16x32_bf16 v[16:19], v[162:165], v[166:169], v[16:19]
	v_mfma_f32_16x16x32_bf16 v[20:23], v[162:165], v[170:173], v[20:23]
	v_mfma_f32_16x16x32_bf16 v[24:27], v[162:165], v[174:177], v[24:27]
	v_mfma_f32_16x16x32_bf16 v[28:31], v[162:165], v[252:255], v[28:31]
	s_waitcnt lgkmcnt(1)
	v_mfma_f32_16x16x32_bf16 v[32:35], v[244:247], v[166:169], v[32:35]
	v_mfma_f32_16x16x32_bf16 v[36:39], v[244:247], v[170:173], v[36:39]
	v_mfma_f32_16x16x32_bf16 v[40:43], v[244:247], v[174:177], v[40:43]
	v_mfma_f32_16x16x32_bf16 v[44:47], v[244:247], v[252:255], v[44:47]
	s_waitcnt lgkmcnt(0)
	v_mfma_f32_16x16x32_bf16 v[48:51], v[248:251], v[166:169], v[48:51]
	v_mfma_f32_16x16x32_bf16 v[52:55], v[248:251], v[170:173], v[52:55]
	v_mfma_f32_16x16x32_bf16 v[56:59], v[248:251], v[174:177], v[56:59]
	v_mfma_f32_16x16x32_bf16 v[60:63], v[248:251], v[252:255], v[60:63]
	s_waitcnt vmcnt(0) lgkmcnt(0)
	s_barrier
	s_add_u32 s98, s98, 0x80
	s_addc_u32 s99, s99, 0
	s_add_u32 s100, s100, 0x80
	s_addc_u32 s101, s101, 0
	ds_read_b128 v[112:115], v239 offset:32768
	ds_read_b128 v[134:137], v241 offset:32768
	ds_read_b128 v[138:141], v241 offset:34816
	ds_read_b128 v[142:145], v241 offset:36864
	ds_read_b128 v[154:157], v241 offset:38912
	ds_read_b128 v[118:121], v239 offset:34816
	ds_read_b128 v[126:129], v239 offset:36864
	ds_read_b128 v[130:133], v239 offset:38912
	s_waitcnt lgkmcnt(6)
	v_mfma_f32_16x16x32_bf16 v[0:3], v[112:115], v[134:137], v[0:3]
	ds_read_b128 v[158:161], v240 offset:32768
	s_waitcnt lgkmcnt(6)
	v_mfma_f32_16x16x32_bf16 v[4:7], v[112:115], v[138:141], v[4:7]
	ds_read_b128 v[166:169], v242 offset:32768
	s_waitcnt lgkmcnt(6)
	v_mfma_f32_16x16x32_bf16 v[8:11], v[112:115], v[142:145], v[8:11]
	ds_read_b128 v[170:173], v242 offset:34816
	s_waitcnt lgkmcnt(6)
	v_mfma_f32_16x16x32_bf16 v[12:15], v[112:115], v[154:157], v[12:15]
	ds_read_b128 v[174:177], v242 offset:36864
	s_waitcnt lgkmcnt(6)
	v_mfma_f32_16x16x32_bf16 v[16:19], v[118:121], v[134:137], v[16:19]
	ds_read_b128 v[252:255], v242 offset:38912
	v_mfma_f32_16x16x32_bf16 v[20:23], v[118:121], v[138:141], v[20:23]
	ds_read_b128 v[162:165], v240 offset:34816
	v_mfma_f32_16x16x32_bf16 v[24:27], v[118:121], v[142:145], v[24:27]
	ds_read_b128 v[244:247], v240 offset:36864
	v_mfma_f32_16x16x32_bf16 v[28:31], v[118:121], v[154:157], v[28:31]
	ds_read_b128 v[248:251], v240 offset:38912
	s_add_u32 m0, s15, 0x0
	s_waitcnt lgkmcnt(9)
	v_mfma_f32_16x16x32_bf16 v[32:35], v[126:129], v[134:137], v[32:35]
	global_load_lds_dwordx4 v93, s[98:99]
	s_add_u32 m0, s15, 0x1000
	v_mfma_f32_16x16x32_bf16 v[36:39], v[126:129], v[138:141], v[36:39]
	global_load_lds_dwordx4 v94, s[98:99]
	s_add_u32 m0, s15, 0x2000
	v_mfma_f32_16x16x32_bf16 v[40:43], v[126:129], v[142:145], v[40:43]
	global_load_lds_dwordx4 v95, s[98:99]
	s_add_u32 m0, s15, 0x3000
	v_mfma_f32_16x16x32_bf16 v[44:47], v[126:129], v[154:157], v[44:47]
	global_load_lds_dwordx4 v109, s[98:99]
	s_add_u32 m0, s15, 0x4000
	s_waitcnt lgkmcnt(8)
	v_mfma_f32_16x16x32_bf16 v[48:51], v[130:133], v[134:137], v[48:51]
	global_load_lds_dwordx4 v93, s[100:101]
	s_add_u32 m0, s15, 0x5000
	v_mfma_f32_16x16x32_bf16 v[52:55], v[130:133], v[138:141], v[52:55]
	global_load_lds_dwordx4 v94, s[100:101]
	s_add_u32 m0, s15, 0x6000
	v_mfma_f32_16x16x32_bf16 v[56:59], v[130:133], v[142:145], v[56:59]
	global_load_lds_dwordx4 v95, s[100:101]
	s_add_u32 m0, s15, 0x7000
	v_mfma_f32_16x16x32_bf16 v[60:63], v[130:133], v[154:157], v[60:63]
	global_load_lds_dwordx4 v109, s[100:101]
	s_waitcnt lgkmcnt(6)
	v_mfma_f32_16x16x32_bf16 v[0:3], v[158:161], v[166:169], v[0:3]
	s_waitcnt lgkmcnt(5)
	v_mfma_f32_16x16x32_bf16 v[4:7], v[158:161], v[170:173], v[4:7]
	s_waitcnt lgkmcnt(4)
	v_mfma_f32_16x16x32_bf16 v[8:11], v[158:161], v[174:177], v[8:11]
	s_waitcnt lgkmcnt(3)
	v_mfma_f32_16x16x32_bf16 v[12:15], v[158:161], v[252:255], v[12:15]
	s_waitcnt lgkmcnt(2)
	v_mfma_f32_16x16x32_bf16 v[16:19], v[162:165], v[166:169], v[16:19]
	v_mfma_f32_16x16x32_bf16 v[20:23], v[162:165], v[170:173], v[20:23]
	v_mfma_f32_16x16x32_bf16 v[24:27], v[162:165], v[174:177], v[24:27]
	v_mfma_f32_16x16x32_bf16 v[28:31], v[162:165], v[252:255], v[28:31]
	s_waitcnt lgkmcnt(1)
	v_mfma_f32_16x16x32_bf16 v[32:35], v[244:247], v[166:169], v[32:35]
	v_mfma_f32_16x16x32_bf16 v[36:39], v[244:247], v[170:173], v[36:39]
	v_mfma_f32_16x16x32_bf16 v[40:43], v[244:247], v[174:177], v[40:43]
	v_mfma_f32_16x16x32_bf16 v[44:47], v[244:247], v[252:255], v[44:47]
	s_waitcnt lgkmcnt(0)
	v_mfma_f32_16x16x32_bf16 v[48:51], v[248:251], v[166:169], v[48:51]
	v_mfma_f32_16x16x32_bf16 v[52:55], v[248:251], v[170:173], v[52:55]
	v_mfma_f32_16x16x32_bf16 v[56:59], v[248:251], v[174:177], v[56:59]
	v_mfma_f32_16x16x32_bf16 v[60:63], v[248:251], v[252:255], v[60:63]
	s_waitcnt vmcnt(0) lgkmcnt(0)
	s_barrier
	s_add_u32 s98, s98, 0x80
	s_addc_u32 s99, s99, 0
	s_add_u32 s100, s100, 0x80
	s_addc_u32 s101, s101, 0
	ds_read_b128 v[112:115], v239
	ds_read_b128 v[134:137], v241
	ds_read_b128 v[138:141], v241 offset:2048
	ds_read_b128 v[142:145], v241 offset:4096
	ds_read_b128 v[154:157], v241 offset:6144
	ds_read_b128 v[118:121], v239 offset:2048
	ds_read_b128 v[126:129], v239 offset:4096
	ds_read_b128 v[130:133], v239 offset:6144
	s_waitcnt lgkmcnt(6)
	v_mfma_f32_16x16x32_bf16 v[0:3], v[112:115], v[134:137], v[0:3]
	ds_read_b128 v[158:161], v240
	s_waitcnt lgkmcnt(6)
	v_mfma_f32_16x16x32_bf16 v[4:7], v[112:115], v[138:141], v[4:7]
	ds_read_b128 v[166:169], v242
	s_waitcnt lgkmcnt(6)
	v_mfma_f32_16x16x32_bf16 v[8:11], v[112:115], v[142:145], v[8:11]
	ds_read_b128 v[170:173], v242 offset:2048
	s_waitcnt lgkmcnt(6)
	v_mfma_f32_16x16x32_bf16 v[12:15], v[112:115], v[154:157], v[12:15]
	ds_read_b128 v[174:177], v242 offset:4096
	s_waitcnt lgkmcnt(6)
	v_mfma_f32_16x16x32_bf16 v[16:19], v[118:121], v[134:137], v[16:19]
	ds_read_b128 v[252:255], v242 offset:6144
	v_mfma_f32_16x16x32_bf16 v[20:23], v[118:121], v[138:141], v[20:23]
	ds_read_b128 v[162:165], v240 offset:2048
	v_mfma_f32_16x16x32_bf16 v[24:27], v[118:121], v[142:145], v[24:27]
	ds_read_b128 v[244:247], v240 offset:4096
	v_mfma_f32_16x16x32_bf16 v[28:31], v[118:121], v[154:157], v[28:31]
	ds_read_b128 v[248:251], v240 offset:6144
	s_add_u32 m0, s15, 0x8000
	s_waitcnt lgkmcnt(9)
	v_mfma_f32_16x16x32_bf16 v[32:35], v[126:129], v[134:137], v[32:35]
	global_load_lds_dwordx4 v93, s[98:99]
	s_add_u32 m0, s15, 0x9000
	v_mfma_f32_16x16x32_bf16 v[36:39], v[126:129], v[138:141], v[36:39]
	global_load_lds_dwordx4 v94, s[98:99]
	s_add_u32 m0, s15, 0xa000
	v_mfma_f32_16x16x32_bf16 v[40:43], v[126:129], v[142:145], v[40:43]
	global_load_lds_dwordx4 v95, s[98:99]
	s_add_u32 m0, s15, 0xb000
	v_mfma_f32_16x16x32_bf16 v[44:47], v[126:129], v[154:157], v[44:47]
	global_load_lds_dwordx4 v109, s[98:99]
	s_add_u32 m0, s15, 0xc000
	s_waitcnt lgkmcnt(8)
	v_mfma_f32_16x16x32_bf16 v[48:51], v[130:133], v[134:137], v[48:51]
	global_load_lds_dwordx4 v93, s[100:101]
	s_add_u32 m0, s15, 0xd000
	v_mfma_f32_16x16x32_bf16 v[52:55], v[130:133], v[138:141], v[52:55]
	global_load_lds_dwordx4 v94, s[100:101]
	s_add_u32 m0, s15, 0xe000
	v_mfma_f32_16x16x32_bf16 v[56:59], v[130:133], v[142:145], v[56:59]
	global_load_lds_dwordx4 v95, s[100:101]
	s_add_u32 m0, s15, 0xf000
	v_mfma_f32_16x16x32_bf16 v[60:63], v[130:133], v[154:157], v[60:63]
	global_load_lds_dwordx4 v109, s[100:101]
	s_waitcnt lgkmcnt(6)
	v_mfma_f32_16x16x32_bf16 v[0:3], v[158:161], v[166:169], v[0:3]
	s_waitcnt lgkmcnt(5)
	v_mfma_f32_16x16x32_bf16 v[4:7], v[158:161], v[170:173], v[4:7]
	s_waitcnt lgkmcnt(4)
	v_mfma_f32_16x16x32_bf16 v[8:11], v[158:161], v[174:177], v[8:11]
	s_waitcnt lgkmcnt(3)
	v_mfma_f32_16x16x32_bf16 v[12:15], v[158:161], v[252:255], v[12:15]
	s_waitcnt lgkmcnt(2)
	v_mfma_f32_16x16x32_bf16 v[16:19], v[162:165], v[166:169], v[16:19]
	v_mfma_f32_16x16x32_bf16 v[20:23], v[162:165], v[170:173], v[20:23]
	v_mfma_f32_16x16x32_bf16 v[24:27], v[162:165], v[174:177], v[24:27]
	v_mfma_f32_16x16x32_bf16 v[28:31], v[162:165], v[252:255], v[28:31]
	s_waitcnt lgkmcnt(1)
	v_mfma_f32_16x16x32_bf16 v[32:35], v[244:247], v[166:169], v[32:35]
	v_mfma_f32_16x16x32_bf16 v[36:39], v[244:247], v[170:173], v[36:39]
	v_mfma_f32_16x16x32_bf16 v[40:43], v[244:247], v[174:177], v[40:43]
	v_mfma_f32_16x16x32_bf16 v[44:47], v[244:247], v[252:255], v[44:47]
	s_waitcnt lgkmcnt(0)
	v_mfma_f32_16x16x32_bf16 v[48:51], v[248:251], v[166:169], v[48:51]
	v_mfma_f32_16x16x32_bf16 v[52:55], v[248:251], v[170:173], v[52:55]
	v_mfma_f32_16x16x32_bf16 v[56:59], v[248:251], v[174:177], v[56:59]
	v_mfma_f32_16x16x32_bf16 v[60:63], v[248:251], v[252:255], v[60:63]
	s_waitcnt vmcnt(0) lgkmcnt(0)
	s_barrier
	s_add_u32 s98, s98, 0x80
	s_addc_u32 s99, s99, 0
	s_add_u32 s100, s100, 0x80
	s_addc_u32 s101, s101, 0
	ds_read_b128 v[112:115], v239 offset:32768
	ds_read_b128 v[134:137], v241 offset:32768
	ds_read_b128 v[138:141], v241 offset:34816
	ds_read_b128 v[142:145], v241 offset:36864
	ds_read_b128 v[154:157], v241 offset:38912
	ds_read_b128 v[118:121], v239 offset:34816
	ds_read_b128 v[126:129], v239 offset:36864
	ds_read_b128 v[130:133], v239 offset:38912
	s_waitcnt lgkmcnt(6)
	v_mfma_f32_16x16x32_bf16 v[0:3], v[112:115], v[134:137], v[0:3]
	ds_read_b128 v[158:161], v240 offset:32768
	s_waitcnt lgkmcnt(6)
	v_mfma_f32_16x16x32_bf16 v[4:7], v[112:115], v[138:141], v[4:7]
	ds_read_b128 v[166:169], v242 offset:32768
	s_waitcnt lgkmcnt(6)
	v_mfma_f32_16x16x32_bf16 v[8:11], v[112:115], v[142:145], v[8:11]
	ds_read_b128 v[170:173], v242 offset:34816
	s_waitcnt lgkmcnt(6)
	v_mfma_f32_16x16x32_bf16 v[12:15], v[112:115], v[154:157], v[12:15]
	ds_read_b128 v[174:177], v242 offset:36864
	s_waitcnt lgkmcnt(6)
	v_mfma_f32_16x16x32_bf16 v[16:19], v[118:121], v[134:137], v[16:19]
	ds_read_b128 v[252:255], v242 offset:38912
	v_mfma_f32_16x16x32_bf16 v[20:23], v[118:121], v[138:141], v[20:23]
	ds_read_b128 v[162:165], v240 offset:34816
	v_mfma_f32_16x16x32_bf16 v[24:27], v[118:121], v[142:145], v[24:27]
	ds_read_b128 v[244:247], v240 offset:36864
	v_mfma_f32_16x16x32_bf16 v[28:31], v[118:121], v[154:157], v[28:31]
	ds_read_b128 v[248:251], v240 offset:38912
	s_add_u32 m0, s15, 0x0
	s_waitcnt lgkmcnt(9)
	v_mfma_f32_16x16x32_bf16 v[32:35], v[126:129], v[134:137], v[32:35]
	global_load_lds_dwordx4 v93, s[98:99]
	s_add_u32 m0, s15, 0x1000
	v_mfma_f32_16x16x32_bf16 v[36:39], v[126:129], v[138:141], v[36:39]
	global_load_lds_dwordx4 v94, s[98:99]
	s_add_u32 m0, s15, 0x2000
	v_mfma_f32_16x16x32_bf16 v[40:43], v[126:129], v[142:145], v[40:43]
	global_load_lds_dwordx4 v95, s[98:99]
	s_add_u32 m0, s15, 0x3000
	v_mfma_f32_16x16x32_bf16 v[44:47], v[126:129], v[154:157], v[44:47]
	global_load_lds_dwordx4 v109, s[98:99]
	s_add_u32 m0, s15, 0x4000
	s_waitcnt lgkmcnt(8)
	v_mfma_f32_16x16x32_bf16 v[48:51], v[130:133], v[134:137], v[48:51]
	global_load_lds_dwordx4 v93, s[100:101]
	s_add_u32 m0, s15, 0x5000
	v_mfma_f32_16x16x32_bf16 v[52:55], v[130:133], v[138:141], v[52:55]
	global_load_lds_dwordx4 v94, s[100:101]
	s_add_u32 m0, s15, 0x6000
	v_mfma_f32_16x16x32_bf16 v[56:59], v[130:133], v[142:145], v[56:59]
	global_load_lds_dwordx4 v95, s[100:101]
	s_add_u32 m0, s15, 0x7000
	v_mfma_f32_16x16x32_bf16 v[60:63], v[130:133], v[154:157], v[60:63]
	global_load_lds_dwordx4 v109, s[100:101]
	s_waitcnt lgkmcnt(6)
	v_mfma_f32_16x16x32_bf16 v[0:3], v[158:161], v[166:169], v[0:3]
	s_waitcnt lgkmcnt(5)
	v_mfma_f32_16x16x32_bf16 v[4:7], v[158:161], v[170:173], v[4:7]
	s_waitcnt lgkmcnt(4)
	v_mfma_f32_16x16x32_bf16 v[8:11], v[158:161], v[174:177], v[8:11]
	s_waitcnt lgkmcnt(3)
	v_mfma_f32_16x16x32_bf16 v[12:15], v[158:161], v[252:255], v[12:15]
	s_waitcnt lgkmcnt(2)
	v_mfma_f32_16x16x32_bf16 v[16:19], v[162:165], v[166:169], v[16:19]
	v_mfma_f32_16x16x32_bf16 v[20:23], v[162:165], v[170:173], v[20:23]
	v_mfma_f32_16x16x32_bf16 v[24:27], v[162:165], v[174:177], v[24:27]
	v_mfma_f32_16x16x32_bf16 v[28:31], v[162:165], v[252:255], v[28:31]
	s_waitcnt lgkmcnt(1)
	v_mfma_f32_16x16x32_bf16 v[32:35], v[244:247], v[166:169], v[32:35]
	v_mfma_f32_16x16x32_bf16 v[36:39], v[244:247], v[170:173], v[36:39]
	v_mfma_f32_16x16x32_bf16 v[40:43], v[244:247], v[174:177], v[40:43]
	v_mfma_f32_16x16x32_bf16 v[44:47], v[244:247], v[252:255], v[44:47]
	s_waitcnt lgkmcnt(0)
	v_mfma_f32_16x16x32_bf16 v[48:51], v[248:251], v[166:169], v[48:51]
	v_mfma_f32_16x16x32_bf16 v[52:55], v[248:251], v[170:173], v[52:55]
	v_mfma_f32_16x16x32_bf16 v[56:59], v[248:251], v[174:177], v[56:59]
	v_mfma_f32_16x16x32_bf16 v[60:63], v[248:251], v[252:255], v[60:63]
	s_waitcnt vmcnt(0) lgkmcnt(0)
	s_barrier
	s_add_u32 s98, s98, 0x80
	s_addc_u32 s99, s99, 0
	s_add_u32 s100, s100, 0x80
	s_addc_u32 s101, s101, 0
	ds_read_b128 v[112:115], v239
	ds_read_b128 v[134:137], v241
	ds_read_b128 v[138:141], v241 offset:2048
	ds_read_b128 v[142:145], v241 offset:4096
	ds_read_b128 v[154:157], v241 offset:6144
	ds_read_b128 v[118:121], v239 offset:2048
	ds_read_b128 v[126:129], v239 offset:4096
	ds_read_b128 v[130:133], v239 offset:6144
	s_waitcnt lgkmcnt(6)
	v_mfma_f32_16x16x32_bf16 v[0:3], v[112:115], v[134:137], v[0:3]
	ds_read_b128 v[158:161], v240
	s_waitcnt lgkmcnt(6)
	v_mfma_f32_16x16x32_bf16 v[4:7], v[112:115], v[138:141], v[4:7]
	ds_read_b128 v[166:169], v242
	s_waitcnt lgkmcnt(6)
	v_mfma_f32_16x16x32_bf16 v[8:11], v[112:115], v[142:145], v[8:11]
	ds_read_b128 v[170:173], v242 offset:2048
	s_waitcnt lgkmcnt(6)
	v_mfma_f32_16x16x32_bf16 v[12:15], v[112:115], v[154:157], v[12:15]
	ds_read_b128 v[174:177], v242 offset:4096
	s_waitcnt lgkmcnt(6)
	v_mfma_f32_16x16x32_bf16 v[16:19], v[118:121], v[134:137], v[16:19]
	ds_read_b128 v[252:255], v242 offset:6144
	v_mfma_f32_16x16x32_bf16 v[20:23], v[118:121], v[138:141], v[20:23]
	ds_read_b128 v[162:165], v240 offset:2048
	v_mfma_f32_16x16x32_bf16 v[24:27], v[118:121], v[142:145], v[24:27]
	ds_read_b128 v[244:247], v240 offset:4096
	v_mfma_f32_16x16x32_bf16 v[28:31], v[118:121], v[154:157], v[28:31]
	ds_read_b128 v[248:251], v240 offset:6144
	s_add_u32 m0, s15, 0x8000
	s_waitcnt lgkmcnt(9)
	v_mfma_f32_16x16x32_bf16 v[32:35], v[126:129], v[134:137], v[32:35]
	global_load_lds_dwordx4 v93, s[98:99]
	s_add_u32 m0, s15, 0x9000
	v_mfma_f32_16x16x32_bf16 v[36:39], v[126:129], v[138:141], v[36:39]
	global_load_lds_dwordx4 v94, s[98:99]
	s_add_u32 m0, s15, 0xa000
	v_mfma_f32_16x16x32_bf16 v[40:43], v[126:129], v[142:145], v[40:43]
	global_load_lds_dwordx4 v95, s[98:99]
	s_add_u32 m0, s15, 0xb000
	v_mfma_f32_16x16x32_bf16 v[44:47], v[126:129], v[154:157], v[44:47]
	global_load_lds_dwordx4 v109, s[98:99]
	s_add_u32 m0, s15, 0xc000
	s_waitcnt lgkmcnt(8)
	v_mfma_f32_16x16x32_bf16 v[48:51], v[130:133], v[134:137], v[48:51]
	global_load_lds_dwordx4 v93, s[100:101]
	s_add_u32 m0, s15, 0xd000
	v_mfma_f32_16x16x32_bf16 v[52:55], v[130:133], v[138:141], v[52:55]
	global_load_lds_dwordx4 v94, s[100:101]
	s_add_u32 m0, s15, 0xe000
	v_mfma_f32_16x16x32_bf16 v[56:59], v[130:133], v[142:145], v[56:59]
	global_load_lds_dwordx4 v95, s[100:101]
	s_add_u32 m0, s15, 0xf000
	v_mfma_f32_16x16x32_bf16 v[60:63], v[130:133], v[154:157], v[60:63]
	global_load_lds_dwordx4 v109, s[100:101]
	s_waitcnt lgkmcnt(6)
	v_mfma_f32_16x16x32_bf16 v[0:3], v[158:161], v[166:169], v[0:3]
	s_waitcnt lgkmcnt(5)
	v_mfma_f32_16x16x32_bf16 v[4:7], v[158:161], v[170:173], v[4:7]
	s_waitcnt lgkmcnt(4)
	v_mfma_f32_16x16x32_bf16 v[8:11], v[158:161], v[174:177], v[8:11]
	s_waitcnt lgkmcnt(3)
	v_mfma_f32_16x16x32_bf16 v[12:15], v[158:161], v[252:255], v[12:15]
	s_waitcnt lgkmcnt(2)
	v_mfma_f32_16x16x32_bf16 v[16:19], v[162:165], v[166:169], v[16:19]
	v_mfma_f32_16x16x32_bf16 v[20:23], v[162:165], v[170:173], v[20:23]
	v_mfma_f32_16x16x32_bf16 v[24:27], v[162:165], v[174:177], v[24:27]
	v_mfma_f32_16x16x32_bf16 v[28:31], v[162:165], v[252:255], v[28:31]
	s_waitcnt lgkmcnt(1)
	v_mfma_f32_16x16x32_bf16 v[32:35], v[244:247], v[166:169], v[32:35]
	v_mfma_f32_16x16x32_bf16 v[36:39], v[244:247], v[170:173], v[36:39]
	v_mfma_f32_16x16x32_bf16 v[40:43], v[244:247], v[174:177], v[40:43]
	v_mfma_f32_16x16x32_bf16 v[44:47], v[244:247], v[252:255], v[44:47]
	s_waitcnt lgkmcnt(0)
	v_mfma_f32_16x16x32_bf16 v[48:51], v[248:251], v[166:169], v[48:51]
	v_mfma_f32_16x16x32_bf16 v[52:55], v[248:251], v[170:173], v[52:55]
	v_mfma_f32_16x16x32_bf16 v[56:59], v[248:251], v[174:177], v[56:59]
	v_mfma_f32_16x16x32_bf16 v[60:63], v[248:251], v[252:255], v[60:63]
	s_waitcnt vmcnt(0) lgkmcnt(0)
	s_barrier
	s_add_u32 s98, s98, 0x80
	s_addc_u32 s99, s99, 0
	s_add_u32 s100, s100, 0x80
	s_addc_u32 s101, s101, 0
	ds_read_b128 v[112:115], v239 offset:32768
	ds_read_b128 v[134:137], v241 offset:32768
	ds_read_b128 v[138:141], v241 offset:34816
	ds_read_b128 v[142:145], v241 offset:36864
	ds_read_b128 v[154:157], v241 offset:38912
	ds_read_b128 v[118:121], v239 offset:34816
	ds_read_b128 v[126:129], v239 offset:36864
	ds_read_b128 v[130:133], v239 offset:38912
	s_waitcnt lgkmcnt(6)
	v_mfma_f32_16x16x32_bf16 v[0:3], v[112:115], v[134:137], v[0:3]
	ds_read_b128 v[158:161], v240 offset:32768
	s_waitcnt lgkmcnt(6)
	v_mfma_f32_16x16x32_bf16 v[4:7], v[112:115], v[138:141], v[4:7]
	ds_read_b128 v[166:169], v242 offset:32768
	s_waitcnt lgkmcnt(6)
	v_mfma_f32_16x16x32_bf16 v[8:11], v[112:115], v[142:145], v[8:11]
	ds_read_b128 v[170:173], v242 offset:34816
	s_waitcnt lgkmcnt(6)
	v_mfma_f32_16x16x32_bf16 v[12:15], v[112:115], v[154:157], v[12:15]
	ds_read_b128 v[174:177], v242 offset:36864
	s_waitcnt lgkmcnt(6)
	v_mfma_f32_16x16x32_bf16 v[16:19], v[118:121], v[134:137], v[16:19]
	ds_read_b128 v[252:255], v242 offset:38912
	v_mfma_f32_16x16x32_bf16 v[20:23], v[118:121], v[138:141], v[20:23]
	ds_read_b128 v[162:165], v240 offset:34816
	v_mfma_f32_16x16x32_bf16 v[24:27], v[118:121], v[142:145], v[24:27]
	ds_read_b128 v[244:247], v240 offset:36864
	v_mfma_f32_16x16x32_bf16 v[28:31], v[118:121], v[154:157], v[28:31]
	ds_read_b128 v[248:251], v240 offset:38912
	s_add_u32 m0, s15, 0x0
	s_waitcnt lgkmcnt(9)
	v_mfma_f32_16x16x32_bf16 v[32:35], v[126:129], v[134:137], v[32:35]
	global_load_lds_dwordx4 v93, s[98:99]
	s_add_u32 m0, s15, 0x1000
	v_mfma_f32_16x16x32_bf16 v[36:39], v[126:129], v[138:141], v[36:39]
	global_load_lds_dwordx4 v94, s[98:99]
	s_add_u32 m0, s15, 0x2000
	v_mfma_f32_16x16x32_bf16 v[40:43], v[126:129], v[142:145], v[40:43]
	global_load_lds_dwordx4 v95, s[98:99]
	s_add_u32 m0, s15, 0x3000
	v_mfma_f32_16x16x32_bf16 v[44:47], v[126:129], v[154:157], v[44:47]
	global_load_lds_dwordx4 v109, s[98:99]
	s_add_u32 m0, s15, 0x4000
	s_waitcnt lgkmcnt(8)
	v_mfma_f32_16x16x32_bf16 v[48:51], v[130:133], v[134:137], v[48:51]
	global_load_lds_dwordx4 v93, s[100:101]
	s_add_u32 m0, s15, 0x5000
	v_mfma_f32_16x16x32_bf16 v[52:55], v[130:133], v[138:141], v[52:55]
	global_load_lds_dwordx4 v94, s[100:101]
	s_add_u32 m0, s15, 0x6000
	v_mfma_f32_16x16x32_bf16 v[56:59], v[130:133], v[142:145], v[56:59]
	global_load_lds_dwordx4 v95, s[100:101]
	s_add_u32 m0, s15, 0x7000
	v_mfma_f32_16x16x32_bf16 v[60:63], v[130:133], v[154:157], v[60:63]
	global_load_lds_dwordx4 v109, s[100:101]
	s_waitcnt lgkmcnt(6)
	v_mfma_f32_16x16x32_bf16 v[0:3], v[158:161], v[166:169], v[0:3]
	s_waitcnt lgkmcnt(5)
	v_mfma_f32_16x16x32_bf16 v[4:7], v[158:161], v[170:173], v[4:7]
	s_waitcnt lgkmcnt(4)
	v_mfma_f32_16x16x32_bf16 v[8:11], v[158:161], v[174:177], v[8:11]
	s_waitcnt lgkmcnt(3)
	v_mfma_f32_16x16x32_bf16 v[12:15], v[158:161], v[252:255], v[12:15]
	s_waitcnt lgkmcnt(2)
	v_mfma_f32_16x16x32_bf16 v[16:19], v[162:165], v[166:169], v[16:19]
	v_mfma_f32_16x16x32_bf16 v[20:23], v[162:165], v[170:173], v[20:23]
	v_mfma_f32_16x16x32_bf16 v[24:27], v[162:165], v[174:177], v[24:27]
	v_mfma_f32_16x16x32_bf16 v[28:31], v[162:165], v[252:255], v[28:31]
	s_waitcnt lgkmcnt(1)
	v_mfma_f32_16x16x32_bf16 v[32:35], v[244:247], v[166:169], v[32:35]
	v_mfma_f32_16x16x32_bf16 v[36:39], v[244:247], v[170:173], v[36:39]
	v_mfma_f32_16x16x32_bf16 v[40:43], v[244:247], v[174:177], v[40:43]
	v_mfma_f32_16x16x32_bf16 v[44:47], v[244:247], v[252:255], v[44:47]
	s_waitcnt lgkmcnt(0)
	v_mfma_f32_16x16x32_bf16 v[48:51], v[248:251], v[166:169], v[48:51]
	v_mfma_f32_16x16x32_bf16 v[52:55], v[248:251], v[170:173], v[52:55]
	v_mfma_f32_16x16x32_bf16 v[56:59], v[248:251], v[174:177], v[56:59]
	v_mfma_f32_16x16x32_bf16 v[60:63], v[248:251], v[252:255], v[60:63]
	s_waitcnt vmcnt(0) lgkmcnt(0)
	s_barrier
	s_add_u32 s98, s98, 0x80
	s_addc_u32 s99, s99, 0
	s_add_u32 s100, s100, 0x80
	s_addc_u32 s101, s101, 0
	ds_read_b128 v[112:115], v239
	ds_read_b128 v[134:137], v241
	ds_read_b128 v[138:141], v241 offset:2048
	ds_read_b128 v[142:145], v241 offset:4096
	ds_read_b128 v[154:157], v241 offset:6144
	ds_read_b128 v[118:121], v239 offset:2048
	ds_read_b128 v[126:129], v239 offset:4096
	ds_read_b128 v[130:133], v239 offset:6144
	s_waitcnt lgkmcnt(6)
	v_mfma_f32_16x16x32_bf16 v[0:3], v[112:115], v[134:137], v[0:3]
	ds_read_b128 v[158:161], v240
	s_waitcnt lgkmcnt(6)
	v_mfma_f32_16x16x32_bf16 v[4:7], v[112:115], v[138:141], v[4:7]
	ds_read_b128 v[166:169], v242
	s_waitcnt lgkmcnt(6)
	v_mfma_f32_16x16x32_bf16 v[8:11], v[112:115], v[142:145], v[8:11]
	ds_read_b128 v[170:173], v242 offset:2048
	s_waitcnt lgkmcnt(6)
	v_mfma_f32_16x16x32_bf16 v[12:15], v[112:115], v[154:157], v[12:15]
	ds_read_b128 v[174:177], v242 offset:4096
	s_waitcnt lgkmcnt(6)
	v_mfma_f32_16x16x32_bf16 v[16:19], v[118:121], v[134:137], v[16:19]
	ds_read_b128 v[252:255], v242 offset:6144
	v_mfma_f32_16x16x32_bf16 v[20:23], v[118:121], v[138:141], v[20:23]
	ds_read_b128 v[162:165], v240 offset:2048
	v_mfma_f32_16x16x32_bf16 v[24:27], v[118:121], v[142:145], v[24:27]
	ds_read_b128 v[244:247], v240 offset:4096
	v_mfma_f32_16x16x32_bf16 v[28:31], v[118:121], v[154:157], v[28:31]
	ds_read_b128 v[248:251], v240 offset:6144
	s_add_u32 m0, s15, 0x8000
	s_waitcnt lgkmcnt(9)
	v_mfma_f32_16x16x32_bf16 v[32:35], v[126:129], v[134:137], v[32:35]
	global_load_lds_dwordx4 v93, s[98:99]
	s_add_u32 m0, s15, 0x9000
	v_mfma_f32_16x16x32_bf16 v[36:39], v[126:129], v[138:141], v[36:39]
	global_load_lds_dwordx4 v94, s[98:99]
	s_add_u32 m0, s15, 0xa000
	v_mfma_f32_16x16x32_bf16 v[40:43], v[126:129], v[142:145], v[40:43]
	global_load_lds_dwordx4 v95, s[98:99]
	s_add_u32 m0, s15, 0xb000
	v_mfma_f32_16x16x32_bf16 v[44:47], v[126:129], v[154:157], v[44:47]
	global_load_lds_dwordx4 v109, s[98:99]
	s_add_u32 m0, s15, 0xc000
	s_waitcnt lgkmcnt(8)
	v_mfma_f32_16x16x32_bf16 v[48:51], v[130:133], v[134:137], v[48:51]
	global_load_lds_dwordx4 v93, s[100:101]
	s_add_u32 m0, s15, 0xd000
	v_mfma_f32_16x16x32_bf16 v[52:55], v[130:133], v[138:141], v[52:55]
	global_load_lds_dwordx4 v94, s[100:101]
	s_add_u32 m0, s15, 0xe000
	v_mfma_f32_16x16x32_bf16 v[56:59], v[130:133], v[142:145], v[56:59]
	global_load_lds_dwordx4 v95, s[100:101]
	s_add_u32 m0, s15, 0xf000
	v_mfma_f32_16x16x32_bf16 v[60:63], v[130:133], v[154:157], v[60:63]
	global_load_lds_dwordx4 v109, s[100:101]
	s_waitcnt lgkmcnt(6)
	v_mfma_f32_16x16x32_bf16 v[0:3], v[158:161], v[166:169], v[0:3]
	s_waitcnt lgkmcnt(5)
	v_mfma_f32_16x16x32_bf16 v[4:7], v[158:161], v[170:173], v[4:7]
	s_waitcnt lgkmcnt(4)
	v_mfma_f32_16x16x32_bf16 v[8:11], v[158:161], v[174:177], v[8:11]
	s_waitcnt lgkmcnt(3)
	v_mfma_f32_16x16x32_bf16 v[12:15], v[158:161], v[252:255], v[12:15]
	s_waitcnt lgkmcnt(2)
	v_mfma_f32_16x16x32_bf16 v[16:19], v[162:165], v[166:169], v[16:19]
	v_mfma_f32_16x16x32_bf16 v[20:23], v[162:165], v[170:173], v[20:23]
	v_mfma_f32_16x16x32_bf16 v[24:27], v[162:165], v[174:177], v[24:27]
	v_mfma_f32_16x16x32_bf16 v[28:31], v[162:165], v[252:255], v[28:31]
	s_waitcnt lgkmcnt(1)
	v_mfma_f32_16x16x32_bf16 v[32:35], v[244:247], v[166:169], v[32:35]
	v_mfma_f32_16x16x32_bf16 v[36:39], v[244:247], v[170:173], v[36:39]
	v_mfma_f32_16x16x32_bf16 v[40:43], v[244:247], v[174:177], v[40:43]
	v_mfma_f32_16x16x32_bf16 v[44:47], v[244:247], v[252:255], v[44:47]
	s_waitcnt lgkmcnt(0)
	v_mfma_f32_16x16x32_bf16 v[48:51], v[248:251], v[166:169], v[48:51]
	v_mfma_f32_16x16x32_bf16 v[52:55], v[248:251], v[170:173], v[52:55]
	v_mfma_f32_16x16x32_bf16 v[56:59], v[248:251], v[174:177], v[56:59]
	v_mfma_f32_16x16x32_bf16 v[60:63], v[248:251], v[252:255], v[60:63]
	s_waitcnt vmcnt(0) lgkmcnt(0)
	s_barrier
	ds_read_b128 v[112:115], v239 offset:32768
	ds_read_b128 v[134:137], v241 offset:32768
	ds_read_b128 v[138:141], v241 offset:34816
	ds_read_b128 v[142:145], v241 offset:36864
	ds_read_b128 v[154:157], v241 offset:38912
	ds_read_b128 v[118:121], v239 offset:34816
	ds_read_b128 v[126:129], v239 offset:36864
	ds_read_b128 v[130:133], v239 offset:38912
	s_waitcnt lgkmcnt(6)
	v_mfma_f32_16x16x32_bf16 v[0:3], v[112:115], v[134:137], v[0:3]
	ds_read_b128 v[158:161], v240 offset:32768
	s_waitcnt lgkmcnt(6)
	v_mfma_f32_16x16x32_bf16 v[4:7], v[112:115], v[138:141], v[4:7]
	ds_read_b128 v[166:169], v242 offset:32768
	s_waitcnt lgkmcnt(6)
	v_mfma_f32_16x16x32_bf16 v[8:11], v[112:115], v[142:145], v[8:11]
	ds_read_b128 v[170:173], v242 offset:34816
	s_waitcnt lgkmcnt(6)
	v_mfma_f32_16x16x32_bf16 v[12:15], v[112:115], v[154:157], v[12:15]
	ds_read_b128 v[174:177], v242 offset:36864
	s_waitcnt lgkmcnt(6)
	v_mfma_f32_16x16x32_bf16 v[16:19], v[118:121], v[134:137], v[16:19]
	ds_read_b128 v[252:255], v242 offset:38912
	v_mfma_f32_16x16x32_bf16 v[20:23], v[118:121], v[138:141], v[20:23]
	ds_read_b128 v[162:165], v240 offset:34816
	v_mfma_f32_16x16x32_bf16 v[24:27], v[118:121], v[142:145], v[24:27]
	ds_read_b128 v[244:247], v240 offset:36864
	v_mfma_f32_16x16x32_bf16 v[28:31], v[118:121], v[154:157], v[28:31]
	ds_read_b128 v[248:251], v240 offset:38912
	s_waitcnt lgkmcnt(9)
	v_mfma_f32_16x16x32_bf16 v[32:35], v[126:129], v[134:137], v[32:35]
	v_mfma_f32_16x16x32_bf16 v[36:39], v[126:129], v[138:141], v[36:39]
	v_mfma_f32_16x16x32_bf16 v[40:43], v[126:129], v[142:145], v[40:43]
	v_mfma_f32_16x16x32_bf16 v[44:47], v[126:129], v[154:157], v[44:47]
	s_waitcnt lgkmcnt(8)
	v_mfma_f32_16x16x32_bf16 v[48:51], v[130:133], v[134:137], v[48:51]
	v_mfma_f32_16x16x32_bf16 v[52:55], v[130:133], v[138:141], v[52:55]
	v_mfma_f32_16x16x32_bf16 v[56:59], v[130:133], v[142:145], v[56:59]
	v_mfma_f32_16x16x32_bf16 v[60:63], v[130:133], v[154:157], v[60:63]
	s_waitcnt lgkmcnt(6)
	v_mfma_f32_16x16x32_bf16 v[0:3], v[158:161], v[166:169], v[0:3]
	s_waitcnt lgkmcnt(5)
	v_mfma_f32_16x16x32_bf16 v[4:7], v[158:161], v[170:173], v[4:7]
	s_waitcnt lgkmcnt(4)
	v_mfma_f32_16x16x32_bf16 v[8:11], v[158:161], v[174:177], v[8:11]
	s_waitcnt lgkmcnt(3)
	v_mfma_f32_16x16x32_bf16 v[12:15], v[158:161], v[252:255], v[12:15]
	s_waitcnt lgkmcnt(2)
	v_mfma_f32_16x16x32_bf16 v[16:19], v[162:165], v[166:169], v[16:19]
	v_mfma_f32_16x16x32_bf16 v[20:23], v[162:165], v[170:173], v[20:23]
	v_mfma_f32_16x16x32_bf16 v[24:27], v[162:165], v[174:177], v[24:27]
	v_mfma_f32_16x16x32_bf16 v[28:31], v[162:165], v[252:255], v[28:31]
	s_waitcnt lgkmcnt(1)
	v_mfma_f32_16x16x32_bf16 v[32:35], v[244:247], v[166:169], v[32:35]
	v_mfma_f32_16x16x32_bf16 v[36:39], v[244:247], v[170:173], v[36:39]
	v_mfma_f32_16x16x32_bf16 v[40:43], v[244:247], v[174:177], v[40:43]
	v_mfma_f32_16x16x32_bf16 v[44:47], v[244:247], v[252:255], v[44:47]
	s_waitcnt lgkmcnt(0)
	v_mfma_f32_16x16x32_bf16 v[48:51], v[248:251], v[166:169], v[48:51]
	v_mfma_f32_16x16x32_bf16 v[52:55], v[248:251], v[170:173], v[52:55]
	v_mfma_f32_16x16x32_bf16 v[56:59], v[248:251], v[174:177], v[56:59]
	v_mfma_f32_16x16x32_bf16 v[60:63], v[248:251], v[252:255], v[60:63]
	s_waitcnt vmcnt(0) lgkmcnt(0)
	s_barrier
	s_nop 15
	ds_write_b32 v243, v0
	ds_write_b32 v243, v1 offset:528
	ds_write_b32 v243, v2 offset:1056
	ds_write_b32 v243, v3 offset:1584
	ds_write_b32 v243, v4 offset:64
	ds_write_b32 v243, v5 offset:592
	ds_write_b32 v243, v6 offset:1120
	ds_write_b32 v243, v7 offset:1648
	ds_write_b32 v243, v8 offset:128
	ds_write_b32 v243, v9 offset:656
	ds_write_b32 v243, v10 offset:1184
	ds_write_b32 v243, v11 offset:1712
	ds_write_b32 v243, v12 offset:192
	ds_write_b32 v243, v13 offset:720
	ds_write_b32 v243, v14 offset:1248
	ds_write_b32 v243, v15 offset:1776
	ds_write_b32 v243, v16 offset:8448
	ds_write_b32 v243, v17 offset:8976
	ds_write_b32 v243, v18 offset:9504
	ds_write_b32 v243, v19 offset:10032
	ds_write_b32 v243, v20 offset:8512
	ds_write_b32 v243, v21 offset:9040
	ds_write_b32 v243, v22 offset:9568
	ds_write_b32 v243, v23 offset:10096
	ds_write_b32 v243, v24 offset:8576
	ds_write_b32 v243, v25 offset:9104
	ds_write_b32 v243, v26 offset:9632
	ds_write_b32 v243, v27 offset:10160
	ds_write_b32 v243, v28 offset:8640
	ds_write_b32 v243, v29 offset:9168
	ds_write_b32 v243, v30 offset:9696
	ds_write_b32 v243, v31 offset:10224
	ds_write_b32 v243, v32 offset:16896
	ds_write_b32 v243, v33 offset:17424
	ds_write_b32 v243, v34 offset:17952
	ds_write_b32 v243, v35 offset:18480
	ds_write_b32 v243, v36 offset:16960
	ds_write_b32 v243, v37 offset:17488
	ds_write_b32 v243, v38 offset:18016
	ds_write_b32 v243, v39 offset:18544
	ds_write_b32 v243, v40 offset:17024
	ds_write_b32 v243, v41 offset:17552
	ds_write_b32 v243, v42 offset:18080
	ds_write_b32 v243, v43 offset:18608
	ds_write_b32 v243, v44 offset:17088
	ds_write_b32 v243, v45 offset:17616
	ds_write_b32 v243, v46 offset:18144
	ds_write_b32 v243, v47 offset:18672
	ds_write_b32 v243, v48 offset:25344
	ds_write_b32 v243, v49 offset:25872
	ds_write_b32 v243, v50 offset:26400
	ds_write_b32 v243, v51 offset:26928
	ds_write_b32 v243, v52 offset:25408
	ds_write_b32 v243, v53 offset:25936
	ds_write_b32 v243, v54 offset:26464
	ds_write_b32 v243, v55 offset:26992
	ds_write_b32 v243, v56 offset:25472
	ds_write_b32 v243, v57 offset:26000
	ds_write_b32 v243, v58 offset:26528
	ds_write_b32 v243, v59 offset:27056
	ds_write_b32 v243, v60 offset:25536
	ds_write_b32 v243, v61 offset:26064
	ds_write_b32 v243, v62 offset:26592
	ds_write_b32 v243, v63 offset:27120
	v_or_b32_e32 v2, s25, v74
	v_ashrrev_i32_e32 v3, 31, v2
	v_lshl_add_u64 v[0:1], v[2:3], 2, s[54:55]
	v_or_b32_e32 v4, s24, v82
	v_or_b32_e32 v5, s24, v86
	v_or_b32_e32 v6, s24, v89
	v_or_b32_e32 v7, s24, v147
	v_lshlrev_b64 v[2:3], 2, v[2:3]
	v_mov_b32_e32 v8, v84
	v_mov_b32_e32 v9, v90
	v_mov_b32_e32 v10, v87
	v_mov_b32_e32 v11, v83
	s_waitcnt lgkmcnt(0)
	s_barrier

.LBB0_922:
	s_and_b64 vcc, exec, s[10:11]
	s_cbranch_vccz .LBB0_881
	s_ashr_i32 s10, s2, 31
	s_lshr_b32 s10, s10, 29
	s_add_i32 s10, s2, s10
	s_lshl_b32 s11, s10, 4
	s_and_b32 s10, s10, 0x1fffff8
	s_sub_i32 s10, s2, s10
	s_and_b32 s20, s11, 0xffffff80
	s_lshl_b32 s10, s10, 7
	v_add_u32_e32 v0, s20, v105
	v_add_u32_e32 v16, s10, v105
	v_ashrrev_i32_e32 v1, 31, v0
	v_ashrrev_i32_e32 v17, 31, v16
	v_lshlrev_b64 v[0:1], 11, v[0:1]
	v_lshlrev_b64 v[16:17], 11, v[16:17]
	v_lshl_add_u64 v[78:79], v[68:69], 0, v[0:1]
	v_lshl_add_u64 v[80:81], v[76:77], 0, v[16:17]
	v_readfirstlane_b32 s98, v68
	v_readfirstlane_b32 s99, v69
	v_readfirstlane_b32 s100, v76
	v_readfirstlane_b32 s101, v77
	s_lshl_b32 s11, s20, 11
	s_add_u32 s98, s98, s11
	s_addc_u32 s99, s99, 0
	s_lshl_b32 s11, s10, 11
	s_add_u32 s100, s100, s11
	s_addc_u32 s101, s101, 0
	v_lshrrev_b32_e32 v246, 3, v100
	v_and_b32_e32 v247, 7, v100
	v_bfe_u32 v244, v100, 4, 3
	v_xor_b32_e32 v244, v244, v247
	v_lshlrev_b32_e32 v244, 4, v244
	v_lshl_or_b32 v124, v246, 7, v244
	v_lshlrev_b32_e32 v245, 4, v247
	v_lshl_or_b32 v115, v246, 11, v244
	v_add_u32_e32 v116, 0x10000, v115
	v_add_u32_e32 v122, 0x20000, v115
	v_add_u32_e32 v123, 0x30000, v115
	v_and_b32_e32 v244, 15, v100
	v_bfe_u32 v245, v100, 4, 2
	v_bfe_u32 v246, v100, 1, 3
	v_xor_b32_e32 v247, v245, v246
	v_lshlrev_b32_e32 v247, 4, v247
	v_lshl_or_b32 v247, v244, 7, v247
	v_bfe_u32 v246, v100, 7, 1
	v_lshl_add_u32 v239, v246, 13, v247
	v_xor_b32_e32 v240, 64, v239
	v_bfe_u32 v246, v100, 6, 1
	v_lshl_add_u32 v241, v246, 13, v247
	v_add_u32_e32 v241, 0x4000, v241
	v_xor_b32_e32 v242, 64, v241
	v_bfe_u32 v247, v100, 7, 1
	v_lshlrev_b32_e32 v247, 6, v247
	v_lshl_add_u32 v247, v245, 2, v247
	v_mul_u32_u24_e32 v247, 0x84, v247
	v_lshl_add_u32 v247, v246, 6, v247
	v_add_u32_e32 v247, v247, v244
	v_lshlrev_b32_e32 v243, 2, v247
	v_lshrrev_b32_e32 v244, 6, v100
	v_lshlrev_b32_e32 v244, 10, v244
	s_nop 1
	v_readfirstlane_b32 s11, v244
	s_nop 3
	s_add_u32 m0, s11, 0x0
	s_nop 0
	global_load_lds_dwordx4 v115, s[98:99]
	s_add_u32 m0, s11, 0x1000
	s_nop 0
	global_load_lds_dwordx4 v116, s[98:99]
	s_add_u32 m0, s11, 0x2000
	s_nop 0
	global_load_lds_dwordx4 v122, s[98:99]
	s_add_u32 m0, s11, 0x3000
	s_nop 0
	global_load_lds_dwordx4 v123, s[98:99]
	s_add_u32 m0, s11, 0x4000
	s_nop 0
	global_load_lds_dwordx4 v115, s[100:101]
	s_add_u32 m0, s11, 0x5000
	s_nop 0
	global_load_lds_dwordx4 v116, s[100:101]
	s_add_u32 m0, s11, 0x6000
	s_nop 0
	global_load_lds_dwordx4 v122, s[100:101]
	s_add_u32 m0, s11, 0x7000
	s_nop 0
	global_load_lds_dwordx4 v123, s[100:101]
	v_readlane_b32 s44, v238, 32
	v_readlane_b32 s56, v238, 44
	v_readlane_b32 s57, v238, 45
	v_readlane_b32 s58, v238, 46
	v_readlane_b32 s59, v238, 47
	s_mov_b64 s[24:25], s[56:57]
	v_readlane_b32 s45, v238, 33
	v_readlane_b32 s46, v238, 34
	v_readlane_b32 s47, v238, 35
	v_readlane_b32 s48, v238, 36
	v_readlane_b32 s49, v238, 37
	v_readlane_b32 s50, v238, 38
	v_readlane_b32 s51, v238, 39
	v_readlane_b32 s52, v238, 40
	v_readlane_b32 s53, v238, 41
	v_readlane_b32 s54, v238, 42
	v_readlane_b32 s55, v238, 43
	s_mov_b64 s[26:27], s[58:59]
	s_waitcnt vmcnt(0)
	s_barrier
	s_add_u32 s98, s98, 0x80
	s_addc_u32 s99, s99, 0
	s_add_u32 s100, s100, 0x80
	s_addc_u32 s101, s101, 0
	ds_read_b128 v[118:121], v239
	ds_read_b128 v[138:141], v241
	ds_read_b128 v[142:145], v241 offset:2048
	ds_read_b128 v[148:151], v241 offset:4096
	ds_read_b128 v[154:157], v241 offset:6144
	ds_read_b128 v[126:129], v239 offset:2048
	ds_read_b128 v[130:133], v239 offset:4096
	ds_read_b128 v[134:137], v239 offset:6144
	s_waitcnt lgkmcnt(6)
	v_mfma_f32_16x16x32_bf16 v[0:3], v[118:121], v[138:141], 0
	ds_read_b128 v[158:161], v240
	s_waitcnt lgkmcnt(6)
	v_mfma_f32_16x16x32_bf16 v[4:7], v[118:121], v[142:145], 0
	ds_read_b128 v[166:169], v242
	s_waitcnt lgkmcnt(6)
	v_mfma_f32_16x16x32_bf16 v[8:11], v[118:121], v[148:151], 0
	ds_read_b128 v[170:173], v242 offset:2048
	s_waitcnt lgkmcnt(6)
	v_mfma_f32_16x16x32_bf16 v[12:15], v[118:121], v[154:157], 0
	ds_read_b128 v[174:177], v242 offset:4096
	s_waitcnt lgkmcnt(6)
	v_mfma_f32_16x16x32_bf16 v[16:19], v[126:129], v[138:141], 0
	ds_read_b128 v[252:255], v242 offset:6144
	v_mfma_f32_16x16x32_bf16 v[20:23], v[126:129], v[142:145], 0
	ds_read_b128 v[162:165], v240 offset:2048
	v_mfma_f32_16x16x32_bf16 v[24:27], v[126:129], v[148:151], 0
	ds_read_b128 v[244:247], v240 offset:4096
	v_mfma_f32_16x16x32_bf16 v[28:31], v[126:129], v[154:157], 0
	ds_read_b128 v[248:251], v240 offset:6144
	s_add_u32 m0, s11, 0x8000
	s_waitcnt lgkmcnt(9)
	v_mfma_f32_16x16x32_bf16 v[32:35], v[130:133], v[138:141], 0
	global_load_lds_dwordx4 v115, s[98:99]
	s_add_u32 m0, s11, 0x9000
	v_mfma_f32_16x16x32_bf16 v[36:39], v[130:133], v[142:145], 0
	global_load_lds_dwordx4 v116, s[98:99]
	s_add_u32 m0, s11, 0xa000
	v_mfma_f32_16x16x32_bf16 v[40:43], v[130:133], v[148:151], 0
	global_load_lds_dwordx4 v122, s[98:99]
	s_add_u32 m0, s11, 0xb000
	v_mfma_f32_16x16x32_bf16 v[44:47], v[130:133], v[154:157], 0
	global_load_lds_dwordx4 v123, s[98:99]
	s_add_u32 m0, s11, 0xc000
	s_waitcnt lgkmcnt(8)
	v_mfma_f32_16x16x32_bf16 v[48:51], v[134:137], v[138:141], 0
	global_load_lds_dwordx4 v115, s[100:101]
	s_add_u32 m0, s11, 0xd000
	v_mfma_f32_16x16x32_bf16 v[52:55], v[134:137], v[142:145], 0
	global_load_lds_dwordx4 v116, s[100:101]
	s_add_u32 m0, s11, 0xe000
	v_mfma_f32_16x16x32_bf16 v[56:59], v[134:137], v[148:151], 0
	global_load_lds_dwordx4 v122, s[100:101]
	s_add_u32 m0, s11, 0xf000
	v_mfma_f32_16x16x32_bf16 v[60:63], v[134:137], v[154:157], 0
	global_load_lds_dwordx4 v123, s[100:101]
	s_waitcnt lgkmcnt(6)
	v_mfma_f32_16x16x32_bf16 v[0:3], v[158:161], v[166:169], v[0:3]
	s_waitcnt lgkmcnt(5)
	v_mfma_f32_16x16x32_bf16 v[4:7], v[158:161], v[170:173], v[4:7]
	s_waitcnt lgkmcnt(4)
	v_mfma_f32_16x16x32_bf16 v[8:11], v[158:161], v[174:177], v[8:11]
	s_waitcnt lgkmcnt(3)
	v_mfma_f32_16x16x32_bf16 v[12:15], v[158:161], v[252:255], v[12:15]
	s_waitcnt lgkmcnt(2)
	v_mfma_f32_16x16x32_bf16 v[16:19], v[162:165], v[166:169], v[16:19]
	v_mfma_f32_16x16x32_bf16 v[20:23], v[162:165], v[170:173], v[20:23]
	v_mfma_f32_16x16x32_bf16 v[24:27], v[162:165], v[174:177], v[24:27]
	v_mfma_f32_16x16x32_bf16 v[28:31], v[162:165], v[252:255], v[28:31]
	s_waitcnt lgkmcnt(1)
	v_mfma_f32_16x16x32_bf16 v[32:35], v[244:247], v[166:169], v[32:35]
	v_mfma_f32_16x16x32_bf16 v[36:39], v[244:247], v[170:173], v[36:39]
	v_mfma_f32_16x16x32_bf16 v[40:43], v[244:247], v[174:177], v[40:43]
	v_mfma_f32_16x16x32_bf16 v[44:47], v[244:247], v[252:255], v[44:47]
	s_waitcnt lgkmcnt(0)
	v_mfma_f32_16x16x32_bf16 v[48:51], v[248:251], v[166:169], v[48:51]
	v_mfma_f32_16x16x32_bf16 v[52:55], v[248:251], v[170:173], v[52:55]
	v_mfma_f32_16x16x32_bf16 v[56:59], v[248:251], v[174:177], v[56:59]
	v_mfma_f32_16x16x32_bf16 v[60:63], v[248:251], v[252:255], v[60:63]
	s_waitcnt vmcnt(0) lgkmcnt(0)
	s_barrier
	s_add_u32 s98, s98, 0x80
	s_addc_u32 s99, s99, 0
	s_add_u32 s100, s100, 0x80
	s_addc_u32 s101, s101, 0
	ds_read_b128 v[118:121], v239 offset:32768
	ds_read_b128 v[138:141], v241 offset:32768
	ds_read_b128 v[142:145], v241 offset:34816
	ds_read_b128 v[148:151], v241 offset:36864
	ds_read_b128 v[154:157], v241 offset:38912
	ds_read_b128 v[126:129], v239 offset:34816
	ds_read_b128 v[130:133], v239 offset:36864
	ds_read_b128 v[134:137], v239 offset:38912
	s_waitcnt lgkmcnt(6)
	v_mfma_f32_16x16x32_bf16 v[0:3], v[118:121], v[138:141], v[0:3]
	ds_read_b128 v[158:161], v240 offset:32768
	s_waitcnt lgkmcnt(6)
	v_mfma_f32_16x16x32_bf16 v[4:7], v[118:121], v[142:145], v[4:7]
	ds_read_b128 v[166:169], v242 offset:32768
	s_waitcnt lgkmcnt(6)
	v_mfma_f32_16x16x32_bf16 v[8:11], v[118:121], v[148:151], v[8:11]
	ds_read_b128 v[170:173], v242 offset:34816
	s_waitcnt lgkmcnt(6)
	v_mfma_f32_16x16x32_bf16 v[12:15], v[118:121], v[154:157], v[12:15]
	ds_read_b128 v[174:177], v242 offset:36864
	s_waitcnt lgkmcnt(6)
	v_mfma_f32_16x16x32_bf16 v[16:19], v[126:129], v[138:141], v[16:19]
	ds_read_b128 v[252:255], v242 offset:38912
	v_mfma_f32_16x16x32_bf16 v[20:23], v[126:129], v[142:145], v[20:23]
	ds_read_b128 v[162:165], v240 offset:34816
	v_mfma_f32_16x16x32_bf16 v[24:27], v[126:129], v[148:151], v[24:27]
	ds_read_b128 v[244:247], v240 offset:36864
	v_mfma_f32_16x16x32_bf16 v[28:31], v[126:129], v[154:157], v[28:31]
	ds_read_b128 v[248:251], v240 offset:38912
	s_add_u32 m0, s11, 0x0
	s_waitcnt lgkmcnt(9)
	v_mfma_f32_16x16x32_bf16 v[32:35], v[130:133], v[138:141], v[32:35]
	global_load_lds_dwordx4 v115, s[98:99]
	s_add_u32 m0, s11, 0x1000
	v_mfma_f32_16x16x32_bf16 v[36:39], v[130:133], v[142:145], v[36:39]
	global_load_lds_dwordx4 v116, s[98:99]
	s_add_u32 m0, s11, 0x2000
	v_mfma_f32_16x16x32_bf16 v[40:43], v[130:133], v[148:151], v[40:43]
	global_load_lds_dwordx4 v122, s[98:99]
	s_add_u32 m0, s11, 0x3000
	v_mfma_f32_16x16x32_bf16 v[44:47], v[130:133], v[154:157], v[44:47]
	global_load_lds_dwordx4 v123, s[98:99]
	s_add_u32 m0, s11, 0x4000
	s_waitcnt lgkmcnt(8)
	v_mfma_f32_16x16x32_bf16 v[48:51], v[134:137], v[138:141], v[48:51]
	global_load_lds_dwordx4 v115, s[100:101]
	s_add_u32 m0, s11, 0x5000
	v_mfma_f32_16x16x32_bf16 v[52:55], v[134:137], v[142:145], v[52:55]
	global_load_lds_dwordx4 v116, s[100:101]
	s_add_u32 m0, s11, 0x6000
	v_mfma_f32_16x16x32_bf16 v[56:59], v[134:137], v[148:151], v[56:59]
	global_load_lds_dwordx4 v122, s[100:101]
	s_add_u32 m0, s11, 0x7000
	v_mfma_f32_16x16x32_bf16 v[60:63], v[134:137], v[154:157], v[60:63]
	global_load_lds_dwordx4 v123, s[100:101]
	s_waitcnt lgkmcnt(6)
	v_mfma_f32_16x16x32_bf16 v[0:3], v[158:161], v[166:169], v[0:3]
	s_waitcnt lgkmcnt(5)
	v_mfma_f32_16x16x32_bf16 v[4:7], v[158:161], v[170:173], v[4:7]
	s_waitcnt lgkmcnt(4)
	v_mfma_f32_16x16x32_bf16 v[8:11], v[158:161], v[174:177], v[8:11]
	s_waitcnt lgkmcnt(3)
	v_mfma_f32_16x16x32_bf16 v[12:15], v[158:161], v[252:255], v[12:15]
	s_waitcnt lgkmcnt(2)
	v_mfma_f32_16x16x32_bf16 v[16:19], v[162:165], v[166:169], v[16:19]
	v_mfma_f32_16x16x32_bf16 v[20:23], v[162:165], v[170:173], v[20:23]
	v_mfma_f32_16x16x32_bf16 v[24:27], v[162:165], v[174:177], v[24:27]
	v_mfma_f32_16x16x32_bf16 v[28:31], v[162:165], v[252:255], v[28:31]
	s_waitcnt lgkmcnt(1)
	v_mfma_f32_16x16x32_bf16 v[32:35], v[244:247], v[166:169], v[32:35]
	v_mfma_f32_16x16x32_bf16 v[36:39], v[244:247], v[170:173], v[36:39]
	v_mfma_f32_16x16x32_bf16 v[40:43], v[244:247], v[174:177], v[40:43]
	v_mfma_f32_16x16x32_bf16 v[44:47], v[244:247], v[252:255], v[44:47]
	s_waitcnt lgkmcnt(0)
	v_mfma_f32_16x16x32_bf16 v[48:51], v[248:251], v[166:169], v[48:51]
	v_mfma_f32_16x16x32_bf16 v[52:55], v[248:251], v[170:173], v[52:55]
	v_mfma_f32_16x16x32_bf16 v[56:59], v[248:251], v[174:177], v[56:59]
	v_mfma_f32_16x16x32_bf16 v[60:63], v[248:251], v[252:255], v[60:63]
	s_waitcnt vmcnt(0) lgkmcnt(0)
	s_barrier
	s_add_u32 s98, s98, 0x80
	s_addc_u32 s99, s99, 0
	s_add_u32 s100, s100, 0x80
	s_addc_u32 s101, s101, 0
	ds_read_b128 v[118:121], v239
	ds_read_b128 v[138:141], v241
	ds_read_b128 v[142:145], v241 offset:2048
	ds_read_b128 v[148:151], v241 offset:4096
	ds_read_b128 v[154:157], v241 offset:6144
	ds_read_b128 v[126:129], v239 offset:2048
	ds_read_b128 v[130:133], v239 offset:4096
	ds_read_b128 v[134:137], v239 offset:6144
	s_waitcnt lgkmcnt(6)
	v_mfma_f32_16x16x32_bf16 v[0:3], v[118:121], v[138:141], v[0:3]
	ds_read_b128 v[158:161], v240
	s_waitcnt lgkmcnt(6)
	v_mfma_f32_16x16x32_bf16 v[4:7], v[118:121], v[142:145], v[4:7]
	ds_read_b128 v[166:169], v242
	s_waitcnt lgkmcnt(6)
	v_mfma_f32_16x16x32_bf16 v[8:11], v[118:121], v[148:151], v[8:11]
	ds_read_b128 v[170:173], v242 offset:2048
	s_waitcnt lgkmcnt(6)
	v_mfma_f32_16x16x32_bf16 v[12:15], v[118:121], v[154:157], v[12:15]
	ds_read_b128 v[174:177], v242 offset:4096
	s_waitcnt lgkmcnt(6)
	v_mfma_f32_16x16x32_bf16 v[16:19], v[126:129], v[138:141], v[16:19]
	ds_read_b128 v[252:255], v242 offset:6144
	v_mfma_f32_16x16x32_bf16 v[20:23], v[126:129], v[142:145], v[20:23]
	ds_read_b128 v[162:165], v240 offset:2048
	v_mfma_f32_16x16x32_bf16 v[24:27], v[126:129], v[148:151], v[24:27]
	ds_read_b128 v[244:247], v240 offset:4096
	v_mfma_f32_16x16x32_bf16 v[28:31], v[126:129], v[154:157], v[28:31]
	ds_read_b128 v[248:251], v240 offset:6144
	s_add_u32 m0, s11, 0x8000
	s_waitcnt lgkmcnt(9)
	v_mfma_f32_16x16x32_bf16 v[32:35], v[130:133], v[138:141], v[32:35]
	global_load_lds_dwordx4 v115, s[98:99]
	s_add_u32 m0, s11, 0x9000
	v_mfma_f32_16x16x32_bf16 v[36:39], v[130:133], v[142:145], v[36:39]
	global_load_lds_dwordx4 v116, s[98:99]
	s_add_u32 m0, s11, 0xa000
	v_mfma_f32_16x16x32_bf16 v[40:43], v[130:133], v[148:151], v[40:43]
	global_load_lds_dwordx4 v122, s[98:99]
	s_add_u32 m0, s11, 0xb000
	v_mfma_f32_16x16x32_bf16 v[44:47], v[130:133], v[154:157], v[44:47]
	global_load_lds_dwordx4 v123, s[98:99]
	s_add_u32 m0, s11, 0xc000
	s_waitcnt lgkmcnt(8)
	v_mfma_f32_16x16x32_bf16 v[48:51], v[134:137], v[138:141], v[48:51]
	global_load_lds_dwordx4 v115, s[100:101]
	s_add_u32 m0, s11, 0xd000
	v_mfma_f32_16x16x32_bf16 v[52:55], v[134:137], v[142:145], v[52:55]
	global_load_lds_dwordx4 v116, s[100:101]
	s_add_u32 m0, s11, 0xe000
	v_mfma_f32_16x16x32_bf16 v[56:59], v[134:137], v[148:151], v[56:59]
	global_load_lds_dwordx4 v122, s[100:101]
	s_add_u32 m0, s11, 0xf000
	v_mfma_f32_16x16x32_bf16 v[60:63], v[134:137], v[154:157], v[60:63]
	global_load_lds_dwordx4 v123, s[100:101]
	s_waitcnt lgkmcnt(6)
	v_mfma_f32_16x16x32_bf16 v[0:3], v[158:161], v[166:169], v[0:3]
	s_waitcnt lgkmcnt(5)
	v_mfma_f32_16x16x32_bf16 v[4:7], v[158:161], v[170:173], v[4:7]
	s_waitcnt lgkmcnt(4)
	v_mfma_f32_16x16x32_bf16 v[8:11], v[158:161], v[174:177], v[8:11]
	s_waitcnt lgkmcnt(3)
	v_mfma_f32_16x16x32_bf16 v[12:15], v[158:161], v[252:255], v[12:15]
	s_waitcnt lgkmcnt(2)
	v_mfma_f32_16x16x32_bf16 v[16:19], v[162:165], v[166:169], v[16:19]
	v_mfma_f32_16x16x32_bf16 v[20:23], v[162:165], v[170:173], v[20:23]
	v_mfma_f32_16x16x32_bf16 v[24:27], v[162:165], v[174:177], v[24:27]
	v_mfma_f32_16x16x32_bf16 v[28:31], v[162:165], v[252:255], v[28:31]
	s_waitcnt lgkmcnt(1)
	v_mfma_f32_16x16x32_bf16 v[32:35], v[244:247], v[166:169], v[32:35]
	v_mfma_f32_16x16x32_bf16 v[36:39], v[244:247], v[170:173], v[36:39]
	v_mfma_f32_16x16x32_bf16 v[40:43], v[244:247], v[174:177], v[40:43]
	v_mfma_f32_16x16x32_bf16 v[44:47], v[244:247], v[252:255], v[44:47]
	s_waitcnt lgkmcnt(0)
	v_mfma_f32_16x16x32_bf16 v[48:51], v[248:251], v[166:169], v[48:51]
	v_mfma_f32_16x16x32_bf16 v[52:55], v[248:251], v[170:173], v[52:55]
	v_mfma_f32_16x16x32_bf16 v[56:59], v[248:251], v[174:177], v[56:59]
	v_mfma_f32_16x16x32_bf16 v[60:63], v[248:251], v[252:255], v[60:63]
	s_waitcnt vmcnt(0) lgkmcnt(0)
	s_barrier
	s_add_u32 s98, s98, 0x80
	s_addc_u32 s99, s99, 0
	s_add_u32 s100, s100, 0x80
	s_addc_u32 s101, s101, 0
	ds_read_b128 v[118:121], v239 offset:32768
	ds_read_b128 v[138:141], v241 offset:32768
	ds_read_b128 v[142:145], v241 offset:34816
	ds_read_b128 v[148:151], v241 offset:36864
	ds_read_b128 v[154:157], v241 offset:38912
	ds_read_b128 v[126:129], v239 offset:34816
	ds_read_b128 v[130:133], v239 offset:36864
	ds_read_b128 v[134:137], v239 offset:38912
	s_waitcnt lgkmcnt(6)
	v_mfma_f32_16x16x32_bf16 v[0:3], v[118:121], v[138:141], v[0:3]
	ds_read_b128 v[158:161], v240 offset:32768
	s_waitcnt lgkmcnt(6)
	v_mfma_f32_16x16x32_bf16 v[4:7], v[118:121], v[142:145], v[4:7]
	ds_read_b128 v[166:169], v242 offset:32768
	s_waitcnt lgkmcnt(6)
	v_mfma_f32_16x16x32_bf16 v[8:11], v[118:121], v[148:151], v[8:11]
	ds_read_b128 v[170:173], v242 offset:34816
	s_waitcnt lgkmcnt(6)
	v_mfma_f32_16x16x32_bf16 v[12:15], v[118:121], v[154:157], v[12:15]
	ds_read_b128 v[174:177], v242 offset:36864
	s_waitcnt lgkmcnt(6)
	v_mfma_f32_16x16x32_bf16 v[16:19], v[126:129], v[138:141], v[16:19]
	ds_read_b128 v[252:255], v242 offset:38912
	v_mfma_f32_16x16x32_bf16 v[20:23], v[126:129], v[142:145], v[20:23]
	ds_read_b128 v[162:165], v240 offset:34816
	v_mfma_f32_16x16x32_bf16 v[24:27], v[126:129], v[148:151], v[24:27]
	ds_read_b128 v[244:247], v240 offset:36864
	v_mfma_f32_16x16x32_bf16 v[28:31], v[126:129], v[154:157], v[28:31]
	ds_read_b128 v[248:251], v240 offset:38912
	s_add_u32 m0, s11, 0x0
	s_waitcnt lgkmcnt(9)
	v_mfma_f32_16x16x32_bf16 v[32:35], v[130:133], v[138:141], v[32:35]
	global_load_lds_dwordx4 v115, s[98:99]
	s_add_u32 m0, s11, 0x1000
	v_mfma_f32_16x16x32_bf16 v[36:39], v[130:133], v[142:145], v[36:39]
	global_load_lds_dwordx4 v116, s[98:99]
	s_add_u32 m0, s11, 0x2000
	v_mfma_f32_16x16x32_bf16 v[40:43], v[130:133], v[148:151], v[40:43]
	global_load_lds_dwordx4 v122, s[98:99]
	s_add_u32 m0, s11, 0x3000
	v_mfma_f32_16x16x32_bf16 v[44:47], v[130:133], v[154:157], v[44:47]
	global_load_lds_dwordx4 v123, s[98:99]
	s_add_u32 m0, s11, 0x4000
	s_waitcnt lgkmcnt(8)
	v_mfma_f32_16x16x32_bf16 v[48:51], v[134:137], v[138:141], v[48:51]
	global_load_lds_dwordx4 v115, s[100:101]
	s_add_u32 m0, s11, 0x5000
	v_mfma_f32_16x16x32_bf16 v[52:55], v[134:137], v[142:145], v[52:55]
	global_load_lds_dwordx4 v116, s[100:101]
	s_add_u32 m0, s11, 0x6000
	v_mfma_f32_16x16x32_bf16 v[56:59], v[134:137], v[148:151], v[56:59]
	global_load_lds_dwordx4 v122, s[100:101]
	s_add_u32 m0, s11, 0x7000
	v_mfma_f32_16x16x32_bf16 v[60:63], v[134:137], v[154:157], v[60:63]
	global_load_lds_dwordx4 v123, s[100:101]
	s_waitcnt lgkmcnt(6)
	v_mfma_f32_16x16x32_bf16 v[0:3], v[158:161], v[166:169], v[0:3]
	s_waitcnt lgkmcnt(5)
	v_mfma_f32_16x16x32_bf16 v[4:7], v[158:161], v[170:173], v[4:7]
	s_waitcnt lgkmcnt(4)
	v_mfma_f32_16x16x32_bf16 v[8:11], v[158:161], v[174:177], v[8:11]
	s_waitcnt lgkmcnt(3)
	v_mfma_f32_16x16x32_bf16 v[12:15], v[158:161], v[252:255], v[12:15]
	s_waitcnt lgkmcnt(2)
	v_mfma_f32_16x16x32_bf16 v[16:19], v[162:165], v[166:169], v[16:19]
	v_mfma_f32_16x16x32_bf16 v[20:23], v[162:165], v[170:173], v[20:23]
	v_mfma_f32_16x16x32_bf16 v[24:27], v[162:165], v[174:177], v[24:27]
	v_mfma_f32_16x16x32_bf16 v[28:31], v[162:165], v[252:255], v[28:31]
	s_waitcnt lgkmcnt(1)
	v_mfma_f32_16x16x32_bf16 v[32:35], v[244:247], v[166:169], v[32:35]
	v_mfma_f32_16x16x32_bf16 v[36:39], v[244:247], v[170:173], v[36:39]
	v_mfma_f32_16x16x32_bf16 v[40:43], v[244:247], v[174:177], v[40:43]
	v_mfma_f32_16x16x32_bf16 v[44:47], v[244:247], v[252:255], v[44:47]
	s_waitcnt lgkmcnt(0)
	v_mfma_f32_16x16x32_bf16 v[48:51], v[248:251], v[166:169], v[48:51]
	v_mfma_f32_16x16x32_bf16 v[52:55], v[248:251], v[170:173], v[52:55]
	v_mfma_f32_16x16x32_bf16 v[56:59], v[248:251], v[174:177], v[56:59]
	v_mfma_f32_16x16x32_bf16 v[60:63], v[248:251], v[252:255], v[60:63]
	s_waitcnt vmcnt(0) lgkmcnt(0)
	s_barrier
	s_add_u32 s98, s98, 0x80
	s_addc_u32 s99, s99, 0
	s_add_u32 s100, s100, 0x80
	s_addc_u32 s101, s101, 0
	ds_read_b128 v[118:121], v239
	ds_read_b128 v[138:141], v241
	ds_read_b128 v[142:145], v241 offset:2048
	ds_read_b128 v[148:151], v241 offset:4096
	ds_read_b128 v[154:157], v241 offset:6144
	ds_read_b128 v[126:129], v239 offset:2048
	ds_read_b128 v[130:133], v239 offset:4096
	ds_read_b128 v[134:137], v239 offset:6144
	s_waitcnt lgkmcnt(6)
	v_mfma_f32_16x16x32_bf16 v[0:3], v[118:121], v[138:141], v[0:3]
	ds_read_b128 v[158:161], v240
	s_waitcnt lgkmcnt(6)
	v_mfma_f32_16x16x32_bf16 v[4:7], v[118:121], v[142:145], v[4:7]
	ds_read_b128 v[166:169], v242
	s_waitcnt lgkmcnt(6)
	v_mfma_f32_16x16x32_bf16 v[8:11], v[118:121], v[148:151], v[8:11]
	ds_read_b128 v[170:173], v242 offset:2048
	s_waitcnt lgkmcnt(6)
	v_mfma_f32_16x16x32_bf16 v[12:15], v[118:121], v[154:157], v[12:15]
	ds_read_b128 v[174:177], v242 offset:4096
	s_waitcnt lgkmcnt(6)
	v_mfma_f32_16x16x32_bf16 v[16:19], v[126:129], v[138:141], v[16:19]
	ds_read_b128 v[252:255], v242 offset:6144
	v_mfma_f32_16x16x32_bf16 v[20:23], v[126:129], v[142:145], v[20:23]
	ds_read_b128 v[162:165], v240 offset:2048
	v_mfma_f32_16x16x32_bf16 v[24:27], v[126:129], v[148:151], v[24:27]
	ds_read_b128 v[244:247], v240 offset:4096
	v_mfma_f32_16x16x32_bf16 v[28:31], v[126:129], v[154:157], v[28:31]
	ds_read_b128 v[248:251], v240 offset:6144
	s_add_u32 m0, s11, 0x8000
	s_waitcnt lgkmcnt(9)
	v_mfma_f32_16x16x32_bf16 v[32:35], v[130:133], v[138:141], v[32:35]
	global_load_lds_dwordx4 v115, s[98:99]
	s_add_u32 m0, s11, 0x9000
	v_mfma_f32_16x16x32_bf16 v[36:39], v[130:133], v[142:145], v[36:39]
	global_load_lds_dwordx4 v116, s[98:99]
	s_add_u32 m0, s11, 0xa000
	v_mfma_f32_16x16x32_bf16 v[40:43], v[130:133], v[148:151], v[40:43]
	global_load_lds_dwordx4 v122, s[98:99]
	s_add_u32 m0, s11, 0xb000
	v_mfma_f32_16x16x32_bf16 v[44:47], v[130:133], v[154:157], v[44:47]
	global_load_lds_dwordx4 v123, s[98:99]
	s_add_u32 m0, s11, 0xc000
	s_waitcnt lgkmcnt(8)
	v_mfma_f32_16x16x32_bf16 v[48:51], v[134:137], v[138:141], v[48:51]
	global_load_lds_dwordx4 v115, s[100:101]
	s_add_u32 m0, s11, 0xd000
	v_mfma_f32_16x16x32_bf16 v[52:55], v[134:137], v[142:145], v[52:55]
	global_load_lds_dwordx4 v116, s[100:101]
	s_add_u32 m0, s11, 0xe000
	v_mfma_f32_16x16x32_bf16 v[56:59], v[134:137], v[148:151], v[56:59]
	global_load_lds_dwordx4 v122, s[100:101]
	s_add_u32 m0, s11, 0xf000
	v_mfma_f32_16x16x32_bf16 v[60:63], v[134:137], v[154:157], v[60:63]
	global_load_lds_dwordx4 v123, s[100:101]
	s_waitcnt lgkmcnt(6)
	v_mfma_f32_16x16x32_bf16 v[0:3], v[158:161], v[166:169], v[0:3]
	s_waitcnt lgkmcnt(5)
	v_mfma_f32_16x16x32_bf16 v[4:7], v[158:161], v[170:173], v[4:7]
	s_waitcnt lgkmcnt(4)
	v_mfma_f32_16x16x32_bf16 v[8:11], v[158:161], v[174:177], v[8:11]
	s_waitcnt lgkmcnt(3)
	v_mfma_f32_16x16x32_bf16 v[12:15], v[158:161], v[252:255], v[12:15]
	s_waitcnt lgkmcnt(2)
	v_mfma_f32_16x16x32_bf16 v[16:19], v[162:165], v[166:169], v[16:19]
	v_mfma_f32_16x16x32_bf16 v[20:23], v[162:165], v[170:173], v[20:23]
	v_mfma_f32_16x16x32_bf16 v[24:27], v[162:165], v[174:177], v[24:27]
	v_mfma_f32_16x16x32_bf16 v[28:31], v[162:165], v[252:255], v[28:31]
	s_waitcnt lgkmcnt(1)
	v_mfma_f32_16x16x32_bf16 v[32:35], v[244:247], v[166:169], v[32:35]
	v_mfma_f32_16x16x32_bf16 v[36:39], v[244:247], v[170:173], v[36:39]
	v_mfma_f32_16x16x32_bf16 v[40:43], v[244:247], v[174:177], v[40:43]
	v_mfma_f32_16x16x32_bf16 v[44:47], v[244:247], v[252:255], v[44:47]
	s_waitcnt lgkmcnt(0)
	v_mfma_f32_16x16x32_bf16 v[48:51], v[248:251], v[166:169], v[48:51]
	v_mfma_f32_16x16x32_bf16 v[52:55], v[248:251], v[170:173], v[52:55]
	v_mfma_f32_16x16x32_bf16 v[56:59], v[248:251], v[174:177], v[56:59]
	v_mfma_f32_16x16x32_bf16 v[60:63], v[248:251], v[252:255], v[60:63]
	s_waitcnt vmcnt(0) lgkmcnt(0)
	s_barrier
	s_add_u32 s98, s98, 0x80
	s_addc_u32 s99, s99, 0
	s_add_u32 s100, s100, 0x80
	s_addc_u32 s101, s101, 0
	ds_read_b128 v[118:121], v239 offset:32768
	ds_read_b128 v[138:141], v241 offset:32768
	ds_read_b128 v[142:145], v241 offset:34816
	ds_read_b128 v[148:151], v241 offset:36864
	ds_read_b128 v[154:157], v241 offset:38912
	ds_read_b128 v[126:129], v239 offset:34816
	ds_read_b128 v[130:133], v239 offset:36864
	ds_read_b128 v[134:137], v239 offset:38912
	s_waitcnt lgkmcnt(6)
	v_mfma_f32_16x16x32_bf16 v[0:3], v[118:121], v[138:141], v[0:3]
	ds_read_b128 v[158:161], v240 offset:32768
	s_waitcnt lgkmcnt(6)
	v_mfma_f32_16x16x32_bf16 v[4:7], v[118:121], v[142:145], v[4:7]
	ds_read_b128 v[166:169], v242 offset:32768
	s_waitcnt lgkmcnt(6)
	v_mfma_f32_16x16x32_bf16 v[8:11], v[118:121], v[148:151], v[8:11]
	ds_read_b128 v[170:173], v242 offset:34816
	s_waitcnt lgkmcnt(6)
	v_mfma_f32_16x16x32_bf16 v[12:15], v[118:121], v[154:157], v[12:15]
	ds_read_b128 v[174:177], v242 offset:36864
	s_waitcnt lgkmcnt(6)
	v_mfma_f32_16x16x32_bf16 v[16:19], v[126:129], v[138:141], v[16:19]
	ds_read_b128 v[252:255], v242 offset:38912
	v_mfma_f32_16x16x32_bf16 v[20:23], v[126:129], v[142:145], v[20:23]
	ds_read_b128 v[162:165], v240 offset:34816
	v_mfma_f32_16x16x32_bf16 v[24:27], v[126:129], v[148:151], v[24:27]
	ds_read_b128 v[244:247], v240 offset:36864
	v_mfma_f32_16x16x32_bf16 v[28:31], v[126:129], v[154:157], v[28:31]
	ds_read_b128 v[248:251], v240 offset:38912
	s_add_u32 m0, s11, 0x0
	s_waitcnt lgkmcnt(9)
	v_mfma_f32_16x16x32_bf16 v[32:35], v[130:133], v[138:141], v[32:35]
	global_load_lds_dwordx4 v115, s[98:99]
	s_add_u32 m0, s11, 0x1000
	v_mfma_f32_16x16x32_bf16 v[36:39], v[130:133], v[142:145], v[36:39]
	global_load_lds_dwordx4 v116, s[98:99]
	s_add_u32 m0, s11, 0x2000
	v_mfma_f32_16x16x32_bf16 v[40:43], v[130:133], v[148:151], v[40:43]
	global_load_lds_dwordx4 v122, s[98:99]
	s_add_u32 m0, s11, 0x3000
	v_mfma_f32_16x16x32_bf16 v[44:47], v[130:133], v[154:157], v[44:47]
	global_load_lds_dwordx4 v123, s[98:99]
	s_add_u32 m0, s11, 0x4000
	s_waitcnt lgkmcnt(8)
	v_mfma_f32_16x16x32_bf16 v[48:51], v[134:137], v[138:141], v[48:51]
	global_load_lds_dwordx4 v115, s[100:101]
	s_add_u32 m0, s11, 0x5000
	v_mfma_f32_16x16x32_bf16 v[52:55], v[134:137], v[142:145], v[52:55]
	global_load_lds_dwordx4 v116, s[100:101]
	s_add_u32 m0, s11, 0x6000
	v_mfma_f32_16x16x32_bf16 v[56:59], v[134:137], v[148:151], v[56:59]
	global_load_lds_dwordx4 v122, s[100:101]
	s_add_u32 m0, s11, 0x7000
	v_mfma_f32_16x16x32_bf16 v[60:63], v[134:137], v[154:157], v[60:63]
	global_load_lds_dwordx4 v123, s[100:101]
	s_waitcnt lgkmcnt(6)
	v_mfma_f32_16x16x32_bf16 v[0:3], v[158:161], v[166:169], v[0:3]
	s_waitcnt lgkmcnt(5)
	v_mfma_f32_16x16x32_bf16 v[4:7], v[158:161], v[170:173], v[4:7]
	s_waitcnt lgkmcnt(4)
	v_mfma_f32_16x16x32_bf16 v[8:11], v[158:161], v[174:177], v[8:11]
	s_waitcnt lgkmcnt(3)
	v_mfma_f32_16x16x32_bf16 v[12:15], v[158:161], v[252:255], v[12:15]
	s_waitcnt lgkmcnt(2)
	v_mfma_f32_16x16x32_bf16 v[16:19], v[162:165], v[166:169], v[16:19]
	v_mfma_f32_16x16x32_bf16 v[20:23], v[162:165], v[170:173], v[20:23]
	v_mfma_f32_16x16x32_bf16 v[24:27], v[162:165], v[174:177], v[24:27]
	v_mfma_f32_16x16x32_bf16 v[28:31], v[162:165], v[252:255], v[28:31]
	s_waitcnt lgkmcnt(1)
	v_mfma_f32_16x16x32_bf16 v[32:35], v[244:247], v[166:169], v[32:35]
	v_mfma_f32_16x16x32_bf16 v[36:39], v[244:247], v[170:173], v[36:39]
	v_mfma_f32_16x16x32_bf16 v[40:43], v[244:247], v[174:177], v[40:43]
	v_mfma_f32_16x16x32_bf16 v[44:47], v[244:247], v[252:255], v[44:47]
	s_waitcnt lgkmcnt(0)
	v_mfma_f32_16x16x32_bf16 v[48:51], v[248:251], v[166:169], v[48:51]
	v_mfma_f32_16x16x32_bf16 v[52:55], v[248:251], v[170:173], v[52:55]
	v_mfma_f32_16x16x32_bf16 v[56:59], v[248:251], v[174:177], v[56:59]
	v_mfma_f32_16x16x32_bf16 v[60:63], v[248:251], v[252:255], v[60:63]
	s_waitcnt vmcnt(0) lgkmcnt(0)
	s_barrier
	s_add_u32 s98, s98, 0x80
	s_addc_u32 s99, s99, 0
	s_add_u32 s100, s100, 0x80
	s_addc_u32 s101, s101, 0
	ds_read_b128 v[118:121], v239
	ds_read_b128 v[138:141], v241
	ds_read_b128 v[142:145], v241 offset:2048
	ds_read_b128 v[148:151], v241 offset:4096
	ds_read_b128 v[154:157], v241 offset:6144
	ds_read_b128 v[126:129], v239 offset:2048
	ds_read_b128 v[130:133], v239 offset:4096
	ds_read_b128 v[134:137], v239 offset:6144
	s_waitcnt lgkmcnt(6)
	v_mfma_f32_16x16x32_bf16 v[0:3], v[118:121], v[138:141], v[0:3]
	ds_read_b128 v[158:161], v240
	s_waitcnt lgkmcnt(6)
	v_mfma_f32_16x16x32_bf16 v[4:7], v[118:121], v[142:145], v[4:7]
	ds_read_b128 v[166:169], v242
	s_waitcnt lgkmcnt(6)
	v_mfma_f32_16x16x32_bf16 v[8:11], v[118:121], v[148:151], v[8:11]
	ds_read_b128 v[170:173], v242 offset:2048
	s_waitcnt lgkmcnt(6)
	v_mfma_f32_16x16x32_bf16 v[12:15], v[118:121], v[154:157], v[12:15]
	ds_read_b128 v[174:177], v242 offset:4096
	s_waitcnt lgkmcnt(6)
	v_mfma_f32_16x16x32_bf16 v[16:19], v[126:129], v[138:141], v[16:19]
	ds_read_b128 v[252:255], v242 offset:6144
	v_mfma_f32_16x16x32_bf16 v[20:23], v[126:129], v[142:145], v[20:23]
	ds_read_b128 v[162:165], v240 offset:2048
	v_mfma_f32_16x16x32_bf16 v[24:27], v[126:129], v[148:151], v[24:27]
	ds_read_b128 v[244:247], v240 offset:4096
	v_mfma_f32_16x16x32_bf16 v[28:31], v[126:129], v[154:157], v[28:31]
	ds_read_b128 v[248:251], v240 offset:6144
	s_add_u32 m0, s11, 0x8000
	s_waitcnt lgkmcnt(9)
	v_mfma_f32_16x16x32_bf16 v[32:35], v[130:133], v[138:141], v[32:35]
	global_load_lds_dwordx4 v115, s[98:99]
	s_add_u32 m0, s11, 0x9000
	v_mfma_f32_16x16x32_bf16 v[36:39], v[130:133], v[142:145], v[36:39]
	global_load_lds_dwordx4 v116, s[98:99]
	s_add_u32 m0, s11, 0xa000
	v_mfma_f32_16x16x32_bf16 v[40:43], v[130:133], v[148:151], v[40:43]
	global_load_lds_dwordx4 v122, s[98:99]
	s_add_u32 m0, s11, 0xb000
	v_mfma_f32_16x16x32_bf16 v[44:47], v[130:133], v[154:157], v[44:47]
	global_load_lds_dwordx4 v123, s[98:99]
	s_add_u32 m0, s11, 0xc000
	s_waitcnt lgkmcnt(8)
	v_mfma_f32_16x16x32_bf16 v[48:51], v[134:137], v[138:141], v[48:51]
	global_load_lds_dwordx4 v115, s[100:101]
	s_add_u32 m0, s11, 0xd000
	v_mfma_f32_16x16x32_bf16 v[52:55], v[134:137], v[142:145], v[52:55]
	global_load_lds_dwordx4 v116, s[100:101]
	s_add_u32 m0, s11, 0xe000
	v_mfma_f32_16x16x32_bf16 v[56:59], v[134:137], v[148:151], v[56:59]
	global_load_lds_dwordx4 v122, s[100:101]
	s_add_u32 m0, s11, 0xf000
	v_mfma_f32_16x16x32_bf16 v[60:63], v[134:137], v[154:157], v[60:63]
	global_load_lds_dwordx4 v123, s[100:101]
	s_waitcnt lgkmcnt(6)
	v_mfma_f32_16x16x32_bf16 v[0:3], v[158:161], v[166:169], v[0:3]
	s_waitcnt lgkmcnt(5)
	v_mfma_f32_16x16x32_bf16 v[4:7], v[158:161], v[170:173], v[4:7]
	s_waitcnt lgkmcnt(4)
	v_mfma_f32_16x16x32_bf16 v[8:11], v[158:161], v[174:177], v[8:11]
	s_waitcnt lgkmcnt(3)
	v_mfma_f32_16x16x32_bf16 v[12:15], v[158:161], v[252:255], v[12:15]
	s_waitcnt lgkmcnt(2)
	v_mfma_f32_16x16x32_bf16 v[16:19], v[162:165], v[166:169], v[16:19]
	v_mfma_f32_16x16x32_bf16 v[20:23], v[162:165], v[170:173], v[20:23]
	v_mfma_f32_16x16x32_bf16 v[24:27], v[162:165], v[174:177], v[24:27]
	v_mfma_f32_16x16x32_bf16 v[28:31], v[162:165], v[252:255], v[28:31]
	s_waitcnt lgkmcnt(1)
	v_mfma_f32_16x16x32_bf16 v[32:35], v[244:247], v[166:169], v[32:35]
	v_mfma_f32_16x16x32_bf16 v[36:39], v[244:247], v[170:173], v[36:39]
	v_mfma_f32_16x16x32_bf16 v[40:43], v[244:247], v[174:177], v[40:43]
	v_mfma_f32_16x16x32_bf16 v[44:47], v[244:247], v[252:255], v[44:47]
	s_waitcnt lgkmcnt(0)
	v_mfma_f32_16x16x32_bf16 v[48:51], v[248:251], v[166:169], v[48:51]
	v_mfma_f32_16x16x32_bf16 v[52:55], v[248:251], v[170:173], v[52:55]
	v_mfma_f32_16x16x32_bf16 v[56:59], v[248:251], v[174:177], v[56:59]
	v_mfma_f32_16x16x32_bf16 v[60:63], v[248:251], v[252:255], v[60:63]
	s_waitcnt vmcnt(0) lgkmcnt(0)
	s_barrier
	s_add_u32 s98, s98, 0x80
	s_addc_u32 s99, s99, 0
	s_add_u32 s100, s100, 0x80
	s_addc_u32 s101, s101, 0
	ds_read_b128 v[118:121], v239 offset:32768
	ds_read_b128 v[138:141], v241 offset:32768
	ds_read_b128 v[142:145], v241 offset:34816
	ds_read_b128 v[148:151], v241 offset:36864
	ds_read_b128 v[154:157], v241 offset:38912
	ds_read_b128 v[126:129], v239 offset:34816
	ds_read_b128 v[130:133], v239 offset:36864
	ds_read_b128 v[134:137], v239 offset:38912
	s_waitcnt lgkmcnt(6)
	v_mfma_f32_16x16x32_bf16 v[0:3], v[118:121], v[138:141], v[0:3]
	ds_read_b128 v[158:161], v240 offset:32768
	s_waitcnt lgkmcnt(6)
	v_mfma_f32_16x16x32_bf16 v[4:7], v[118:121], v[142:145], v[4:7]
	ds_read_b128 v[166:169], v242 offset:32768
	s_waitcnt lgkmcnt(6)
	v_mfma_f32_16x16x32_bf16 v[8:11], v[118:121], v[148:151], v[8:11]
	ds_read_b128 v[170:173], v242 offset:34816
	s_waitcnt lgkmcnt(6)
	v_mfma_f32_16x16x32_bf16 v[12:15], v[118:121], v[154:157], v[12:15]
	ds_read_b128 v[174:177], v242 offset:36864
	s_waitcnt lgkmcnt(6)
	v_mfma_f32_16x16x32_bf16 v[16:19], v[126:129], v[138:141], v[16:19]
	ds_read_b128 v[252:255], v242 offset:38912
	v_mfma_f32_16x16x32_bf16 v[20:23], v[126:129], v[142:145], v[20:23]
	ds_read_b128 v[162:165], v240 offset:34816
	v_mfma_f32_16x16x32_bf16 v[24:27], v[126:129], v[148:151], v[24:27]
	ds_read_b128 v[244:247], v240 offset:36864
	v_mfma_f32_16x16x32_bf16 v[28:31], v[126:129], v[154:157], v[28:31]
	ds_read_b128 v[248:251], v240 offset:38912
	s_add_u32 m0, s11, 0x0
	s_waitcnt lgkmcnt(9)
	v_mfma_f32_16x16x32_bf16 v[32:35], v[130:133], v[138:141], v[32:35]
	global_load_lds_dwordx4 v115, s[98:99]
	s_add_u32 m0, s11, 0x1000
	v_mfma_f32_16x16x32_bf16 v[36:39], v[130:133], v[142:145], v[36:39]
	global_load_lds_dwordx4 v116, s[98:99]
	s_add_u32 m0, s11, 0x2000
	v_mfma_f32_16x16x32_bf16 v[40:43], v[130:133], v[148:151], v[40:43]
	global_load_lds_dwordx4 v122, s[98:99]
	s_add_u32 m0, s11, 0x3000
	v_mfma_f32_16x16x32_bf16 v[44:47], v[130:133], v[154:157], v[44:47]
	global_load_lds_dwordx4 v123, s[98:99]
	s_add_u32 m0, s11, 0x4000
	s_waitcnt lgkmcnt(8)
	v_mfma_f32_16x16x32_bf16 v[48:51], v[134:137], v[138:141], v[48:51]
	global_load_lds_dwordx4 v115, s[100:101]
	s_add_u32 m0, s11, 0x5000
	v_mfma_f32_16x16x32_bf16 v[52:55], v[134:137], v[142:145], v[52:55]
	global_load_lds_dwordx4 v116, s[100:101]
	s_add_u32 m0, s11, 0x6000
	v_mfma_f32_16x16x32_bf16 v[56:59], v[134:137], v[148:151], v[56:59]
	global_load_lds_dwordx4 v122, s[100:101]
	s_add_u32 m0, s11, 0x7000
	v_mfma_f32_16x16x32_bf16 v[60:63], v[134:137], v[154:157], v[60:63]
	global_load_lds_dwordx4 v123, s[100:101]
	s_waitcnt lgkmcnt(6)
	v_mfma_f32_16x16x32_bf16 v[0:3], v[158:161], v[166:169], v[0:3]
	s_waitcnt lgkmcnt(5)
	v_mfma_f32_16x16x32_bf16 v[4:7], v[158:161], v[170:173], v[4:7]
	s_waitcnt lgkmcnt(4)
	v_mfma_f32_16x16x32_bf16 v[8:11], v[158:161], v[174:177], v[8:11]
	s_waitcnt lgkmcnt(3)
	v_mfma_f32_16x16x32_bf16 v[12:15], v[158:161], v[252:255], v[12:15]
	s_waitcnt lgkmcnt(2)
	v_mfma_f32_16x16x32_bf16 v[16:19], v[162:165], v[166:169], v[16:19]
	v_mfma_f32_16x16x32_bf16 v[20:23], v[162:165], v[170:173], v[20:23]
	v_mfma_f32_16x16x32_bf16 v[24:27], v[162:165], v[174:177], v[24:27]
	v_mfma_f32_16x16x32_bf16 v[28:31], v[162:165], v[252:255], v[28:31]
	s_waitcnt lgkmcnt(1)
	v_mfma_f32_16x16x32_bf16 v[32:35], v[244:247], v[166:169], v[32:35]
	v_mfma_f32_16x16x32_bf16 v[36:39], v[244:247], v[170:173], v[36:39]
	v_mfma_f32_16x16x32_bf16 v[40:43], v[244:247], v[174:177], v[40:43]
	v_mfma_f32_16x16x32_bf16 v[44:47], v[244:247], v[252:255], v[44:47]
	s_waitcnt lgkmcnt(0)
	v_mfma_f32_16x16x32_bf16 v[48:51], v[248:251], v[166:169], v[48:51]
	v_mfma_f32_16x16x32_bf16 v[52:55], v[248:251], v[170:173], v[52:55]
	v_mfma_f32_16x16x32_bf16 v[56:59], v[248:251], v[174:177], v[56:59]
	v_mfma_f32_16x16x32_bf16 v[60:63], v[248:251], v[252:255], v[60:63]
	s_waitcnt vmcnt(0) lgkmcnt(0)
	s_barrier
	s_add_u32 s98, s98, 0x80
	s_addc_u32 s99, s99, 0
	s_add_u32 s100, s100, 0x80
	s_addc_u32 s101, s101, 0
	ds_read_b128 v[118:121], v239
	ds_read_b128 v[138:141], v241
	ds_read_b128 v[142:145], v241 offset:2048
	ds_read_b128 v[148:151], v241 offset:4096
	ds_read_b128 v[154:157], v241 offset:6144
	ds_read_b128 v[126:129], v239 offset:2048
	ds_read_b128 v[130:133], v239 offset:4096
	ds_read_b128 v[134:137], v239 offset:6144
	s_waitcnt lgkmcnt(6)
	v_mfma_f32_16x16x32_bf16 v[0:3], v[118:121], v[138:141], v[0:3]
	ds_read_b128 v[158:161], v240
	s_waitcnt lgkmcnt(6)
	v_mfma_f32_16x16x32_bf16 v[4:7], v[118:121], v[142:145], v[4:7]
	ds_read_b128 v[166:169], v242
	s_waitcnt lgkmcnt(6)
	v_mfma_f32_16x16x32_bf16 v[8:11], v[118:121], v[148:151], v[8:11]
	ds_read_b128 v[170:173], v242 offset:2048
	s_waitcnt lgkmcnt(6)
	v_mfma_f32_16x16x32_bf16 v[12:15], v[118:121], v[154:157], v[12:15]
	ds_read_b128 v[174:177], v242 offset:4096
	s_waitcnt lgkmcnt(6)
	v_mfma_f32_16x16x32_bf16 v[16:19], v[126:129], v[138:141], v[16:19]
	ds_read_b128 v[252:255], v242 offset:6144
	v_mfma_f32_16x16x32_bf16 v[20:23], v[126:129], v[142:145], v[20:23]
	ds_read_b128 v[162:165], v240 offset:2048
	v_mfma_f32_16x16x32_bf16 v[24:27], v[126:129], v[148:151], v[24:27]
	ds_read_b128 v[244:247], v240 offset:4096
	v_mfma_f32_16x16x32_bf16 v[28:31], v[126:129], v[154:157], v[28:31]
	ds_read_b128 v[248:251], v240 offset:6144
	s_add_u32 m0, s11, 0x8000
	s_waitcnt lgkmcnt(9)
	v_mfma_f32_16x16x32_bf16 v[32:35], v[130:133], v[138:141], v[32:35]
	global_load_lds_dwordx4 v115, s[98:99]
	s_add_u32 m0, s11, 0x9000
	v_mfma_f32_16x16x32_bf16 v[36:39], v[130:133], v[142:145], v[36:39]
	global_load_lds_dwordx4 v116, s[98:99]
	s_add_u32 m0, s11, 0xa000
	v_mfma_f32_16x16x32_bf16 v[40:43], v[130:133], v[148:151], v[40:43]
	global_load_lds_dwordx4 v122, s[98:99]
	s_add_u32 m0, s11, 0xb000
	v_mfma_f32_16x16x32_bf16 v[44:47], v[130:133], v[154:157], v[44:47]
	global_load_lds_dwordx4 v123, s[98:99]
	s_add_u32 m0, s11, 0xc000
	s_waitcnt lgkmcnt(8)
	v_mfma_f32_16x16x32_bf16 v[48:51], v[134:137], v[138:141], v[48:51]
	global_load_lds_dwordx4 v115, s[100:101]
	s_add_u32 m0, s11, 0xd000
	v_mfma_f32_16x16x32_bf16 v[52:55], v[134:137], v[142:145], v[52:55]
	global_load_lds_dwordx4 v116, s[100:101]
	s_add_u32 m0, s11, 0xe000
	v_mfma_f32_16x16x32_bf16 v[56:59], v[134:137], v[148:151], v[56:59]
	global_load_lds_dwordx4 v122, s[100:101]
	s_add_u32 m0, s11, 0xf000
	v_mfma_f32_16x16x32_bf16 v[60:63], v[134:137], v[154:157], v[60:63]
	global_load_lds_dwordx4 v123, s[100:101]
	s_waitcnt lgkmcnt(6)
	v_mfma_f32_16x16x32_bf16 v[0:3], v[158:161], v[166:169], v[0:3]
	s_waitcnt lgkmcnt(5)
	v_mfma_f32_16x16x32_bf16 v[4:7], v[158:161], v[170:173], v[4:7]
	s_waitcnt lgkmcnt(4)
	v_mfma_f32_16x16x32_bf16 v[8:11], v[158:161], v[174:177], v[8:11]
	s_waitcnt lgkmcnt(3)
	v_mfma_f32_16x16x32_bf16 v[12:15], v[158:161], v[252:255], v[12:15]
	s_waitcnt lgkmcnt(2)
	v_mfma_f32_16x16x32_bf16 v[16:19], v[162:165], v[166:169], v[16:19]
	v_mfma_f32_16x16x32_bf16 v[20:23], v[162:165], v[170:173], v[20:23]
	v_mfma_f32_16x16x32_bf16 v[24:27], v[162:165], v[174:177], v[24:27]
	v_mfma_f32_16x16x32_bf16 v[28:31], v[162:165], v[252:255], v[28:31]
	s_waitcnt lgkmcnt(1)
	v_mfma_f32_16x16x32_bf16 v[32:35], v[244:247], v[166:169], v[32:35]
	v_mfma_f32_16x16x32_bf16 v[36:39], v[244:247], v[170:173], v[36:39]
	v_mfma_f32_16x16x32_bf16 v[40:43], v[244:247], v[174:177], v[40:43]
	v_mfma_f32_16x16x32_bf16 v[44:47], v[244:247], v[252:255], v[44:47]
	s_waitcnt lgkmcnt(0)
	v_mfma_f32_16x16x32_bf16 v[48:51], v[248:251], v[166:169], v[48:51]
	v_mfma_f32_16x16x32_bf16 v[52:55], v[248:251], v[170:173], v[52:55]
	v_mfma_f32_16x16x32_bf16 v[56:59], v[248:251], v[174:177], v[56:59]
	v_mfma_f32_16x16x32_bf16 v[60:63], v[248:251], v[252:255], v[60:63]
	s_waitcnt vmcnt(0) lgkmcnt(0)
	s_barrier
	s_add_u32 s98, s98, 0x80
	s_addc_u32 s99, s99, 0
	s_add_u32 s100, s100, 0x80
	s_addc_u32 s101, s101, 0
	ds_read_b128 v[118:121], v239 offset:32768
	ds_read_b128 v[138:141], v241 offset:32768
	ds_read_b128 v[142:145], v241 offset:34816
	ds_read_b128 v[148:151], v241 offset:36864
	ds_read_b128 v[154:157], v241 offset:38912
	ds_read_b128 v[126:129], v239 offset:34816
	ds_read_b128 v[130:133], v239 offset:36864
	ds_read_b128 v[134:137], v239 offset:38912
	s_waitcnt lgkmcnt(6)
	v_mfma_f32_16x16x32_bf16 v[0:3], v[118:121], v[138:141], v[0:3]
	ds_read_b128 v[158:161], v240 offset:32768
	s_waitcnt lgkmcnt(6)
	v_mfma_f32_16x16x32_bf16 v[4:7], v[118:121], v[142:145], v[4:7]
	ds_read_b128 v[166:169], v242 offset:32768
	s_waitcnt lgkmcnt(6)
	v_mfma_f32_16x16x32_bf16 v[8:11], v[118:121], v[148:151], v[8:11]
	ds_read_b128 v[170:173], v242 offset:34816
	s_waitcnt lgkmcnt(6)
	v_mfma_f32_16x16x32_bf16 v[12:15], v[118:121], v[154:157], v[12:15]
	ds_read_b128 v[174:177], v242 offset:36864
	s_waitcnt lgkmcnt(6)
	v_mfma_f32_16x16x32_bf16 v[16:19], v[126:129], v[138:141], v[16:19]
	ds_read_b128 v[252:255], v242 offset:38912
	v_mfma_f32_16x16x32_bf16 v[20:23], v[126:129], v[142:145], v[20:23]
	ds_read_b128 v[162:165], v240 offset:34816
	v_mfma_f32_16x16x32_bf16 v[24:27], v[126:129], v[148:151], v[24:27]
	ds_read_b128 v[244:247], v240 offset:36864
	v_mfma_f32_16x16x32_bf16 v[28:31], v[126:129], v[154:157], v[28:31]
	ds_read_b128 v[248:251], v240 offset:38912
	s_add_u32 m0, s11, 0x0
	s_waitcnt lgkmcnt(9)
	v_mfma_f32_16x16x32_bf16 v[32:35], v[130:133], v[138:141], v[32:35]
	global_load_lds_dwordx4 v115, s[98:99]
	s_add_u32 m0, s11, 0x1000
	v_mfma_f32_16x16x32_bf16 v[36:39], v[130:133], v[142:145], v[36:39]
	global_load_lds_dwordx4 v116, s[98:99]
	s_add_u32 m0, s11, 0x2000
	v_mfma_f32_16x16x32_bf16 v[40:43], v[130:133], v[148:151], v[40:43]
	global_load_lds_dwordx4 v122, s[98:99]
	s_add_u32 m0, s11, 0x3000
	v_mfma_f32_16x16x32_bf16 v[44:47], v[130:133], v[154:157], v[44:47]
	global_load_lds_dwordx4 v123, s[98:99]
	s_add_u32 m0, s11, 0x4000
	s_waitcnt lgkmcnt(8)
	v_mfma_f32_16x16x32_bf16 v[48:51], v[134:137], v[138:141], v[48:51]
	global_load_lds_dwordx4 v115, s[100:101]
	s_add_u32 m0, s11, 0x5000
	v_mfma_f32_16x16x32_bf16 v[52:55], v[134:137], v[142:145], v[52:55]
	global_load_lds_dwordx4 v116, s[100:101]
	s_add_u32 m0, s11, 0x6000
	v_mfma_f32_16x16x32_bf16 v[56:59], v[134:137], v[148:151], v[56:59]
	global_load_lds_dwordx4 v122, s[100:101]
	s_add_u32 m0, s11, 0x7000
	v_mfma_f32_16x16x32_bf16 v[60:63], v[134:137], v[154:157], v[60:63]
	global_load_lds_dwordx4 v123, s[100:101]
	s_waitcnt lgkmcnt(6)
	v_mfma_f32_16x16x32_bf16 v[0:3], v[158:161], v[166:169], v[0:3]
	s_waitcnt lgkmcnt(5)
	v_mfma_f32_16x16x32_bf16 v[4:7], v[158:161], v[170:173], v[4:7]
	s_waitcnt lgkmcnt(4)
	v_mfma_f32_16x16x32_bf16 v[8:11], v[158:161], v[174:177], v[8:11]
	s_waitcnt lgkmcnt(3)
	v_mfma_f32_16x16x32_bf16 v[12:15], v[158:161], v[252:255], v[12:15]
	s_waitcnt lgkmcnt(2)
	v_mfma_f32_16x16x32_bf16 v[16:19], v[162:165], v[166:169], v[16:19]
	v_mfma_f32_16x16x32_bf16 v[20:23], v[162:165], v[170:173], v[20:23]
	v_mfma_f32_16x16x32_bf16 v[24:27], v[162:165], v[174:177], v[24:27]
	v_mfma_f32_16x16x32_bf16 v[28:31], v[162:165], v[252:255], v[28:31]
	s_waitcnt lgkmcnt(1)
	v_mfma_f32_16x16x32_bf16 v[32:35], v[244:247], v[166:169], v[32:35]
	v_mfma_f32_16x16x32_bf16 v[36:39], v[244:247], v[170:173], v[36:39]
	v_mfma_f32_16x16x32_bf16 v[40:43], v[244:247], v[174:177], v[40:43]
	v_mfma_f32_16x16x32_bf16 v[44:47], v[244:247], v[252:255], v[44:47]
	s_waitcnt lgkmcnt(0)
	v_mfma_f32_16x16x32_bf16 v[48:51], v[248:251], v[166:169], v[48:51]
	v_mfma_f32_16x16x32_bf16 v[52:55], v[248:251], v[170:173], v[52:55]
	v_mfma_f32_16x16x32_bf16 v[56:59], v[248:251], v[174:177], v[56:59]
	v_mfma_f32_16x16x32_bf16 v[60:63], v[248:251], v[252:255], v[60:63]
	s_waitcnt vmcnt(0) lgkmcnt(0)
	s_barrier
	s_add_u32 s98, s98, 0x80
	s_addc_u32 s99, s99, 0
	s_add_u32 s100, s100, 0x80
	s_addc_u32 s101, s101, 0
	ds_read_b128 v[118:121], v239
	ds_read_b128 v[138:141], v241
	ds_read_b128 v[142:145], v241 offset:2048
	ds_read_b128 v[148:151], v241 offset:4096
	ds_read_b128 v[154:157], v241 offset:6144
	ds_read_b128 v[126:129], v239 offset:2048
	ds_read_b128 v[130:133], v239 offset:4096
	ds_read_b128 v[134:137], v239 offset:6144
	s_waitcnt lgkmcnt(6)
	v_mfma_f32_16x16x32_bf16 v[0:3], v[118:121], v[138:141], v[0:3]
	ds_read_b128 v[158:161], v240
	s_waitcnt lgkmcnt(6)
	v_mfma_f32_16x16x32_bf16 v[4:7], v[118:121], v[142:145], v[4:7]
	ds_read_b128 v[166:169], v242
	s_waitcnt lgkmcnt(6)
	v_mfma_f32_16x16x32_bf16 v[8:11], v[118:121], v[148:151], v[8:11]
	ds_read_b128 v[170:173], v242 offset:2048
	s_waitcnt lgkmcnt(6)
	v_mfma_f32_16x16x32_bf16 v[12:15], v[118:121], v[154:157], v[12:15]
	ds_read_b128 v[174:177], v242 offset:4096
	s_waitcnt lgkmcnt(6)
	v_mfma_f32_16x16x32_bf16 v[16:19], v[126:129], v[138:141], v[16:19]
	ds_read_b128 v[252:255], v242 offset:6144
	v_mfma_f32_16x16x32_bf16 v[20:23], v[126:129], v[142:145], v[20:23]
	ds_read_b128 v[162:165], v240 offset:2048
	v_mfma_f32_16x16x32_bf16 v[24:27], v[126:129], v[148:151], v[24:27]
	ds_read_b128 v[244:247], v240 offset:4096
	v_mfma_f32_16x16x32_bf16 v[28:31], v[126:129], v[154:157], v[28:31]
	ds_read_b128 v[248:251], v240 offset:6144
	s_add_u32 m0, s11, 0x8000
	s_waitcnt lgkmcnt(9)
	v_mfma_f32_16x16x32_bf16 v[32:35], v[130:133], v[138:141], v[32:35]
	global_load_lds_dwordx4 v115, s[98:99]
	s_add_u32 m0, s11, 0x9000
	v_mfma_f32_16x16x32_bf16 v[36:39], v[130:133], v[142:145], v[36:39]
	global_load_lds_dwordx4 v116, s[98:99]
	s_add_u32 m0, s11, 0xa000
	v_mfma_f32_16x16x32_bf16 v[40:43], v[130:133], v[148:151], v[40:43]
	global_load_lds_dwordx4 v122, s[98:99]
	s_add_u32 m0, s11, 0xb000
	v_mfma_f32_16x16x32_bf16 v[44:47], v[130:133], v[154:157], v[44:47]
	global_load_lds_dwordx4 v123, s[98:99]
	s_add_u32 m0, s11, 0xc000
	s_waitcnt lgkmcnt(8)
	v_mfma_f32_16x16x32_bf16 v[48:51], v[134:137], v[138:141], v[48:51]
	global_load_lds_dwordx4 v115, s[100:101]
	s_add_u32 m0, s11, 0xd000
	v_mfma_f32_16x16x32_bf16 v[52:55], v[134:137], v[142:145], v[52:55]
	global_load_lds_dwordx4 v116, s[100:101]
	s_add_u32 m0, s11, 0xe000
	v_mfma_f32_16x16x32_bf16 v[56:59], v[134:137], v[148:151], v[56:59]
	global_load_lds_dwordx4 v122, s[100:101]
	s_add_u32 m0, s11, 0xf000
	v_mfma_f32_16x16x32_bf16 v[60:63], v[134:137], v[154:157], v[60:63]
	global_load_lds_dwordx4 v123, s[100:101]
	s_waitcnt lgkmcnt(6)
	v_mfma_f32_16x16x32_bf16 v[0:3], v[158:161], v[166:169], v[0:3]
	s_waitcnt lgkmcnt(5)
	v_mfma_f32_16x16x32_bf16 v[4:7], v[158:161], v[170:173], v[4:7]
	s_waitcnt lgkmcnt(4)
	v_mfma_f32_16x16x32_bf16 v[8:11], v[158:161], v[174:177], v[8:11]
	s_waitcnt lgkmcnt(3)
	v_mfma_f32_16x16x32_bf16 v[12:15], v[158:161], v[252:255], v[12:15]
	s_waitcnt lgkmcnt(2)
	v_mfma_f32_16x16x32_bf16 v[16:19], v[162:165], v[166:169], v[16:19]
	v_mfma_f32_16x16x32_bf16 v[20:23], v[162:165], v[170:173], v[20:23]
	v_mfma_f32_16x16x32_bf16 v[24:27], v[162:165], v[174:177], v[24:27]
	v_mfma_f32_16x16x32_bf16 v[28:31], v[162:165], v[252:255], v[28:31]
	s_waitcnt lgkmcnt(1)
	v_mfma_f32_16x16x32_bf16 v[32:35], v[244:247], v[166:169], v[32:35]
	v_mfma_f32_16x16x32_bf16 v[36:39], v[244:247], v[170:173], v[36:39]
	v_mfma_f32_16x16x32_bf16 v[40:43], v[244:247], v[174:177], v[40:43]
	v_mfma_f32_16x16x32_bf16 v[44:47], v[244:247], v[252:255], v[44:47]
	s_waitcnt lgkmcnt(0)
	v_mfma_f32_16x16x32_bf16 v[48:51], v[248:251], v[166:169], v[48:51]
	v_mfma_f32_16x16x32_bf16 v[52:55], v[248:251], v[170:173], v[52:55]
	v_mfma_f32_16x16x32_bf16 v[56:59], v[248:251], v[174:177], v[56:59]
	v_mfma_f32_16x16x32_bf16 v[60:63], v[248:251], v[252:255], v[60:63]
	s_waitcnt vmcnt(0) lgkmcnt(0)
	s_barrier
	s_add_u32 s98, s98, 0x80
	s_addc_u32 s99, s99, 0
	s_add_u32 s100, s100, 0x80
	s_addc_u32 s101, s101, 0
	ds_read_b128 v[118:121], v239 offset:32768
	ds_read_b128 v[138:141], v241 offset:32768
	ds_read_b128 v[142:145], v241 offset:34816
	ds_read_b128 v[148:151], v241 offset:36864
	ds_read_b128 v[154:157], v241 offset:38912
	ds_read_b128 v[126:129], v239 offset:34816
	ds_read_b128 v[130:133], v239 offset:36864
	ds_read_b128 v[134:137], v239 offset:38912
	s_waitcnt lgkmcnt(6)
	v_mfma_f32_16x16x32_bf16 v[0:3], v[118:121], v[138:141], v[0:3]
	ds_read_b128 v[158:161], v240 offset:32768
	s_waitcnt lgkmcnt(6)
	v_mfma_f32_16x16x32_bf16 v[4:7], v[118:121], v[142:145], v[4:7]
	ds_read_b128 v[166:169], v242 offset:32768
	s_waitcnt lgkmcnt(6)
	v_mfma_f32_16x16x32_bf16 v[8:11], v[118:121], v[148:151], v[8:11]
	ds_read_b128 v[170:173], v242 offset:34816
	s_waitcnt lgkmcnt(6)
	v_mfma_f32_16x16x32_bf16 v[12:15], v[118:121], v[154:157], v[12:15]
	ds_read_b128 v[174:177], v242 offset:36864
	s_waitcnt lgkmcnt(6)
	v_mfma_f32_16x16x32_bf16 v[16:19], v[126:129], v[138:141], v[16:19]
	ds_read_b128 v[252:255], v242 offset:38912
	v_mfma_f32_16x16x32_bf16 v[20:23], v[126:129], v[142:145], v[20:23]
	ds_read_b128 v[162:165], v240 offset:34816
	v_mfma_f32_16x16x32_bf16 v[24:27], v[126:129], v[148:151], v[24:27]
	ds_read_b128 v[244:247], v240 offset:36864
	v_mfma_f32_16x16x32_bf16 v[28:31], v[126:129], v[154:157], v[28:31]
	ds_read_b128 v[248:251], v240 offset:38912
	s_add_u32 m0, s11, 0x0
	s_waitcnt lgkmcnt(9)
	v_mfma_f32_16x16x32_bf16 v[32:35], v[130:133], v[138:141], v[32:35]
	global_load_lds_dwordx4 v115, s[98:99]
	s_add_u32 m0, s11, 0x1000
	v_mfma_f32_16x16x32_bf16 v[36:39], v[130:133], v[142:145], v[36:39]
	global_load_lds_dwordx4 v116, s[98:99]
	s_add_u32 m0, s11, 0x2000
	v_mfma_f32_16x16x32_bf16 v[40:43], v[130:133], v[148:151], v[40:43]
	global_load_lds_dwordx4 v122, s[98:99]
	s_add_u32 m0, s11, 0x3000
	v_mfma_f32_16x16x32_bf16 v[44:47], v[130:133], v[154:157], v[44:47]
	global_load_lds_dwordx4 v123, s[98:99]
	s_add_u32 m0, s11, 0x4000
	s_waitcnt lgkmcnt(8)
	v_mfma_f32_16x16x32_bf16 v[48:51], v[134:137], v[138:141], v[48:51]
	global_load_lds_dwordx4 v115, s[100:101]
	s_add_u32 m0, s11, 0x5000
	v_mfma_f32_16x16x32_bf16 v[52:55], v[134:137], v[142:145], v[52:55]
	global_load_lds_dwordx4 v116, s[100:101]
	s_add_u32 m0, s11, 0x6000
	v_mfma_f32_16x16x32_bf16 v[56:59], v[134:137], v[148:151], v[56:59]
	global_load_lds_dwordx4 v122, s[100:101]
	s_add_u32 m0, s11, 0x7000
	v_mfma_f32_16x16x32_bf16 v[60:63], v[134:137], v[154:157], v[60:63]
	global_load_lds_dwordx4 v123, s[100:101]
	s_waitcnt lgkmcnt(6)
	v_mfma_f32_16x16x32_bf16 v[0:3], v[158:161], v[166:169], v[0:3]
	s_waitcnt lgkmcnt(5)
	v_mfma_f32_16x16x32_bf16 v[4:7], v[158:161], v[170:173], v[4:7]
	s_waitcnt lgkmcnt(4)
	v_mfma_f32_16x16x32_bf16 v[8:11], v[158:161], v[174:177], v[8:11]
	s_waitcnt lgkmcnt(3)
	v_mfma_f32_16x16x32_bf16 v[12:15], v[158:161], v[252:255], v[12:15]
	s_waitcnt lgkmcnt(2)
	v_mfma_f32_16x16x32_bf16 v[16:19], v[162:165], v[166:169], v[16:19]
	v_mfma_f32_16x16x32_bf16 v[20:23], v[162:165], v[170:173], v[20:23]
	v_mfma_f32_16x16x32_bf16 v[24:27], v[162:165], v[174:177], v[24:27]
	v_mfma_f32_16x16x32_bf16 v[28:31], v[162:165], v[252:255], v[28:31]
	s_waitcnt lgkmcnt(1)
	v_mfma_f32_16x16x32_bf16 v[32:35], v[244:247], v[166:169], v[32:35]
	v_mfma_f32_16x16x32_bf16 v[36:39], v[244:247], v[170:173], v[36:39]
	v_mfma_f32_16x16x32_bf16 v[40:43], v[244:247], v[174:177], v[40:43]
	v_mfma_f32_16x16x32_bf16 v[44:47], v[244:247], v[252:255], v[44:47]
	s_waitcnt lgkmcnt(0)
	v_mfma_f32_16x16x32_bf16 v[48:51], v[248:251], v[166:169], v[48:51]
	v_mfma_f32_16x16x32_bf16 v[52:55], v[248:251], v[170:173], v[52:55]
	v_mfma_f32_16x16x32_bf16 v[56:59], v[248:251], v[174:177], v[56:59]
	v_mfma_f32_16x16x32_bf16 v[60:63], v[248:251], v[252:255], v[60:63]
	s_waitcnt vmcnt(0) lgkmcnt(0)
	s_barrier
	s_add_u32 s98, s98, 0x80
	s_addc_u32 s99, s99, 0
	s_add_u32 s100, s100, 0x80
	s_addc_u32 s101, s101, 0
	ds_read_b128 v[118:121], v239
	ds_read_b128 v[138:141], v241
	ds_read_b128 v[142:145], v241 offset:2048
	ds_read_b128 v[148:151], v241 offset:4096
	ds_read_b128 v[154:157], v241 offset:6144
	ds_read_b128 v[126:129], v239 offset:2048
	ds_read_b128 v[130:133], v239 offset:4096
	ds_read_b128 v[134:137], v239 offset:6144
	s_waitcnt lgkmcnt(6)
	v_mfma_f32_16x16x32_bf16 v[0:3], v[118:121], v[138:141], v[0:3]
	ds_read_b128 v[158:161], v240
	s_waitcnt lgkmcnt(6)
	v_mfma_f32_16x16x32_bf16 v[4:7], v[118:121], v[142:145], v[4:7]
	ds_read_b128 v[166:169], v242
	s_waitcnt lgkmcnt(6)
	v_mfma_f32_16x16x32_bf16 v[8:11], v[118:121], v[148:151], v[8:11]
	ds_read_b128 v[170:173], v242 offset:2048
	s_waitcnt lgkmcnt(6)
	v_mfma_f32_16x16x32_bf16 v[12:15], v[118:121], v[154:157], v[12:15]
	ds_read_b128 v[174:177], v242 offset:4096
	s_waitcnt lgkmcnt(6)
	v_mfma_f32_16x16x32_bf16 v[16:19], v[126:129], v[138:141], v[16:19]
	ds_read_b128 v[252:255], v242 offset:6144
	v_mfma_f32_16x16x32_bf16 v[20:23], v[126:129], v[142:145], v[20:23]
	ds_read_b128 v[162:165], v240 offset:2048
	v_mfma_f32_16x16x32_bf16 v[24:27], v[126:129], v[148:151], v[24:27]
	ds_read_b128 v[244:247], v240 offset:4096
	v_mfma_f32_16x16x32_bf16 v[28:31], v[126:129], v[154:157], v[28:31]
	ds_read_b128 v[248:251], v240 offset:6144
	s_add_u32 m0, s11, 0x8000
	s_waitcnt lgkmcnt(9)
	v_mfma_f32_16x16x32_bf16 v[32:35], v[130:133], v[138:141], v[32:35]
	global_load_lds_dwordx4 v115, s[98:99]
	s_add_u32 m0, s11, 0x9000
	v_mfma_f32_16x16x32_bf16 v[36:39], v[130:133], v[142:145], v[36:39]
	global_load_lds_dwordx4 v116, s[98:99]
	s_add_u32 m0, s11, 0xa000
	v_mfma_f32_16x16x32_bf16 v[40:43], v[130:133], v[148:151], v[40:43]
	global_load_lds_dwordx4 v122, s[98:99]
	s_add_u32 m0, s11, 0xb000
	v_mfma_f32_16x16x32_bf16 v[44:47], v[130:133], v[154:157], v[44:47]
	global_load_lds_dwordx4 v123, s[98:99]
	s_add_u32 m0, s11, 0xc000
	s_waitcnt lgkmcnt(8)
	v_mfma_f32_16x16x32_bf16 v[48:51], v[134:137], v[138:141], v[48:51]
	global_load_lds_dwordx4 v115, s[100:101]
	s_add_u32 m0, s11, 0xd000
	v_mfma_f32_16x16x32_bf16 v[52:55], v[134:137], v[142:145], v[52:55]
	global_load_lds_dwordx4 v116, s[100:101]
	s_add_u32 m0, s11, 0xe000
	v_mfma_f32_16x16x32_bf16 v[56:59], v[134:137], v[148:151], v[56:59]
	global_load_lds_dwordx4 v122, s[100:101]
	s_add_u32 m0, s11, 0xf000
	v_mfma_f32_16x16x32_bf16 v[60:63], v[134:137], v[154:157], v[60:63]
	global_load_lds_dwordx4 v123, s[100:101]
	s_waitcnt lgkmcnt(6)
	v_mfma_f32_16x16x32_bf16 v[0:3], v[158:161], v[166:169], v[0:3]
	s_waitcnt lgkmcnt(5)
	v_mfma_f32_16x16x32_bf16 v[4:7], v[158:161], v[170:173], v[4:7]
	s_waitcnt lgkmcnt(4)
	v_mfma_f32_16x16x32_bf16 v[8:11], v[158:161], v[174:177], v[8:11]
	s_waitcnt lgkmcnt(3)
	v_mfma_f32_16x16x32_bf16 v[12:15], v[158:161], v[252:255], v[12:15]
	s_waitcnt lgkmcnt(2)
	v_mfma_f32_16x16x32_bf16 v[16:19], v[162:165], v[166:169], v[16:19]
	v_mfma_f32_16x16x32_bf16 v[20:23], v[162:165], v[170:173], v[20:23]
	v_mfma_f32_16x16x32_bf16 v[24:27], v[162:165], v[174:177], v[24:27]
	v_mfma_f32_16x16x32_bf16 v[28:31], v[162:165], v[252:255], v[28:31]
	s_waitcnt lgkmcnt(1)
	v_mfma_f32_16x16x32_bf16 v[32:35], v[244:247], v[166:169], v[32:35]
	v_mfma_f32_16x16x32_bf16 v[36:39], v[244:247], v[170:173], v[36:39]
	v_mfma_f32_16x16x32_bf16 v[40:43], v[244:247], v[174:177], v[40:43]
	v_mfma_f32_16x16x32_bf16 v[44:47], v[244:247], v[252:255], v[44:47]
	s_waitcnt lgkmcnt(0)
	v_mfma_f32_16x16x32_bf16 v[48:51], v[248:251], v[166:169], v[48:51]
	v_mfma_f32_16x16x32_bf16 v[52:55], v[248:251], v[170:173], v[52:55]
	v_mfma_f32_16x16x32_bf16 v[56:59], v[248:251], v[174:177], v[56:59]
	v_mfma_f32_16x16x32_bf16 v[60:63], v[248:251], v[252:255], v[60:63]
	s_waitcnt vmcnt(0) lgkmcnt(0)
	s_barrier
	s_add_u32 s98, s98, 0x80
	s_addc_u32 s99, s99, 0
	s_add_u32 s100, s100, 0x80
	s_addc_u32 s101, s101, 0
	ds_read_b128 v[118:121], v239 offset:32768
	ds_read_b128 v[138:141], v241 offset:32768
	ds_read_b128 v[142:145], v241 offset:34816
	ds_read_b128 v[148:151], v241 offset:36864
	ds_read_b128 v[154:157], v241 offset:38912
	ds_read_b128 v[126:129], v239 offset:34816
	ds_read_b128 v[130:133], v239 offset:36864
	ds_read_b128 v[134:137], v239 offset:38912
	s_waitcnt lgkmcnt(6)
	v_mfma_f32_16x16x32_bf16 v[0:3], v[118:121], v[138:141], v[0:3]
	ds_read_b128 v[158:161], v240 offset:32768
	s_waitcnt lgkmcnt(6)
	v_mfma_f32_16x16x32_bf16 v[4:7], v[118:121], v[142:145], v[4:7]
	ds_read_b128 v[166:169], v242 offset:32768
	s_waitcnt lgkmcnt(6)
	v_mfma_f32_16x16x32_bf16 v[8:11], v[118:121], v[148:151], v[8:11]
	ds_read_b128 v[170:173], v242 offset:34816
	s_waitcnt lgkmcnt(6)
	v_mfma_f32_16x16x32_bf16 v[12:15], v[118:121], v[154:157], v[12:15]
	ds_read_b128 v[174:177], v242 offset:36864
	s_waitcnt lgkmcnt(6)
	v_mfma_f32_16x16x32_bf16 v[16:19], v[126:129], v[138:141], v[16:19]
	ds_read_b128 v[252:255], v242 offset:38912
	v_mfma_f32_16x16x32_bf16 v[20:23], v[126:129], v[142:145], v[20:23]
	ds_read_b128 v[162:165], v240 offset:34816
	v_mfma_f32_16x16x32_bf16 v[24:27], v[126:129], v[148:151], v[24:27]
	ds_read_b128 v[244:247], v240 offset:36864
	v_mfma_f32_16x16x32_bf16 v[28:31], v[126:129], v[154:157], v[28:31]
	ds_read_b128 v[248:251], v240 offset:38912
	s_add_u32 m0, s11, 0x0
	s_waitcnt lgkmcnt(9)
	v_mfma_f32_16x16x32_bf16 v[32:35], v[130:133], v[138:141], v[32:35]
	global_load_lds_dwordx4 v115, s[98:99]
	s_add_u32 m0, s11, 0x1000
	v_mfma_f32_16x16x32_bf16 v[36:39], v[130:133], v[142:145], v[36:39]
	global_load_lds_dwordx4 v116, s[98:99]
	s_add_u32 m0, s11, 0x2000
	v_mfma_f32_16x16x32_bf16 v[40:43], v[130:133], v[148:151], v[40:43]
	global_load_lds_dwordx4 v122, s[98:99]
	s_add_u32 m0, s11, 0x3000
	v_mfma_f32_16x16x32_bf16 v[44:47], v[130:133], v[154:157], v[44:47]
	global_load_lds_dwordx4 v123, s[98:99]
	s_add_u32 m0, s11, 0x4000
	s_waitcnt lgkmcnt(8)
	v_mfma_f32_16x16x32_bf16 v[48:51], v[134:137], v[138:141], v[48:51]
	global_load_lds_dwordx4 v115, s[100:101]
	s_add_u32 m0, s11, 0x5000
	v_mfma_f32_16x16x32_bf16 v[52:55], v[134:137], v[142:145], v[52:55]
	global_load_lds_dwordx4 v116, s[100:101]
	s_add_u32 m0, s11, 0x6000
	v_mfma_f32_16x16x32_bf16 v[56:59], v[134:137], v[148:151], v[56:59]
	global_load_lds_dwordx4 v122, s[100:101]
	s_add_u32 m0, s11, 0x7000
	v_mfma_f32_16x16x32_bf16 v[60:63], v[134:137], v[154:157], v[60:63]
	global_load_lds_dwordx4 v123, s[100:101]
	s_waitcnt lgkmcnt(6)
	v_mfma_f32_16x16x32_bf16 v[0:3], v[158:161], v[166:169], v[0:3]
	s_waitcnt lgkmcnt(5)
	v_mfma_f32_16x16x32_bf16 v[4:7], v[158:161], v[170:173], v[4:7]
	s_waitcnt lgkmcnt(4)
	v_mfma_f32_16x16x32_bf16 v[8:11], v[158:161], v[174:177], v[8:11]
	s_waitcnt lgkmcnt(3)
	v_mfma_f32_16x16x32_bf16 v[12:15], v[158:161], v[252:255], v[12:15]
	s_waitcnt lgkmcnt(2)
	v_mfma_f32_16x16x32_bf16 v[16:19], v[162:165], v[166:169], v[16:19]
	v_mfma_f32_16x16x32_bf16 v[20:23], v[162:165], v[170:173], v[20:23]
	v_mfma_f32_16x16x32_bf16 v[24:27], v[162:165], v[174:177], v[24:27]
	v_mfma_f32_16x16x32_bf16 v[28:31], v[162:165], v[252:255], v[28:31]
	s_waitcnt lgkmcnt(1)
	v_mfma_f32_16x16x32_bf16 v[32:35], v[244:247], v[166:169], v[32:35]
	v_mfma_f32_16x16x32_bf16 v[36:39], v[244:247], v[170:173], v[36:39]
	v_mfma_f32_16x16x32_bf16 v[40:43], v[244:247], v[174:177], v[40:43]
	v_mfma_f32_16x16x32_bf16 v[44:47], v[244:247], v[252:255], v[44:47]
	s_waitcnt lgkmcnt(0)
	v_mfma_f32_16x16x32_bf16 v[48:51], v[248:251], v[166:169], v[48:51]
	v_mfma_f32_16x16x32_bf16 v[52:55], v[248:251], v[170:173], v[52:55]
	v_mfma_f32_16x16x32_bf16 v[56:59], v[248:251], v[174:177], v[56:59]
	v_mfma_f32_16x16x32_bf16 v[60:63], v[248:251], v[252:255], v[60:63]
	s_waitcnt vmcnt(0) lgkmcnt(0)
	s_barrier
	s_add_u32 s98, s98, 0x80
	s_addc_u32 s99, s99, 0
	s_add_u32 s100, s100, 0x80
	s_addc_u32 s101, s101, 0
	ds_read_b128 v[118:121], v239
	ds_read_b128 v[138:141], v241
	ds_read_b128 v[142:145], v241 offset:2048
	ds_read_b128 v[148:151], v241 offset:4096
	ds_read_b128 v[154:157], v241 offset:6144
	ds_read_b128 v[126:129], v239 offset:2048
	ds_read_b128 v[130:133], v239 offset:4096
	ds_read_b128 v[134:137], v239 offset:6144
	s_waitcnt lgkmcnt(6)
	v_mfma_f32_16x16x32_bf16 v[0:3], v[118:121], v[138:141], v[0:3]
	ds_read_b128 v[158:161], v240
	s_waitcnt lgkmcnt(6)
	v_mfma_f32_16x16x32_bf16 v[4:7], v[118:121], v[142:145], v[4:7]
	ds_read_b128 v[166:169], v242
	s_waitcnt lgkmcnt(6)
	v_mfma_f32_16x16x32_bf16 v[8:11], v[118:121], v[148:151], v[8:11]
	ds_read_b128 v[170:173], v242 offset:2048
	s_waitcnt lgkmcnt(6)
	v_mfma_f32_16x16x32_bf16 v[12:15], v[118:121], v[154:157], v[12:15]
	ds_read_b128 v[174:177], v242 offset:4096
	s_waitcnt lgkmcnt(6)
	v_mfma_f32_16x16x32_bf16 v[16:19], v[126:129], v[138:141], v[16:19]
	ds_read_b128 v[252:255], v242 offset:6144
	v_mfma_f32_16x16x32_bf16 v[20:23], v[126:129], v[142:145], v[20:23]
	ds_read_b128 v[162:165], v240 offset:2048
	v_mfma_f32_16x16x32_bf16 v[24:27], v[126:129], v[148:151], v[24:27]
	ds_read_b128 v[244:247], v240 offset:4096
	v_mfma_f32_16x16x32_bf16 v[28:31], v[126:129], v[154:157], v[28:31]
	ds_read_b128 v[248:251], v240 offset:6144
	s_add_u32 m0, s11, 0x8000
	s_waitcnt lgkmcnt(9)
	v_mfma_f32_16x16x32_bf16 v[32:35], v[130:133], v[138:141], v[32:35]
	global_load_lds_dwordx4 v115, s[98:99]
	s_add_u32 m0, s11, 0x9000
	v_mfma_f32_16x16x32_bf16 v[36:39], v[130:133], v[142:145], v[36:39]
	global_load_lds_dwordx4 v116, s[98:99]
	s_add_u32 m0, s11, 0xa000
	v_mfma_f32_16x16x32_bf16 v[40:43], v[130:133], v[148:151], v[40:43]
	global_load_lds_dwordx4 v122, s[98:99]
	s_add_u32 m0, s11, 0xb000
	v_mfma_f32_16x16x32_bf16 v[44:47], v[130:133], v[154:157], v[44:47]
	global_load_lds_dwordx4 v123, s[98:99]
	s_add_u32 m0, s11, 0xc000
	s_waitcnt lgkmcnt(8)
	v_mfma_f32_16x16x32_bf16 v[48:51], v[134:137], v[138:141], v[48:51]
	global_load_lds_dwordx4 v115, s[100:101]
	s_add_u32 m0, s11, 0xd000
	v_mfma_f32_16x16x32_bf16 v[52:55], v[134:137], v[142:145], v[52:55]
	global_load_lds_dwordx4 v116, s[100:101]
	s_add_u32 m0, s11, 0xe000
	v_mfma_f32_16x16x32_bf16 v[56:59], v[134:137], v[148:151], v[56:59]
	global_load_lds_dwordx4 v122, s[100:101]
	s_add_u32 m0, s11, 0xf000
	v_mfma_f32_16x16x32_bf16 v[60:63], v[134:137], v[154:157], v[60:63]
	global_load_lds_dwordx4 v123, s[100:101]
	s_waitcnt lgkmcnt(6)
	v_mfma_f32_16x16x32_bf16 v[0:3], v[158:161], v[166:169], v[0:3]
	s_waitcnt lgkmcnt(5)
	v_mfma_f32_16x16x32_bf16 v[4:7], v[158:161], v[170:173], v[4:7]
	s_waitcnt lgkmcnt(4)
	v_mfma_f32_16x16x32_bf16 v[8:11], v[158:161], v[174:177], v[8:11]
	s_waitcnt lgkmcnt(3)
	v_mfma_f32_16x16x32_bf16 v[12:15], v[158:161], v[252:255], v[12:15]
	s_waitcnt lgkmcnt(2)
	v_mfma_f32_16x16x32_bf16 v[16:19], v[162:165], v[166:169], v[16:19]
	v_mfma_f32_16x16x32_bf16 v[20:23], v[162:165], v[170:173], v[20:23]
	v_mfma_f32_16x16x32_bf16 v[24:27], v[162:165], v[174:177], v[24:27]
	v_mfma_f32_16x16x32_bf16 v[28:31], v[162:165], v[252:255], v[28:31]
	s_waitcnt lgkmcnt(1)
	v_mfma_f32_16x16x32_bf16 v[32:35], v[244:247], v[166:169], v[32:35]
	v_mfma_f32_16x16x32_bf16 v[36:39], v[244:247], v[170:173], v[36:39]
	v_mfma_f32_16x16x32_bf16 v[40:43], v[244:247], v[174:177], v[40:43]
	v_mfma_f32_16x16x32_bf16 v[44:47], v[244:247], v[252:255], v[44:47]
	s_waitcnt lgkmcnt(0)
	v_mfma_f32_16x16x32_bf16 v[48:51], v[248:251], v[166:169], v[48:51]
	v_mfma_f32_16x16x32_bf16 v[52:55], v[248:251], v[170:173], v[52:55]
	v_mfma_f32_16x16x32_bf16 v[56:59], v[248:251], v[174:177], v[56:59]
	v_mfma_f32_16x16x32_bf16 v[60:63], v[248:251], v[252:255], v[60:63]
	s_waitcnt vmcnt(0) lgkmcnt(0)
	s_barrier
	ds_read_b128 v[118:121], v239 offset:32768
	ds_read_b128 v[138:141], v241 offset:32768
	ds_read_b128 v[142:145], v241 offset:34816
	ds_read_b128 v[148:151], v241 offset:36864
	ds_read_b128 v[154:157], v241 offset:38912
	ds_read_b128 v[126:129], v239 offset:34816
	ds_read_b128 v[130:133], v239 offset:36864
	ds_read_b128 v[134:137], v239 offset:38912
	s_waitcnt lgkmcnt(6)
	v_mfma_f32_16x16x32_bf16 v[0:3], v[118:121], v[138:141], v[0:3]
	ds_read_b128 v[158:161], v240 offset:32768
	s_waitcnt lgkmcnt(6)
	v_mfma_f32_16x16x32_bf16 v[4:7], v[118:121], v[142:145], v[4:7]
	ds_read_b128 v[166:169], v242 offset:32768
	s_waitcnt lgkmcnt(6)
	v_mfma_f32_16x16x32_bf16 v[8:11], v[118:121], v[148:151], v[8:11]
	ds_read_b128 v[170:173], v242 offset:34816
	s_waitcnt lgkmcnt(6)
	v_mfma_f32_16x16x32_bf16 v[12:15], v[118:121], v[154:157], v[12:15]
	ds_read_b128 v[174:177], v242 offset:36864
	s_waitcnt lgkmcnt(6)
	v_mfma_f32_16x16x32_bf16 v[16:19], v[126:129], v[138:141], v[16:19]
	ds_read_b128 v[252:255], v242 offset:38912
	v_mfma_f32_16x16x32_bf16 v[20:23], v[126:129], v[142:145], v[20:23]
	ds_read_b128 v[162:165], v240 offset:34816
	v_mfma_f32_16x16x32_bf16 v[24:27], v[126:129], v[148:151], v[24:27]
	ds_read_b128 v[244:247], v240 offset:36864
	v_mfma_f32_16x16x32_bf16 v[28:31], v[126:129], v[154:157], v[28:31]
	ds_read_b128 v[248:251], v240 offset:38912
	s_waitcnt lgkmcnt(9)
	v_mfma_f32_16x16x32_bf16 v[32:35], v[130:133], v[138:141], v[32:35]
	v_mfma_f32_16x16x32_bf16 v[36:39], v[130:133], v[142:145], v[36:39]
	v_mfma_f32_16x16x32_bf16 v[40:43], v[130:133], v[148:151], v[40:43]
	v_mfma_f32_16x16x32_bf16 v[44:47], v[130:133], v[154:157], v[44:47]
	s_waitcnt lgkmcnt(8)
	v_mfma_f32_16x16x32_bf16 v[48:51], v[134:137], v[138:141], v[48:51]
	v_mfma_f32_16x16x32_bf16 v[52:55], v[134:137], v[142:145], v[52:55]
	v_mfma_f32_16x16x32_bf16 v[56:59], v[134:137], v[148:151], v[56:59]
	v_mfma_f32_16x16x32_bf16 v[60:63], v[134:137], v[154:157], v[60:63]
	s_waitcnt lgkmcnt(6)
	v_mfma_f32_16x16x32_bf16 v[0:3], v[158:161], v[166:169], v[0:3]
	s_waitcnt lgkmcnt(5)
	v_mfma_f32_16x16x32_bf16 v[4:7], v[158:161], v[170:173], v[4:7]
	s_waitcnt lgkmcnt(4)
	v_mfma_f32_16x16x32_bf16 v[8:11], v[158:161], v[174:177], v[8:11]
	s_waitcnt lgkmcnt(3)
	v_mfma_f32_16x16x32_bf16 v[12:15], v[158:161], v[252:255], v[12:15]
	s_waitcnt lgkmcnt(2)
	v_mfma_f32_16x16x32_bf16 v[16:19], v[162:165], v[166:169], v[16:19]
	v_mfma_f32_16x16x32_bf16 v[20:23], v[162:165], v[170:173], v[20:23]
	v_mfma_f32_16x16x32_bf16 v[24:27], v[162:165], v[174:177], v[24:27]
	v_mfma_f32_16x16x32_bf16 v[28:31], v[162:165], v[252:255], v[28:31]
	s_waitcnt lgkmcnt(1)
	v_mfma_f32_16x16x32_bf16 v[32:35], v[244:247], v[166:169], v[32:35]
	v_mfma_f32_16x16x32_bf16 v[36:39], v[244:247], v[170:173], v[36:39]
	v_mfma_f32_16x16x32_bf16 v[40:43], v[244:247], v[174:177], v[40:43]
	v_mfma_f32_16x16x32_bf16 v[44:47], v[244:247], v[252:255], v[44:47]
	s_waitcnt lgkmcnt(0)
	v_mfma_f32_16x16x32_bf16 v[48:51], v[248:251], v[166:169], v[48:51]
	v_mfma_f32_16x16x32_bf16 v[52:55], v[248:251], v[170:173], v[52:55]
	v_mfma_f32_16x16x32_bf16 v[56:59], v[248:251], v[174:177], v[56:59]
	v_mfma_f32_16x16x32_bf16 v[60:63], v[248:251], v[252:255], v[60:63]
	s_waitcnt vmcnt(0) lgkmcnt(0)
	s_barrier
	s_nop 15
	ds_write_b32 v243, v0
	ds_write_b32 v243, v1 offset:528
	ds_write_b32 v243, v2 offset:1056
	ds_write_b32 v243, v3 offset:1584
	ds_write_b32 v243, v4 offset:64
	ds_write_b32 v243, v5 offset:592
	ds_write_b32 v243, v6 offset:1120
	ds_write_b32 v243, v7 offset:1648
	ds_write_b32 v243, v8 offset:128
	ds_write_b32 v243, v9 offset:656
	ds_write_b32 v243, v10 offset:1184
	ds_write_b32 v243, v11 offset:1712
	ds_write_b32 v243, v12 offset:192
	ds_write_b32 v243, v13 offset:720
	ds_write_b32 v243, v14 offset:1248
	ds_write_b32 v243, v15 offset:1776
	ds_write_b32 v243, v16 offset:8448
	ds_write_b32 v243, v17 offset:8976
	ds_write_b32 v243, v18 offset:9504
	ds_write_b32 v243, v19 offset:10032
	ds_write_b32 v243, v20 offset:8512
	ds_write_b32 v243, v21 offset:9040
	ds_write_b32 v243, v22 offset:9568
	ds_write_b32 v243, v23 offset:10096
	ds_write_b32 v243, v24 offset:8576
	ds_write_b32 v243, v25 offset:9104
	ds_write_b32 v243, v26 offset:9632
	ds_write_b32 v243, v27 offset:10160
	ds_write_b32 v243, v28 offset:8640
	ds_write_b32 v243, v29 offset:9168
	ds_write_b32 v243, v30 offset:9696
	ds_write_b32 v243, v31 offset:10224
	ds_write_b32 v243, v32 offset:16896
	ds_write_b32 v243, v33 offset:17424
	ds_write_b32 v243, v34 offset:17952
	ds_write_b32 v243, v35 offset:18480
	ds_write_b32 v243, v36 offset:16960
	ds_write_b32 v243, v37 offset:17488
	ds_write_b32 v243, v38 offset:18016
	ds_write_b32 v243, v39 offset:18544
	ds_write_b32 v243, v40 offset:17024
	ds_write_b32 v243, v41 offset:17552
	ds_write_b32 v243, v42 offset:18080
	ds_write_b32 v243, v43 offset:18608
	ds_write_b32 v243, v44 offset:17088
	ds_write_b32 v243, v45 offset:17616
	ds_write_b32 v243, v46 offset:18144
	ds_write_b32 v243, v47 offset:18672
	ds_write_b32 v243, v48 offset:25344
	ds_write_b32 v243, v49 offset:25872
	ds_write_b32 v243, v50 offset:26400
	ds_write_b32 v243, v51 offset:26928
	ds_write_b32 v243, v52 offset:25408
	ds_write_b32 v243, v53 offset:25936
	ds_write_b32 v243, v54 offset:26464
	ds_write_b32 v243, v55 offset:26992
	ds_write_b32 v243, v56 offset:25472
	ds_write_b32 v243, v57 offset:26000
	ds_write_b32 v243, v58 offset:26528
	ds_write_b32 v243, v59 offset:27056
	ds_write_b32 v243, v60 offset:25536
	ds_write_b32 v243, v61 offset:26064
	ds_write_b32 v243, v62 offset:26592
	ds_write_b32 v243, v63 offset:27120
	v_or_b32_e32 v4, s20, v147
	v_or_b32_e32 v0, s10, v82
	v_ashrrev_i32_e32 v5, 31, v4
	v_ashrrev_i32_e32 v1, 31, v0
	v_cmp_gt_i32_e32 vcc, s17, v4
	v_lshlrev_b64 v[4:5], 11, v[4:5]
	v_lshlrev_b64 v[2:3], 1, v[0:1]
	v_lshl_add_u64 v[4:5], s[24:25], 0, v[4:5]
	v_lshl_add_u64 v[0:1], s[24:25], 0, v[2:3]
	v_lshl_add_u64 v[2:3], v[4:5], 0, v[2:3]
	v_lshl_add_u64 v[4:5], v[2:3], 0, s[12:13]
	v_cmp_ge_u64_e64 s[10:11], v[4:5], v[2:3]
	s_and_b64 s[10:11], vcc, s[10:11]
	s_waitcnt lgkmcnt(0)
	s_barrier
	s_and_saveexec_b64 s[14:15], s[10:11]
	s_xor_b64 s[10:11], exec, s[14:15]
	s_cbranch_execz .LBB0_926
	s_mov_b32 s14, s20
	s_mov_b32 s15, 1
	s_mov_b32 s21, 0
	s_mov_b32 s22, 16
